# coalesced lane-transposed stores also in the MODE_E, MODE_POOL, MODE_PLE and gelu MODE_IN epilogues
# speedup vs baseline: 1.0254x; 1.0014x over previous
; __device__ __forceinline__ u32x4 pack8(const f32x4& v0, const f32x4& v1) { u32x4 w; w.x = cvt_pk_bf16(v0[0], v0[1]); w.y = cvt_pk_bf16(v0[2], v0[3]); w.z = cvt_pk_bf16(v1[0], v1[1]); w.w = cvt_pk_bf16(v1[2], v1[3]); return w; }
; __device__ __forceinline__ void epi_run(const Epi& E, f32x4 (&acc)[2][2][4][2], const Unit& u, int wr, int wc, int fr, int fq) {
;     ...
;     } else if (mode == MODE_E) {
; #pragma unroll
;         for (int ai = 0; ai < 2; ++ai)
; #pragma unroll
;             for (int m = 0; m < 4; ++m)
; #pragma unroll
;                 for (int bj = 0; bj < 2; ++bj) *(u32x4*)(E.C16 + (size_t)(row0 + ai * 128 + m * 16) * D + col0 + bj * 128) = pack8(acc[ai][bj][m][0], acc[ai][bj][m][1]);
.LBB0_268:
	s_cmp_gt_i32 s83, 4
	s_cbranch_scc0 .LBB0_275
	s_mov_b64 s[8:9], 0
	s_mov_b64 s[44:45], -1
	s_cmp_gt_i32 s83, 5
	s_mov_b64 s[96:97], 0
	s_cbranch_scc0 .LBB0_276
	s_cmp_eq_u32 s83, 6
	s_mov_b64 s[96:97], -1
	s_cbranch_scc0 .LBB0_297
	v_lshrrev_b32_e32 v140, 2, v201
	v_and_b32_e32 v141, 3, v201
	v_lshl_add_u32 v154, v141, 4, v140
	v_lshlrev_b32_e32 v154, 2, v154
	v_and_b32_e32 v142, 15, v201
	v_sub_u32_e32 v140, v140, v142
	v_lshrrev_b32_e32 v142, 4, v201
	v_sub_u32_e32 v141, v141, v142
	v_lshlrev_b32_e32 v141, 4, v141
	v_lshlrev_b32_e32 v140, 11, v140
	v_add_u32_e32 v152, v140, v141
	v_ashrrev_i32_e32 v153, 31, v152
	v_ashrrev_i32_e32 v211, 31, v210
	v_ashrrev_i32_e32 v213, 31, v212
	v_lshlrev_b64 v[134:135], 11, v[210:211]
	v_lshl_add_u64 v[134:135], s[62:63], 0, v[134:135]
	v_lshlrev_b64 v[136:137], 1, v[212:213]
	s_waitcnt lgkmcnt(0)
	v_cvt_pk_bf16_f32 v130, v126, v127
	v_cvt_pk_bf16_f32 v131, v128, v129
	v_cvt_pk_bf16_f32 v132, v122, v123
	v_cvt_pk_bf16_f32 v133, v124, v125
	v_lshl_add_u64 v[134:135], v[134:135], 0, v[136:137]
	v_lshl_add_u64 v[148:149], v[134:135], 0, v[152:153]
	ds_bpermute_b32 v140, v154, v130
	ds_bpermute_b32 v141, v154, v131
	ds_bpermute_b32 v142, v154, v132
	ds_bpermute_b32 v143, v154, v133
	s_mov_b32 s2, 0x40000
	s_mov_b64 s[20:21], 0x40000
	v_cvt_pk_bf16_f32 v130, v118, v119
	v_cvt_pk_bf16_f32 v131, v120, v121
	v_cvt_pk_bf16_f32 v132, v114, v115
	v_cvt_pk_bf16_f32 v133, v116, v117
	s_waitcnt lgkmcnt(0)
	global_store_dwordx4 v[148:149], v[140:143], off
	v_lshl_add_u64 v[150:151], v[134:135], 0, v[152:153]
	ds_bpermute_b32 v144, v154, v130
	ds_bpermute_b32 v145, v154, v131
	ds_bpermute_b32 v146, v154, v132
	ds_bpermute_b32 v147, v154, v133
	s_mov_b64 s[96:97], 0
	s_mov_b64 s[44:45], 0
	v_or_b32_e32 v130, 16, v210
	v_ashrrev_i32_e32 v131, 31, v130
	v_lshlrev_b64 v[138:139], 11, v[130:131]
	v_lshl_add_u64 v[138:139], s[62:63], 0, v[138:139]
	v_cvt_pk_bf16_f32 v130, v110, v111
	v_cvt_pk_bf16_f32 v131, v112, v113
	v_cvt_pk_bf16_f32 v132, v106, v107
	v_cvt_pk_bf16_f32 v133, v108, v109
	v_lshl_add_u64 v[138:139], v[138:139], 0, v[136:137]
	s_waitcnt lgkmcnt(0)
	global_store_dwordx4 v[150:151], v[144:147], off offset:256
	v_lshl_add_u64 v[148:149], v[138:139], 0, v[152:153]
	ds_bpermute_b32 v140, v154, v130
	ds_bpermute_b32 v141, v154, v131
	ds_bpermute_b32 v142, v154, v132
	ds_bpermute_b32 v143, v154, v133
	s_nop 1
	v_cvt_pk_bf16_f32 v130, v102, v103
	v_cvt_pk_bf16_f32 v131, v104, v105
	v_cvt_pk_bf16_f32 v132, v94, v95
	v_cvt_pk_bf16_f32 v133, v96, v97
	s_waitcnt lgkmcnt(0)
	global_store_dwordx4 v[148:149], v[140:143], off
	v_lshl_add_u64 v[150:151], v[138:139], 0, v[152:153]
	ds_bpermute_b32 v144, v154, v130
	ds_bpermute_b32 v145, v154, v131
	ds_bpermute_b32 v146, v154, v132
	ds_bpermute_b32 v147, v154, v133
	s_nop 1
	v_or_b32_e32 v130, 32, v210
	v_ashrrev_i32_e32 v131, 31, v130
	v_lshlrev_b64 v[138:139], 11, v[130:131]
	v_lshl_add_u64 v[138:139], s[62:63], 0, v[138:139]
	v_cvt_pk_bf16_f32 v130, v98, v99
	v_cvt_pk_bf16_f32 v131, v100, v101
	v_cvt_pk_bf16_f32 v132, v90, v91
	v_cvt_pk_bf16_f32 v133, v92, v93
	v_lshl_add_u64 v[138:139], v[138:139], 0, v[136:137]
	s_waitcnt lgkmcnt(0)
	global_store_dwordx4 v[150:151], v[144:147], off offset:256
	v_lshl_add_u64 v[148:149], v[138:139], 0, v[152:153]
	ds_bpermute_b32 v140, v154, v130
	ds_bpermute_b32 v141, v154, v131
	ds_bpermute_b32 v142, v154, v132
	ds_bpermute_b32 v143, v154, v133
	s_nop 1
	v_cvt_pk_bf16_f32 v130, v86, v87
	v_cvt_pk_bf16_f32 v131, v88, v89
	v_cvt_pk_bf16_f32 v132, v78, v79
	v_cvt_pk_bf16_f32 v133, v80, v81
	s_waitcnt lgkmcnt(0)
	global_store_dwordx4 v[148:149], v[140:143], off
	v_lshl_add_u64 v[150:151], v[138:139], 0, v[152:153]
	ds_bpermute_b32 v144, v154, v130
	ds_bpermute_b32 v145, v154, v131
	ds_bpermute_b32 v146, v154, v132
	ds_bpermute_b32 v147, v154, v133
	s_nop 1
	v_or_b32_e32 v130, 48, v210
	v_ashrrev_i32_e32 v131, 31, v130
	v_lshlrev_b64 v[138:139], 11, v[130:131]
	v_lshl_add_u64 v[138:139], s[62:63], 0, v[138:139]
	v_cvt_pk_bf16_f32 v130, v82, v83
	v_cvt_pk_bf16_f32 v131, v84, v85
	v_cvt_pk_bf16_f32 v132, v74, v75
	v_cvt_pk_bf16_f32 v133, v76, v77
	v_lshl_add_u64 v[136:137], v[138:139], 0, v[136:137]
	s_waitcnt lgkmcnt(0)
	global_store_dwordx4 v[150:151], v[144:147], off offset:256
	v_lshl_add_u64 v[148:149], v[136:137], 0, v[152:153]
	ds_bpermute_b32 v140, v154, v130
	ds_bpermute_b32 v141, v154, v131
	ds_bpermute_b32 v142, v154, v132
	ds_bpermute_b32 v143, v154, v133
	v_add_co_u32_e32 v138, vcc, s2, v134
	s_nop 0
	v_cvt_pk_bf16_f32 v130, v70, v71
	v_cvt_pk_bf16_f32 v131, v72, v73
	v_cvt_pk_bf16_f32 v132, v66, v67
	v_cvt_pk_bf16_f32 v133, v68, v69
	s_waitcnt lgkmcnt(0)
; __device__ __forceinline__ u32x4 pack8(const f32x4& v0, const f32x4& v1) { u32x4 w; w.x = cvt_pk_bf16(v0[0], v0[1]); w.y = cvt_pk_bf16(v0[2], v0[3]); w.z = cvt_pk_bf16(v1[0], v1[1]); w.w = cvt_pk_bf16(v1[2], v1[3]); return w; }
; __device__ __forceinline__ void epi_run(const Epi& E, f32x4 (&acc)[2][2][4][2], const Unit& u, int wr, int wc, int fr, int fq) {
;     ...
;     } else if (mode == MODE_E) {
; #pragma unroll
;         for (int ai = 0; ai < 2; ++ai)
; #pragma unroll
;             for (int m = 0; m < 4; ++m)
; #pragma unroll
;                 for (int bj = 0; bj < 2; ++bj) *(u32x4*)(E.C16 + (size_t)(row0 + ai * 128 + m * 16) * D + col0 + bj * 128) = pack8(acc[ai][bj][m][0], acc[ai][bj][m][1]);
	global_store_dwordx4 v[148:149], v[140:143], off
	v_lshl_add_u64 v[150:151], v[136:137], 0, v[152:153]
	ds_bpermute_b32 v144, v154, v130
	ds_bpermute_b32 v145, v154, v131
	ds_bpermute_b32 v146, v154, v132
	ds_bpermute_b32 v147, v154, v133
	v_addc_co_u32_e32 v139, vcc, 0, v135, vcc
	s_nop 0
	v_cvt_pk_bf16_f32 v130, v62, v63
	v_cvt_pk_bf16_f32 v131, v64, v65
	v_cvt_pk_bf16_f32 v132, v58, v59
	v_cvt_pk_bf16_f32 v133, v60, v61
	s_mov_b32 s2, 0x48000
	v_lshl_add_u64 v[136:137], v[134:135], 0, s[20:21]
	s_waitcnt lgkmcnt(0)
	global_store_dwordx4 v[150:151], v[144:147], off offset:256
	v_lshl_add_u64 v[148:149], v[138:139], 0, v[152:153]
	ds_bpermute_b32 v140, v154, v130
	ds_bpermute_b32 v141, v154, v131
	ds_bpermute_b32 v142, v154, v132
	ds_bpermute_b32 v143, v154, v133
	v_add_co_u32_e32 v138, vcc, s2, v134
	s_nop 0
	v_cvt_pk_bf16_f32 v130, v54, v55
	v_cvt_pk_bf16_f32 v131, v56, v57
	v_cvt_pk_bf16_f32 v132, v50, v51
	v_cvt_pk_bf16_f32 v133, v52, v53
	s_waitcnt lgkmcnt(0)
	global_store_dwordx4 v[148:149], v[140:143], off
	v_lshl_add_u64 v[150:151], v[136:137], 0, v[152:153]
	ds_bpermute_b32 v144, v154, v130
	ds_bpermute_b32 v145, v154, v131
	ds_bpermute_b32 v146, v154, v132
	ds_bpermute_b32 v147, v154, v133
	s_mov_b64 s[20:21], 0x48000
	v_addc_co_u32_e32 v139, vcc, 0, v135, vcc
	v_cvt_pk_bf16_f32 v130, v46, v47
	v_cvt_pk_bf16_f32 v131, v48, v49
	v_cvt_pk_bf16_f32 v132, v42, v43
	v_cvt_pk_bf16_f32 v133, v44, v45
	s_mov_b32 s2, 0x50000
	v_lshl_add_u64 v[136:137], v[134:135], 0, s[20:21]
	s_waitcnt lgkmcnt(0)
	global_store_dwordx4 v[150:151], v[144:147], off offset:256
	v_lshl_add_u64 v[148:149], v[138:139], 0, v[152:153]
	ds_bpermute_b32 v140, v154, v130
	ds_bpermute_b32 v141, v154, v131
	ds_bpermute_b32 v142, v154, v132
	ds_bpermute_b32 v143, v154, v133
	v_add_co_u32_e32 v138, vcc, s2, v134
	s_nop 0
	v_cvt_pk_bf16_f32 v130, v38, v39
	v_cvt_pk_bf16_f32 v131, v40, v41
	v_cvt_pk_bf16_f32 v132, v34, v35
	v_cvt_pk_bf16_f32 v133, v36, v37
	s_waitcnt lgkmcnt(0)
	global_store_dwordx4 v[148:149], v[140:143], off
	v_lshl_add_u64 v[150:151], v[136:137], 0, v[152:153]
	ds_bpermute_b32 v144, v154, v130
	ds_bpermute_b32 v145, v154, v131
	ds_bpermute_b32 v146, v154, v132
	ds_bpermute_b32 v147, v154, v133
	s_mov_b64 s[20:21], 0x50000
	v_addc_co_u32_e32 v139, vcc, 0, v135, vcc
	v_cvt_pk_bf16_f32 v130, v30, v31
	v_cvt_pk_bf16_f32 v131, v32, v33
	v_cvt_pk_bf16_f32 v132, v26, v27
	v_cvt_pk_bf16_f32 v133, v28, v29
	v_lshl_add_u64 v[136:137], v[134:135], 0, s[20:21]
	s_waitcnt lgkmcnt(0)
	global_store_dwordx4 v[150:151], v[144:147], off offset:256
	v_lshl_add_u64 v[148:149], v[138:139], 0, v[152:153]
	ds_bpermute_b32 v140, v154, v130
	ds_bpermute_b32 v141, v154, v131
	ds_bpermute_b32 v142, v154, v132
	ds_bpermute_b32 v143, v154, v133
	s_mov_b64 s[20:21], 0x58000
	s_mov_b32 s2, 0x58000
	v_cvt_pk_bf16_f32 v130, v22, v23
	v_cvt_pk_bf16_f32 v131, v24, v25
	v_cvt_pk_bf16_f32 v132, v18, v19
	v_cvt_pk_bf16_f32 v133, v20, v21
	s_waitcnt lgkmcnt(0)
	global_store_dwordx4 v[148:149], v[140:143], off
	v_lshl_add_u64 v[150:151], v[136:137], 0, v[152:153]
	ds_bpermute_b32 v144, v154, v130
	ds_bpermute_b32 v145, v154, v131
	ds_bpermute_b32 v146, v154, v132
	ds_bpermute_b32 v147, v154, v133
	v_lshl_add_u64 v[136:137], v[134:135], 0, s[20:21]
	v_add_co_u32_e32 v134, vcc, s2, v134
	v_cvt_pk_bf16_f32 v130, v14, v15
	v_cvt_pk_bf16_f32 v131, v16, v17
	v_cvt_pk_bf16_f32 v132, v10, v11
	v_cvt_pk_bf16_f32 v133, v12, v13
	v_addc_co_u32_e32 v135, vcc, 0, v135, vcc
	s_waitcnt lgkmcnt(0)
	global_store_dwordx4 v[150:151], v[144:147], off offset:256
	v_lshl_add_u64 v[148:149], v[134:135], 0, v[152:153]
	ds_bpermute_b32 v140, v154, v130
	ds_bpermute_b32 v141, v154, v131
	ds_bpermute_b32 v142, v154, v132
	ds_bpermute_b32 v143, v154, v133
	s_nop 1
	v_cvt_pk_bf16_f32 v130, v6, v7
	v_cvt_pk_bf16_f32 v131, v8, v9
	v_cvt_pk_bf16_f32 v132, v2, v3
	v_cvt_pk_bf16_f32 v133, v4, v5
	s_waitcnt lgkmcnt(0)
	global_store_dwordx4 v[148:149], v[140:143], off
	v_lshl_add_u64 v[150:151], v[136:137], 0, v[152:153]
	ds_bpermute_b32 v144, v154, v130
	ds_bpermute_b32 v145, v154, v131
	ds_bpermute_b32 v146, v154, v132
	ds_bpermute_b32 v147, v154, v133
	s_waitcnt lgkmcnt(0)
	global_store_dwordx4 v[150:151], v[144:147], off offset:256
	s_and_b64 vcc, exec, s[8:9]
	s_cbranch_vccnz .LBB0_277
	s_branch .LBB0_298

; __device__ __forceinline__ u32x4 pack8(const f32x4& v0, const f32x4& v1) { u32x4 w; w.x = cvt_pk_bf16(v0[0], v0[1]); w.y = cvt_pk_bf16(v0[2], v0[3]); w.z = cvt_pk_bf16(v1[0], v1[1]); w.w = cvt_pk_bf16(v1[2], v1[3]); return w; }
; __device__ __forceinline__ void epi_run(const Epi& E, f32x4 (&acc)[2][2][4][2], const Unit& u, int wr, int wc, int fr, int fq) {
;     ...
;     } else if (mode == MODE_POOL) {
;         f32x4 sc[2][2];
; #pragma unroll
;         for (int bj = 0; bj < 2; ++bj) { sc[bj][0] = *(const f32x4*)(E.pool_scale + col0 + bj * 128); sc[bj][1] = *(const f32x4*)(E.pool_scale + col0 + bj * 128 + 4); }
; #pragma unroll
;         for (int ai = 0; ai < 2; ++ai)
; #pragma unroll
;             for (int m = 0; m < 4; ++m)
; #pragma unroll
;                 for (int bj = 0; bj < 2; ++bj) *(u32x4*)(E.Z + (size_t)(row0 + ai * 128 + m * 16) * NIN + col0 + bj * 128) = pack8(acc[ai][bj][m][0] * sc[bj][0], acc[ai][bj][m][1] * sc[bj][1]);
.LBB0_303:
	s_andn2_b64 vcc, exec, s[8:9]
	s_cbranch_vccnz .LBB0_305
	v_lshrrev_b32_e32 v160, 2, v201
	v_and_b32_e32 v161, 3, v201
	v_lshl_add_u32 v174, v161, 4, v160
	v_lshlrev_b32_e32 v174, 2, v174
	v_and_b32_e32 v162, 15, v201
	v_sub_u32_e32 v160, v160, v162
	v_lshrrev_b32_e32 v162, 4, v201
	v_sub_u32_e32 v161, v161, v162
	v_lshlrev_b32_e32 v161, 4, v161
	v_mul_lo_u32 v160, v160, s69
	v_add_u32_e32 v172, v160, v161
	v_ashrrev_i32_e32 v173, 31, v172
	v_readlane_b32 s8, v250, 27
	v_ashrrev_i32_e32 v213, 31, v212
	v_readlane_b32 s9, v250, 28
	v_or_b32_e32 v0, 16, v210
	s_nop 0
	v_lshl_add_u64 v[138:139], v[212:213], 2, s[8:9]
	global_load_dwordx4 v[134:137], v[138:139], off offset:16
	global_load_dwordx4 v[142:145], v[138:139], off
	s_waitcnt lgkmcnt(0)
	global_load_dwordx4 v[130:133], v[138:139], off offset:528
	s_nop 0
	global_load_dwordx4 v[138:141], v[138:139], off offset:512
	s_waitcnt vmcnt(0)
	v_pk_mul_f32 v[150:151], v[124:125], v[136:137]
	v_pk_mul_f32 v[148:149], v[128:129], v[144:145]
	v_pk_mul_f32 v[146:147], v[126:127], v[142:143]
	v_pk_mul_f32 v[152:153], v[122:123], v[134:135]
	v_cvt_pk_bf16_f32 v146, v146, v147
	v_cvt_pk_bf16_f32 v147, v148, v149
	v_cvt_pk_bf16_f32 v149, v150, v151
	s_add_u32 s8, s70, 0x1000
	s_addc_u32 s9, s71, 0
	v_mov_b64_e32 v[150:151], s[8:9]
	v_cvt_pk_bf16_f32 v148, v152, v153
	v_mad_i64_i32 v[154:155], s[8:9], v210, s69, v[150:151]
	v_lshlrev_b64 v[152:153], 1, v[212:213]
	v_lshl_add_u64 v[154:155], v[154:155], 0, v[152:153]
	v_lshl_add_u64 v[168:169], v[154:155], 0, v[172:173]
	ds_bpermute_b32 v160, v174, v146
	ds_bpermute_b32 v161, v174, v147
	ds_bpermute_b32 v162, v174, v148
	ds_bpermute_b32 v163, v174, v149
	v_pk_mul_f32 v[156:157], v[116:117], v[132:133]
	v_pk_mul_f32 v[158:159], v[114:115], v[130:131]
	v_pk_mul_f32 v[148:149], v[120:121], v[140:141]
	v_pk_mul_f32 v[146:147], v[118:119], v[138:139]
	s_nop 0
	v_cvt_pk_bf16_f32 v146, v146, v147
	v_cvt_pk_bf16_f32 v147, v148, v149
	v_cvt_pk_bf16_f32 v148, v158, v159
	v_cvt_pk_bf16_f32 v149, v156, v157
	s_waitcnt lgkmcnt(0)
	global_store_dwordx4 v[168:169], v[160:163], off
	v_lshl_add_u64 v[170:171], v[154:155], 0, v[172:173]
	ds_bpermute_b32 v164, v174, v146
	ds_bpermute_b32 v165, v174, v147
	ds_bpermute_b32 v166, v174, v148
	ds_bpermute_b32 v167, v174, v149
	v_pk_mul_f32 v[154:155], v[108:109], v[136:137]
	v_pk_mul_f32 v[156:157], v[106:107], v[134:135]
	v_pk_mul_f32 v[148:149], v[112:113], v[144:145]
	v_pk_mul_f32 v[146:147], v[110:111], v[142:143]
	v_pk_mul_f32 v[158:159], v[94:95], v[130:131]
	v_cvt_pk_bf16_f32 v146, v146, v147
	v_cvt_pk_bf16_f32 v147, v148, v149
	v_cvt_pk_bf16_f32 v149, v154, v155
	v_mad_i64_i32 v[154:155], s[8:9], v0, s69, v[150:151]
	v_cvt_pk_bf16_f32 v148, v156, v157
	v_lshl_add_u64 v[154:155], v[154:155], 0, v[152:153]
	s_waitcnt lgkmcnt(0)
	global_store_dwordx4 v[170:171], v[164:167], off offset:256
	v_lshl_add_u64 v[168:169], v[154:155], 0, v[172:173]
	ds_bpermute_b32 v160, v174, v146
	ds_bpermute_b32 v161, v174, v147
	ds_bpermute_b32 v162, v174, v148
	ds_bpermute_b32 v163, v174, v149
	v_pk_mul_f32 v[156:157], v[96:97], v[132:133]
	v_or_b32_e32 v0, 32, v210
	v_pk_mul_f32 v[148:149], v[104:105], v[140:141]
	v_pk_mul_f32 v[146:147], v[102:103], v[138:139]
	s_nop 0
	v_cvt_pk_bf16_f32 v146, v146, v147
	v_cvt_pk_bf16_f32 v147, v148, v149
	v_cvt_pk_bf16_f32 v148, v158, v159
	v_cvt_pk_bf16_f32 v149, v156, v157
	s_waitcnt lgkmcnt(0)
	global_store_dwordx4 v[168:169], v[160:163], off
	v_lshl_add_u64 v[170:171], v[154:155], 0, v[172:173]
	ds_bpermute_b32 v164, v174, v146
	ds_bpermute_b32 v165, v174, v147
	ds_bpermute_b32 v166, v174, v148
	ds_bpermute_b32 v167, v174, v149
	v_pk_mul_f32 v[154:155], v[92:93], v[136:137]
	v_pk_mul_f32 v[156:157], v[90:91], v[134:135]
	v_pk_mul_f32 v[148:149], v[100:101], v[144:145]
	v_pk_mul_f32 v[146:147], v[98:99], v[142:143]
	v_pk_mul_f32 v[158:159], v[78:79], v[130:131]
	v_cvt_pk_bf16_f32 v146, v146, v147
	v_cvt_pk_bf16_f32 v147, v148, v149
	v_cvt_pk_bf16_f32 v149, v154, v155
	v_mad_i64_i32 v[154:155], s[8:9], v0, s69, v[150:151]
	v_cvt_pk_bf16_f32 v148, v156, v157
	v_lshl_add_u64 v[154:155], v[154:155], 0, v[152:153]
	s_waitcnt lgkmcnt(0)
	global_store_dwordx4 v[170:171], v[164:167], off offset:256
	v_lshl_add_u64 v[168:169], v[154:155], 0, v[172:173]
	ds_bpermute_b32 v160, v174, v146
	ds_bpermute_b32 v161, v174, v147
	ds_bpermute_b32 v162, v174, v148
	ds_bpermute_b32 v163, v174, v149
	v_pk_mul_f32 v[156:157], v[80:81], v[132:133]
	v_or_b32_e32 v0, 48, v210
	v_pk_mul_f32 v[148:149], v[88:89], v[140:141]
	v_pk_mul_f32 v[146:147], v[86:87], v[138:139]
	s_nop 0
	v_cvt_pk_bf16_f32 v146, v146, v147
	v_cvt_pk_bf16_f32 v147, v148, v149
	v_cvt_pk_bf16_f32 v148, v158, v159
	v_cvt_pk_bf16_f32 v149, v156, v157
	s_waitcnt lgkmcnt(0)
	global_store_dwordx4 v[168:169], v[160:163], off
	v_lshl_add_u64 v[170:171], v[154:155], 0, v[172:173]
	ds_bpermute_b32 v164, v174, v146
	ds_bpermute_b32 v165, v174, v147
	ds_bpermute_b32 v166, v174, v148
	ds_bpermute_b32 v167, v174, v149
	v_pk_mul_f32 v[154:155], v[76:77], v[136:137]
	v_pk_mul_f32 v[156:157], v[74:75], v[134:135]
	v_pk_mul_f32 v[148:149], v[84:85], v[144:145]
	v_pk_mul_f32 v[146:147], v[82:83], v[142:143]
	v_pk_mul_f32 v[158:159], v[66:67], v[130:131]
	v_cvt_pk_bf16_f32 v146, v146, v147
	v_cvt_pk_bf16_f32 v147, v148, v149
	v_cvt_pk_bf16_f32 v149, v154, v155
	v_mad_i64_i32 v[154:155], s[8:9], v0, s69, v[150:151]
	v_cvt_pk_bf16_f32 v148, v156, v157
	v_lshl_add_u64 v[154:155], v[154:155], 0, v[152:153]
	s_waitcnt lgkmcnt(0)
; __device__ __forceinline__ u32x4 pack8(const f32x4& v0, const f32x4& v1) { u32x4 w; w.x = cvt_pk_bf16(v0[0], v0[1]); w.y = cvt_pk_bf16(v0[2], v0[3]); w.z = cvt_pk_bf16(v1[0], v1[1]); w.w = cvt_pk_bf16(v1[2], v1[3]); return w; }
; __device__ __forceinline__ void epi_run(const Epi& E, f32x4 (&acc)[2][2][4][2], const Unit& u, int wr, int wc, int fr, int fq) {
;     ...
;         f32x4 sc[2][2];
; #pragma unroll
;         for (int bj = 0; bj < 2; ++bj) { sc[bj][0] = *(const f32x4*)(E.pool_scale + col0 + bj * 128); sc[bj][1] = *(const f32x4*)(E.pool_scale + col0 + bj * 128 + 4); }
; #pragma unroll
;         for (int ai = 0; ai < 2; ++ai)
; #pragma unroll
;             for (int m = 0; m < 4; ++m)
; #pragma unroll
;                 for (int bj = 0; bj < 2; ++bj) *(u32x4*)(E.Z + (size_t)(row0 + ai * 128 + m * 16) * NIN + col0 + bj * 128) = pack8(acc[ai][bj][m][0] * sc[bj][0], acc[ai][bj][m][1] * sc[bj][1]);
	global_store_dwordx4 v[170:171], v[164:167], off offset:256
	v_lshl_add_u64 v[168:169], v[154:155], 0, v[172:173]
	ds_bpermute_b32 v160, v174, v146
	ds_bpermute_b32 v161, v174, v147
	ds_bpermute_b32 v162, v174, v148
	ds_bpermute_b32 v163, v174, v149
	v_pk_mul_f32 v[156:157], v[68:69], v[132:133]
	v_add_u32_e32 v0, 0x80, v210
	v_pk_mul_f32 v[148:149], v[72:73], v[140:141]
	v_pk_mul_f32 v[146:147], v[70:71], v[138:139]
	s_nop 0
	v_cvt_pk_bf16_f32 v146, v146, v147
	v_cvt_pk_bf16_f32 v147, v148, v149
	v_cvt_pk_bf16_f32 v148, v158, v159
	v_cvt_pk_bf16_f32 v149, v156, v157
	s_waitcnt lgkmcnt(0)
	global_store_dwordx4 v[168:169], v[160:163], off
	v_lshl_add_u64 v[170:171], v[154:155], 0, v[172:173]
	ds_bpermute_b32 v164, v174, v146
	ds_bpermute_b32 v165, v174, v147
	ds_bpermute_b32 v166, v174, v148
	ds_bpermute_b32 v167, v174, v149
	v_pk_mul_f32 v[154:155], v[60:61], v[136:137]
	v_pk_mul_f32 v[156:157], v[58:59], v[134:135]
	v_pk_mul_f32 v[148:149], v[64:65], v[144:145]
	v_pk_mul_f32 v[146:147], v[62:63], v[142:143]
	v_pk_mul_f32 v[158:159], v[50:51], v[130:131]
	v_cvt_pk_bf16_f32 v146, v146, v147
	v_cvt_pk_bf16_f32 v147, v148, v149
	v_cvt_pk_bf16_f32 v149, v154, v155
	v_mad_i64_i32 v[154:155], s[8:9], v0, s69, v[150:151]
	v_cvt_pk_bf16_f32 v148, v156, v157
	v_lshl_add_u64 v[154:155], v[154:155], 0, v[152:153]
	s_waitcnt lgkmcnt(0)
	global_store_dwordx4 v[170:171], v[164:167], off offset:256
	v_lshl_add_u64 v[168:169], v[154:155], 0, v[172:173]
	ds_bpermute_b32 v160, v174, v146
	ds_bpermute_b32 v161, v174, v147
	ds_bpermute_b32 v162, v174, v148
	ds_bpermute_b32 v163, v174, v149
	v_pk_mul_f32 v[156:157], v[52:53], v[132:133]
	v_add_u32_e32 v0, 0x90, v210
	v_pk_mul_f32 v[148:149], v[56:57], v[140:141]
	v_pk_mul_f32 v[146:147], v[54:55], v[138:139]
	s_nop 0
	v_cvt_pk_bf16_f32 v146, v146, v147
	v_cvt_pk_bf16_f32 v147, v148, v149
	v_cvt_pk_bf16_f32 v148, v158, v159
	v_cvt_pk_bf16_f32 v149, v156, v157
	s_waitcnt lgkmcnt(0)
	global_store_dwordx4 v[168:169], v[160:163], off
	v_lshl_add_u64 v[170:171], v[154:155], 0, v[172:173]
	ds_bpermute_b32 v164, v174, v146
	ds_bpermute_b32 v165, v174, v147
	ds_bpermute_b32 v166, v174, v148
	ds_bpermute_b32 v167, v174, v149
	v_pk_mul_f32 v[154:155], v[44:45], v[136:137]
	v_pk_mul_f32 v[156:157], v[42:43], v[134:135]
	v_pk_mul_f32 v[148:149], v[48:49], v[144:145]
	v_pk_mul_f32 v[146:147], v[46:47], v[142:143]
	v_pk_mul_f32 v[158:159], v[34:35], v[130:131]
	v_cvt_pk_bf16_f32 v146, v146, v147
	v_cvt_pk_bf16_f32 v147, v148, v149
	v_cvt_pk_bf16_f32 v149, v154, v155
	v_mad_i64_i32 v[154:155], s[8:9], v0, s69, v[150:151]
	v_cvt_pk_bf16_f32 v148, v156, v157
	v_lshl_add_u64 v[154:155], v[154:155], 0, v[152:153]
	s_waitcnt lgkmcnt(0)
	global_store_dwordx4 v[170:171], v[164:167], off offset:256
	v_lshl_add_u64 v[168:169], v[154:155], 0, v[172:173]
	ds_bpermute_b32 v160, v174, v146
	ds_bpermute_b32 v161, v174, v147
	ds_bpermute_b32 v162, v174, v148
	ds_bpermute_b32 v163, v174, v149
	v_pk_mul_f32 v[156:157], v[36:37], v[132:133]
	v_add_u32_e32 v0, 0xa0, v210
	v_pk_mul_f32 v[148:149], v[40:41], v[140:141]
	v_pk_mul_f32 v[146:147], v[38:39], v[138:139]
	s_nop 0
	v_cvt_pk_bf16_f32 v146, v146, v147
	v_cvt_pk_bf16_f32 v147, v148, v149
	v_cvt_pk_bf16_f32 v148, v158, v159
	v_cvt_pk_bf16_f32 v149, v156, v157
	s_waitcnt lgkmcnt(0)
	global_store_dwordx4 v[168:169], v[160:163], off
	v_lshl_add_u64 v[170:171], v[154:155], 0, v[172:173]
	ds_bpermute_b32 v164, v174, v146
	ds_bpermute_b32 v165, v174, v147
	ds_bpermute_b32 v166, v174, v148
	ds_bpermute_b32 v167, v174, v149
	v_pk_mul_f32 v[154:155], v[28:29], v[136:137]
	v_pk_mul_f32 v[156:157], v[26:27], v[134:135]
	v_pk_mul_f32 v[148:149], v[32:33], v[144:145]
	v_pk_mul_f32 v[146:147], v[30:31], v[142:143]
	v_pk_mul_f32 v[158:159], v[18:19], v[130:131]
	v_cvt_pk_bf16_f32 v146, v146, v147
	v_cvt_pk_bf16_f32 v147, v148, v149
	v_cvt_pk_bf16_f32 v149, v154, v155
	v_mad_i64_i32 v[154:155], s[8:9], v0, s69, v[150:151]
	v_cvt_pk_bf16_f32 v148, v156, v157
	v_lshl_add_u64 v[154:155], v[154:155], 0, v[152:153]
	s_waitcnt lgkmcnt(0)
	global_store_dwordx4 v[170:171], v[164:167], off offset:256
	v_lshl_add_u64 v[168:169], v[154:155], 0, v[172:173]
	ds_bpermute_b32 v160, v174, v146
	ds_bpermute_b32 v161, v174, v147
	ds_bpermute_b32 v162, v174, v148
	ds_bpermute_b32 v163, v174, v149
	v_pk_mul_f32 v[156:157], v[20:21], v[132:133]
	v_add_u32_e32 v0, 0xb0, v210
	v_pk_mul_f32 v[148:149], v[24:25], v[140:141]
	v_pk_mul_f32 v[146:147], v[22:23], v[138:139]
	v_pk_mul_f32 v[142:143], v[14:15], v[142:143]
	v_cvt_pk_bf16_f32 v146, v146, v147
	v_cvt_pk_bf16_f32 v147, v148, v149
	v_cvt_pk_bf16_f32 v148, v158, v159
	v_cvt_pk_bf16_f32 v149, v156, v157
	s_waitcnt lgkmcnt(0)
	global_store_dwordx4 v[168:169], v[160:163], off
	v_lshl_add_u64 v[170:171], v[154:155], 0, v[172:173]
	ds_bpermute_b32 v164, v174, v146
	ds_bpermute_b32 v165, v174, v147
	ds_bpermute_b32 v166, v174, v148
	ds_bpermute_b32 v167, v174, v149
	v_pk_mul_f32 v[144:145], v[16:17], v[144:145]
	s_nop 0
	v_pk_mul_f32 v[146:147], v[12:13], v[136:137]
	v_pk_mul_f32 v[136:137], v[10:11], v[134:135]
	v_cvt_pk_bf16_f32 v134, v142, v143
	v_mad_i64_i32 v[142:143], s[8:9], v0, s69, v[150:151]
	v_cvt_pk_bf16_f32 v135, v144, v145
	v_cvt_pk_bf16_f32 v136, v136, v137
	v_cvt_pk_bf16_f32 v137, v146, v147
	v_lshl_add_u64 v[142:143], v[142:143], 0, v[152:153]
	s_waitcnt lgkmcnt(0)
	global_store_dwordx4 v[170:171], v[164:167], off offset:256
	v_lshl_add_u64 v[168:169], v[142:143], 0, v[172:173]
	ds_bpermute_b32 v160, v174, v134
	ds_bpermute_b32 v161, v174, v135
	ds_bpermute_b32 v162, v174, v136
	ds_bpermute_b32 v163, v174, v137
	s_nop 1
	v_pk_mul_f32 v[134:135], v[8:9], v[140:141]
	v_pk_mul_f32 v[136:137], v[6:7], v[138:139]
	v_pk_mul_f32 v[138:139], v[4:5], v[132:133]
	v_pk_mul_f32 v[132:133], v[2:3], v[130:131]
	v_cvt_pk_bf16_f32 v130, v136, v137
	v_cvt_pk_bf16_f32 v131, v134, v135
	v_cvt_pk_bf16_f32 v132, v132, v133
	v_cvt_pk_bf16_f32 v133, v138, v139
	s_waitcnt lgkmcnt(0)
	global_store_dwordx4 v[168:169], v[160:163], off
	v_lshl_add_u64 v[170:171], v[142:143], 0, v[172:173]
	ds_bpermute_b32 v164, v174, v130
	ds_bpermute_b32 v165, v174, v131
	ds_bpermute_b32 v166, v174, v132
	ds_bpermute_b32 v167, v174, v133
	s_waitcnt lgkmcnt(0)
	global_store_dwordx4 v[170:171], v[164:167], off offset:256

; __device__ __forceinline__ void epi_rstd(const float* ssq, int row0, int fq, float (&rs)[2][4]) {
;     float part[2][4][4];
; #pragma unroll
;     for (int ai = 0; ai < 2; ++ai)
; #pragma unroll
;         for (int m = 0; m < 4; ++m)
; #pragma unroll
;             for (int j = 0; j < 4; ++j) part[ai][m][j] = ssq[(size_t)(4 * fq + j) * M + row0 + ai * 128 + m * 16];
; #pragma unroll
;     for (int ai = 0; ai < 2; ++ai)
; #pragma unroll
;         for (int m = 0; m < 4; ++m) { float t = (part[ai][m][0] + part[ai][m][1]) + (part[ai][m][2] + part[ai][m][3]); t += __shfl_xor(t, 16); t += __shfl_xor(t, 32); rs[ai][m] = __builtin_amdgcn_rsqf(t * (1.0f / 1024.0f) + EPS); }
; __device__ __forceinline__ void epi_run(const Epi& E, f32x4 (&acc)[2][2][4][2], const Unit& u, int wr, int wc, int fr, int fq) {
;     ...
;         float rs[2][4]; epi_rstd(E.ssq_in, row0, fq, rs);
;         float* sslot = E.ssq_out + (size_t)(u.pn * 4 + wc) * M;
; #pragma unroll
;         for (int ai = 0; ai < 2; ++ai)
; #pragma unroll
;             for (int mh = 0; mh < 2; ++mh) { u32x4 x[2][2], c[2][2];
; #pragma unroll
;                 for (int mm = 0; mm < 2; ++mm)
; #pragma unroll
;                     for (int bj = 0; bj < 2; ++bj) { const size_t off = (size_t)(row0 + ai * 128 + (2 * mh + mm) * 16) * D + col0 + bj * 128; x[mm][bj] = *(const u32x4*)(E.xin16 + off); c[mm][bj] = *(const u32x4*)(E.C16 + off); }
.LBB0_308:
	s_and_b64 vcc, exec, s[96:97]
	s_cbranch_vccz .LBB0_326
	v_lshrrev_b32_e32 v218, 2, v201
	v_and_b32_e32 v219, 3, v201
	v_lshl_add_u32 v243, v219, 4, v218
	v_lshlrev_b32_e32 v243, 2, v243
	v_and_b32_e32 v220, 15, v201
	v_sub_u32_e32 v218, v218, v220
	v_lshrrev_b32_e32 v220, 4, v201
	v_sub_u32_e32 v219, v219, v220
	v_lshlrev_b32_e32 v219, 4, v219
	v_lshlrev_b32_e32 v218, 11, v218
	v_add_u32_e32 v230, v218, v219
	v_ashrrev_i32_e32 v231, 31, v230
	v_readlane_b32 s8, v250, 3
	v_ashrrev_i32_e32 v211, 31, v210
	v_readlane_b32 s9, v250, 4
	v_lshlrev_b32_e32 v0, 2, v198
	v_lshlrev_b32_e32 v136, 2, v202
	s_waitcnt lgkmcnt(0)
	v_lshl_add_u64 v[130:131], v[210:211], 2, s[8:9]
	v_lshl_add_u64 v[132:133], v[130:131], 0, v[0:1]
	global_load_dword v152, v[132:133], off
	global_load_dword v158, v[132:133], off offset:64
	global_load_dword v159, v[132:133], off offset:128
	v_lshlrev_b32_e32 v0, 2, v200
	v_lshl_add_u64 v[134:135], v[130:131], 0, v[0:1]
	v_mov_b32_e32 v137, v1
	v_lshlrev_b32_e32 v140, 2, v204
	v_mov_b32_e32 v141, v1
	v_lshl_add_u64 v[144:145], v[130:131], 0, 64
	v_lshl_add_u64 v[150:151], v[130:131], 0, s[52:53]
	v_lshl_add_u64 v[138:139], v[130:131], 0, v[136:137]
	v_lshl_add_u64 v[142:143], v[130:131], 0, v[140:141]
	v_lshl_add_u64 v[146:147], v[144:145], 0, v[0:1]
	v_lshl_add_u64 v[148:149], v[144:145], 0, v[136:137]
	v_lshl_add_u64 v[144:145], v[144:145], 0, v[140:141]
	v_lshl_add_u64 v[154:155], v[150:151], 0, v[0:1]
	v_lshl_add_u64 v[156:157], v[150:151], 0, v[136:137]
	global_load_dword v134, v[134:135], off
	s_nop 0
	global_load_dword v153, v[138:139], off
	global_load_dword v135, v[142:143], off
	global_load_dword v160, v[146:147], off
	global_load_dword v161, v[148:149], off
	global_load_dword v162, v[144:145], off
	global_load_dword v163, v[154:155], off
	global_load_dword v164, v[156:157], off
	v_lshl_add_u64 v[138:139], v[150:151], 0, v[140:141]
	global_load_dword v165, v[138:139], off
	s_mov_b64 s[8:9], 0xc0
	v_lshl_add_u64 v[138:139], v[130:131], 0, s[8:9]
	s_mov_b64 s[8:9], 0x200
	v_lshl_add_u64 v[146:147], v[130:131], 0, s[8:9]
	s_mov_b64 s[8:9], 0x240
	global_load_dword v166, v[132:133], off offset:192
	global_load_dword v167, v[132:133], off offset:512
	global_load_dword v168, v[132:133], off offset:576
	v_lshl_add_u64 v[142:143], v[138:139], 0, v[0:1]
	v_lshl_add_u64 v[150:151], v[146:147], 0, v[136:137]
	v_lshl_add_u64 v[154:155], v[130:131], 0, s[8:9]
	v_lshl_add_u64 v[144:145], v[138:139], 0, v[136:137]
	v_lshl_add_u64 v[138:139], v[138:139], 0, v[140:141]
	v_lshl_add_u64 v[148:149], v[146:147], 0, v[0:1]
	v_lshl_add_u64 v[146:147], v[146:147], 0, v[140:141]
	v_lshl_add_u64 v[156:157], v[154:155], 0, v[0:1]
	global_load_dword v169, v[142:143], off
	global_load_dword v172, v[144:145], off
	global_load_dword v173, v[138:139], off
	global_load_dword v174, v[148:149], off
	s_nop 0
	global_load_dword v150, v[150:151], off
	s_nop 0
	global_load_dword v175, v[146:147], off
	global_load_dword v176, v[156:157], off
	s_mov_b64 s[8:9], 0x280
	v_lshl_add_u64 v[144:145], v[130:131], 0, s[8:9]
	v_lshl_add_u64 v[138:139], v[154:155], 0, v[136:137]
	v_lshl_add_u64 v[142:143], v[154:155], 0, v[140:141]
	v_lshl_add_u64 v[146:147], v[144:145], 0, v[0:1]
	v_lshl_add_u64 v[148:149], v[144:145], 0, v[136:137]
	v_lshl_add_u64 v[144:145], v[144:145], 0, v[140:141]
	global_load_dword v138, v[138:139], off
	s_nop 0
	global_load_dword v139, v[142:143], off
	s_nop 0
	global_load_dword v142, v[146:147], off
	global_load_dword v143, v[148:149], off
	s_nop 0
	global_load_dword v144, v[144:145], off
	s_nop 0
	global_load_dword v145, v[132:133], off offset:640
	global_load_dword v146, v[132:133], off offset:704
	s_mov_b64 s[8:9], 0x2c0
	v_lshl_add_u64 v[130:131], v[130:131], 0, s[8:9]
	v_lshl_add_u64 v[132:133], v[130:131], 0, v[0:1]
	v_lshl_add_u64 v[136:137], v[130:131], 0, v[136:137]
	v_lshl_add_u64 v[130:131], v[130:131], 0, v[140:141]
	global_load_dword v140, v[132:133], off
	s_nop 0
	global_load_dword v136, v[136:137], off
	s_nop 0
	global_load_dword v137, v[130:131], off
	v_cmp_lt_i32_e32 vcc, v233, v203
	v_ashrrev_i32_e32 v213, 31, v212
	v_lshlrev_b64 v[148:149], 11, v[210:211]
	v_cndmask_b32_e32 v0, v201, v233, vcc
	v_cmp_lt_i32_e32 vcc, v234, v203
	v_lshlrev_b32_e32 v171, 2, v0
	v_lshl_add_u64 v[148:149], s[78:79], 0, v[148:149]
	v_cndmask_b32_e32 v130, v201, v234, vcc
	v_lshlrev_b32_e32 v170, 2, v130
	v_lshlrev_b64 v[130:131], 10, v[210:211]
	v_lshl_add_u64 v[130:131], v[130:131], 0, v[212:213]
	v_lshlrev_b64 v[130:131], 1, v[130:131]
	v_lshl_add_u64 v[132:133], s[62:63], 0, v[130:131]
	global_load_dwordx4 v[154:157], v[132:133], off
	s_lshl_b32 s2, s23, 2
	v_readlane_b32 s8, v250, 29
	s_or_b32 s8, s2, s8
	s_ashr_i32 s9, s8, 31
	s_lshl_b64 s[8:9], s[8:9], 16
	s_add_u32 s44, s76, s8
	s_addc_u32 s45, s77, s9
	s_waitcnt vmcnt(0)
	v_pk_add_f32 v[132:133], v[152:153], v[134:135]
	s_nop 0
	v_add_f32_e32 v0, v132, v133
	ds_bpermute_b32 v132, v171, v0
	v_add_f32_e32 v133, v158, v160
	v_add_f32_e32 v134, v161, v162
	v_add_f32_e32 v133, v133, v134
	ds_bpermute_b32 v134, v171, v133
	s_waitcnt lgkmcnt(1)
	v_add_f32_e32 v0, v0, v132
	ds_bpermute_b32 v132, v170, v0
	v_add_f32_e32 v135, v159, v163
	v_add_f32_e32 v141, v164, v165
	s_waitcnt lgkmcnt(1)
	v_add_f32_e32 v151, v133, v134
	ds_bpermute_b32 v152, v170, v151
	s_waitcnt lgkmcnt(1)
	v_add_f32_e32 v0, v0, v132
	v_fmamk_f32 v0, v0, 0x3a800000, v197
	v_rsq_f32_e32 v182, v0
	v_add_f32_e32 v133, v166, v169
	v_add_f32_e32 v0, v135, v141
	v_add_f32_e32 v134, v172, v173
	v_add_f32_e32 v133, v133, v134
	ds_bpermute_b32 v132, v171, v0
	ds_bpermute_b32 v134, v171, v133
	v_add_f32_e32 v135, v167, v174
	v_add_f32_e32 v141, v150, v175
	v_add_f32_e32 v135, v135, v141
	s_waitcnt lgkmcnt(1)
; __device__ __forceinline__ float bf_lo(unsigned w) { return __uint_as_float(w << 16); }
; __device__ __forceinline__ float bf_hi(unsigned w) { return __uint_as_float(w & 0xffff0000u); }
; __device__ __forceinline__ float sigm(float v) { return __builtin_amdgcn_rcpf(1.0f + __builtin_amdgcn_exp2f(-1.44269504089f * v)); }
; __device__ __forceinline__ u32x4 pack8(const f32x4& v0, const f32x4& v1) { u32x4 w; w.x = cvt_pk_bf16(v0[0], v0[1]); w.y = cvt_pk_bf16(v0[2], v0[3]); w.z = cvt_pk_bf16(v1[0], v1[1]); w.w = cvt_pk_bf16(v1[2], v1[3]); return w; }
; __device__ __forceinline__ void epi_rstd(const float* ssq, int row0, int fq, float (&rs)[2][4]) {
;     ...
;         for (int m = 0; m < 4; ++m) { float t = (part[ai][m][0] + part[ai][m][1]) + (part[ai][m][2] + part[ai][m][3]); t += __shfl_xor(t, 16); t += __shfl_xor(t, 32); rs[ai][m] = __builtin_amdgcn_rsqf(t * (1.0f / 1024.0f) + EPS); }
; __device__ __forceinline__ void epi_run(const Epi& E, f32x4 (&acc)[2][2][4][2], const Unit& u, int wr, int wc, int fr, int fq) {
;     ...
;             for (int mh = 0; mh < 2; ++mh) { u32x4 x[2][2], c[2][2];
; #pragma unroll
;                 for (int mm = 0; mm < 2; ++mm)
; #pragma unroll
;                     for (int bj = 0; bj < 2; ++bj) { const size_t off = (size_t)(row0 + ai * 128 + (2 * mh + mm) * 16) * D + col0 + bj * 128; x[mm][bj] = *(const u32x4*)(E.xin16 + off); c[mm][bj] = *(const u32x4*)(E.C16 + off); }
; #pragma unroll
;                 for (int mm = 0; mm < 2; ++mm) { const int m = 2 * mh + mm, row = row0 + ai * 128 + m * 16; float sq = 0.f;
; #pragma unroll
;                     for (int bj = 0; bj < 2; ++bj) { const u32x4 xx = x[mm][bj], cc = c[mm][bj];
;                         const f32x4 c0 = (f32x4){bf_lo(cc.x), bf_hi(cc.x), bf_lo(cc.y), bf_hi(cc.y)}, c1 = (f32x4){bf_lo(cc.z), bf_hi(cc.z), bf_lo(cc.w), bf_hi(cc.w)};
;                         f32x4 v0 = acc[ai][bj][m][0] * rs[ai][m], v1 = acc[ai][bj][m][1] * rs[ai][m];
; #pragma unroll
;                         for (int e = 0; e < 4; ++e) { v0[e] = sigm(v0[e]) * c0[e]; v1[e] = sigm(v1[e]) * c1[e]; }
;                         const f32x4 x0 = (f32x4){bf_lo(xx.x), bf_hi(xx.x), bf_lo(xx.y), bf_hi(xx.y)} + v0, x1 = (f32x4){bf_lo(xx.z), bf_hi(xx.z), bf_lo(xx.w), bf_hi(xx.w)} + v1;
;                         sq += sumsq8(x0, x1); *(u32x4*)(E.xout16 + (size_t)row * D + col0 + bj * 128) = pack8(x0, x1); }
	v_add_f32_e32 v0, v0, v132
	s_waitcnt lgkmcnt(0)
	v_add_f32_e32 v180, v133, v134
	v_add_f32_e32 v132, v168, v176
	v_add_f32_e32 v133, v138, v139
	v_add_f32_e32 v134, v132, v133
	v_add_f32_e32 v132, v145, v142
	v_add_f32_e32 v133, v143, v144
	v_add_f32_e32 v138, v132, v133
	v_lshl_add_u64 v[132:133], s[48:49], 0, v[130:131]
	global_load_dwordx4 v[158:161], v[132:133], off
	v_or_b32_e32 v130, 0x100, v130
	v_lshl_add_u64 v[130:131], s[62:63], 0, v[130:131]
	global_load_dwordx4 v[166:169], v[130:131], off
	global_load_dwordx4 v[162:165], v[132:133], off offset:256
	ds_bpermute_b32 v141, v171, v135
	v_add_f32_e32 v140, v146, v140
	v_add_f32_e32 v136, v136, v137
	v_add_f32_e32 v136, v140, v136
	ds_bpermute_b32 v137, v171, v136
	s_waitcnt lgkmcnt(1)
	v_add_f32_e32 v178, v135, v141
	ds_bpermute_b32 v135, v171, v134
	v_or_b32_e32 v146, 16, v210
	v_ashrrev_i32_e32 v147, 31, v146
	ds_bpermute_b32 v139, v171, v138
	v_lshlrev_b64 v[130:131], 10, v[146:147]
	v_lshl_add_u64 v[130:131], v[130:131], 0, v[212:213]
	s_waitcnt lgkmcnt(1)
	v_add_f32_e32 v176, v134, v135
	v_lshlrev_b64 v[134:135], 1, v[130:131]
	v_add_f32_e32 v172, v136, v137
	v_lshl_add_u64 v[130:131], s[48:49], 0, v[134:135]
	v_lshl_add_u64 v[136:137], s[62:63], 0, v[134:135]
	v_or_b32_e32 v134, 0x100, v134
	v_lshl_add_u64 v[134:135], s[62:63], 0, v[134:135]
	s_waitcnt lgkmcnt(0)
	v_add_f32_e32 v174, v138, v139
	global_load_dwordx4 v[138:141], v[130:131], off
	s_nop 0
	global_load_dwordx4 v[130:133], v[130:131], off offset:256
	s_nop 0
	global_load_dwordx4 v[142:145], v[136:137], off
	s_nop 0
	global_load_dwordx4 v[134:137], v[134:135], off
	v_pk_mul_f32 v[184:185], v[126:127], v[182:183] op_sel_hi:[1,0]
	v_pk_mul_f32 v[190:191], v[122:123], v[182:183] op_sel_hi:[1,0]
	v_mul_f32_e32 v153, 0xbfb8aa3b, v184
	v_exp_f32_e32 v153, v153
	v_pk_mul_f32 v[186:187], v[128:129], v[182:183] op_sel_hi:[1,0]
	v_pk_mul_f32 v[188:189], v[124:125], v[182:183] op_sel_hi:[1,0]
	v_mul_f32_e32 v183, 0xbfb8aa3b, v190
	v_exp_f32_e32 v183, v183
	v_add_f32_e32 v153, 1.0, v153
	v_mul_f32_e32 v184, 0xbfb8aa3b, v185
	v_exp_f32_e32 v185, v184
	v_rcp_f32_e32 v184, v153
	v_add_f32_e32 v153, 1.0, v183
	v_mul_f32_e32 v183, 0xbfb8aa3b, v191
	v_exp_f32_e32 v183, v183
	v_lshlrev_b32_e32 v192, 16, v154
	v_and_b32_e32 v193, 0xffff0000, v154
	v_mul_f32_e32 v154, 0xbfb8aa3b, v186
	v_exp_f32_e32 v154, v154
	v_rcp_f32_e32 v190, v153
	v_add_f32_e32 v153, 1.0, v185
	v_rcp_f32_e32 v185, v153
	v_add_f32_e32 v153, 1.0, v183
	v_rcp_f32_e32 v191, v153
	v_add_f32_e32 v153, 1.0, v154
	v_mul_f32_e32 v154, 0xbfb8aa3b, v188
	v_lshlrev_b32_e32 v214, 16, v156
	v_and_b32_e32 v215, 0xffff0000, v156
	v_exp_f32_e32 v154, v154
	v_mul_f32_e32 v156, 0xbfb8aa3b, v187
	v_exp_f32_e32 v156, v156
	v_rcp_f32_e32 v186, v153
	v_add_f32_e32 v153, 1.0, v154
	v_rcp_f32_e32 v154, v153
	v_add_f32_e32 v153, 1.0, v156
	v_mul_f32_e32 v156, 0xbfb8aa3b, v189
	v_exp_f32_e32 v156, v156
	v_rcp_f32_e32 v187, v153
	v_lshlrev_b32_e32 v188, 16, v155
	v_and_b32_e32 v189, 0xffff0000, v155
	v_add_f32_e32 v153, 1.0, v156
	v_rcp_f32_e32 v155, v153
	v_lshlrev_b32_e32 v156, 16, v157
	v_and_b32_e32 v157, 0xffff0000, v157
	ds_bpermute_b32 v150, v170, v0
	ds_bpermute_b32 v181, v170, v180
	ds_bpermute_b32 v179, v170, v178
	ds_bpermute_b32 v177, v170, v176
	ds_bpermute_b32 v175, v170, v174
	ds_bpermute_b32 v173, v170, v172
	s_waitcnt vmcnt(6)
	v_lshlrev_b32_e32 v216, 16, v158
	v_and_b32_e32 v217, 0xffff0000, v158
	v_lshlrev_b32_e32 v158, 16, v159
	v_and_b32_e32 v159, 0xffff0000, v159
	v_pk_fma_f32 v[158:159], v[186:187], v[188:189], v[158:159]
	v_pk_fma_f32 v[184:185], v[184:185], v[192:193], v[216:217]
	v_lshlrev_b32_e32 v186, 16, v160
	v_and_b32_e32 v187, 0xffff0000, v160
	v_lshlrev_b32_e32 v160, 16, v161
	v_and_b32_e32 v161, 0xffff0000, v161
	v_pk_fma_f32 v[160:161], v[154:155], v[156:157], v[160:161]
	v_mul_f32_e32 v153, v185, v185
	v_mul_f32_e32 v154, v159, v159
	v_pk_fma_f32 v[156:157], v[190:191], v[214:215], v[186:187]
	v_fmac_f32_e32 v153, v184, v184
	v_fmac_f32_e32 v154, v158, v158
	v_add_f32_e32 v153, v153, v154
	v_mul_f32_e32 v154, v157, v157
	v_fmac_f32_e32 v154, v156, v156
	v_add_f32_e32 v153, v154, v153
	v_mul_f32_e32 v154, v161, v161
	v_fmac_f32_e32 v154, v160, v160
	v_add_f32_e32 v153, v154, v153
	v_cvt_pk_bf16_f32 v154, v184, v185
	v_cvt_pk_bf16_f32 v155, v158, v159
	v_cvt_pk_bf16_f32 v156, v156, v157
	v_cvt_pk_bf16_f32 v157, v160, v161
	v_pk_mul_f32 v[158:159], v[118:119], v[182:183] op_sel_hi:[1,0]
	v_pk_mul_f32 v[160:161], v[120:121], v[182:183] op_sel_hi:[1,0]
	v_pk_mul_f32 v[184:185], v[116:117], v[182:183] op_sel_hi:[1,0]
	v_pk_mul_f32 v[182:183], v[114:115], v[182:183] op_sel_hi:[1,0]
	v_mul_f32_e32 v158, 0xbfb8aa3b, v158
	v_mul_f32_e32 v183, 0xbfb8aa3b, v183
	v_exp_f32_e32 v183, v183
	v_mul_f32_e32 v159, 0xbfb8aa3b, v159
	s_waitcnt vmcnt(5)
	v_lshlrev_b32_e32 v186, 16, v166
	v_and_b32_e32 v187, 0xffff0000, v166
	v_add_f32_e32 v166, 1.0, v183
	v_mul_f32_e32 v160, 0xbfb8aa3b, v160
	v_mul_f32_e32 v161, 0xbfb8aa3b, v161
	v_exp_f32_e32 v158, v158
	v_exp_f32_e32 v159, v159
	v_exp_f32_e32 v160, v160
	v_rcp_f32_e32 v183, v166
	v_lshlrev_b32_e32 v188, 16, v168
	v_and_b32_e32 v189, 0xffff0000, v168
	v_mul_f32_e32 v166, 0xbfb8aa3b, v184
	v_exp_f32_e32 v161, v161
	v_mul_f32_e32 v168, 0xbfb8aa3b, v185
	v_mul_f32_e32 v182, 0xbfb8aa3b, v182
	v_exp_f32_e32 v166, v166
	v_exp_f32_e32 v168, v168
	v_exp_f32_e32 v182, v182
	v_add_f32_e32 v158, 1.0, v158
	v_add_f32_e32 v159, 1.0, v159
	v_add_f32_e32 v160, 1.0, v160
	v_add_f32_e32 v161, 1.0, v161
	v_rcp_f32_e32 v158, v158
	v_rcp_f32_e32 v159, v159
	v_rcp_f32_e32 v160, v160
	v_add_f32_e32 v166, 1.0, v166
	v_rcp_f32_e32 v161, v161
	v_lshlrev_b32_e32 v184, 16, v167
	v_and_b32_e32 v185, 0xffff0000, v167
	v_add_f32_e32 v167, 1.0, v168
	v_add_f32_e32 v182, 1.0, v182
	v_rcp_f32_e32 v166, v166
	v_rcp_f32_e32 v167, v167
	v_rcp_f32_e32 v182, v182
	s_waitcnt vmcnt(4)
; __device__ __forceinline__ float bf_lo(unsigned w) { return __uint_as_float(w << 16); }
; __device__ __forceinline__ float bf_hi(unsigned w) { return __uint_as_float(w & 0xffff0000u); }
; __device__ __forceinline__ float sigm(float v) { return __builtin_amdgcn_rcpf(1.0f + __builtin_amdgcn_exp2f(-1.44269504089f * v)); }
; __device__ __forceinline__ u32x4 pack8(const f32x4& v0, const f32x4& v1) { u32x4 w; w.x = cvt_pk_bf16(v0[0], v0[1]); w.y = cvt_pk_bf16(v0[2], v0[3]); w.z = cvt_pk_bf16(v1[0], v1[1]); w.w = cvt_pk_bf16(v1[2], v1[3]); return w; }
; __device__ __forceinline__ float sumsq8(const f32x4& v0, const f32x4& v1) { return (v0[0] * v0[0] + v0[1] * v0[1]) + (v0[2] * v0[2] + v0[3] * v0[3]) + (v1[0] * v1[0] + v1[1] * v1[1]) + (v1[2] * v1[2] + v1[3] * v1[3]); }
; __device__ __forceinline__ void epi_run(const Epi& E, f32x4 (&acc)[2][2][4][2], const Unit& u, int wr, int wc, int fr, int fq) {
;     ...
;                 for (int mm = 0; mm < 2; ++mm) { const int m = 2 * mh + mm, row = row0 + ai * 128 + m * 16; float sq = 0.f;
; #pragma unroll
;                     for (int bj = 0; bj < 2; ++bj) { const u32x4 xx = x[mm][bj], cc = c[mm][bj];
;                         const f32x4 c0 = (f32x4){bf_lo(cc.x), bf_hi(cc.x), bf_lo(cc.y), bf_hi(cc.y)}, c1 = (f32x4){bf_lo(cc.z), bf_hi(cc.z), bf_lo(cc.w), bf_hi(cc.w)};
;                         f32x4 v0 = acc[ai][bj][m][0] * rs[ai][m], v1 = acc[ai][bj][m][1] * rs[ai][m];
; #pragma unroll
;                         for (int e = 0; e < 4; ++e) { v0[e] = sigm(v0[e]) * c0[e]; v1[e] = sigm(v1[e]) * c1[e]; }
;                         const f32x4 x0 = (f32x4){bf_lo(xx.x), bf_hi(xx.x), bf_lo(xx.y), bf_hi(xx.y)} + v0, x1 = (f32x4){bf_lo(xx.z), bf_hi(xx.z), bf_lo(xx.w), bf_hi(xx.w)} + v1;
;                         sq += sumsq8(x0, x1); *(u32x4*)(E.xout16 + (size_t)row * D + col0 + bj * 128) = pack8(x0, x1); }
;                     sq += __shfl_xor(sq, 16); sq += __shfl_xor(sq, 32); if (fq == 0) sslot[row] = sq; }
	v_lshlrev_b32_e32 v190, 16, v162
	v_and_b32_e32 v191, 0xffff0000, v162
	v_lshlrev_b32_e32 v162, 16, v163
	v_and_b32_e32 v163, 0xffff0000, v163
	v_lshlrev_b32_e32 v168, 16, v169
	v_and_b32_e32 v169, 0xffff0000, v169
	v_pk_fma_f32 v[160:161], v[160:161], v[184:185], v[162:163]
	v_pk_fma_f32 v[158:159], v[158:159], v[186:187], v[190:191]
	v_lshlrev_b32_e32 v162, 16, v164
	v_and_b32_e32 v163, 0xffff0000, v164
	v_lshlrev_b32_e32 v164, 16, v165
	v_and_b32_e32 v165, 0xffff0000, v165
	v_pk_fma_f32 v[164:165], v[166:167], v[168:169], v[164:165]
	v_mul_f32_e32 v166, v159, v159
	v_mul_f32_e32 v167, v161, v161
	v_pk_fma_f32 v[162:163], v[182:183], v[188:189], v[162:163]
	v_fmac_f32_e32 v166, v158, v158
	v_fmac_f32_e32 v167, v160, v160
	v_add_f32_e32 v166, v166, v167
	v_mul_f32_e32 v167, v163, v163
	v_fmac_f32_e32 v167, v162, v162
	v_add_f32_e32 v166, v167, v166
	v_mul_f32_e32 v167, v165, v165
	v_fmac_f32_e32 v167, v164, v164
	v_add_f32_e32 v166, v167, v166
	v_add_f32_e32 v153, v153, v166
	ds_bpermute_b32 v168, v171, v153
	v_lshl_add_u64 v[166:167], v[212:213], 1, v[148:149]
	v_lshl_add_u64 v[226:227], v[166:167], 0, v[230:231]
	ds_bpermute_b32 v218, v243, v154
	ds_bpermute_b32 v219, v243, v155
	ds_bpermute_b32 v220, v243, v156
	ds_bpermute_b32 v221, v243, v157
	s_waitcnt lgkmcnt(0)
	v_add_f32_e32 v148, v153, v168
	ds_bpermute_b32 v149, v170, v148
	v_cvt_pk_bf16_f32 v154, v158, v159
	v_cvt_pk_bf16_f32 v155, v160, v161
	v_cvt_pk_bf16_f32 v156, v162, v163
	v_cvt_pk_bf16_f32 v157, v164, v165
	s_waitcnt lgkmcnt(0)
	global_store_dwordx4 v[226:227], v[218:221], off
	v_lshl_add_u64 v[228:229], v[166:167], 0, v[230:231]
	ds_bpermute_b32 v222, v243, v154
	ds_bpermute_b32 v223, v243, v155
	ds_bpermute_b32 v224, v243, v156
	ds_bpermute_b32 v225, v243, v157
	s_and_saveexec_b64 s[8:9], s[40:41]
	s_cbranch_execz .LBB0_311
	v_lshl_add_u64 v[154:155], v[210:211], 2, s[44:45]
	s_waitcnt lgkmcnt(0)
	v_add_f32_e32 v148, v148, v149
	global_store_dword v[154:155], v148, off
.LBB0_311:
	s_or_b64 exec, exec, s[8:9]
	v_add_f32_e32 v148, v151, v152
	v_fmamk_f32 v148, v148, 0x3a800000, v197
	v_rsq_f32_e32 v148, v148
	s_waitcnt vmcnt(3)
	v_lshlrev_b32_e32 v160, 16, v142
	v_and_b32_e32 v161, 0xffff0000, v142
	v_lshlrev_b32_e32 v162, 16, v144
	s_waitcnt lgkmcnt(0)
	v_pk_mul_f32 v[154:155], v[110:111], v[148:149] op_sel_hi:[1,0]
	v_pk_mul_f32 v[152:153], v[112:113], v[148:149] op_sel_hi:[1,0]
	v_pk_mul_f32 v[156:157], v[108:109], v[148:149] op_sel_hi:[1,0]
	v_mul_f32_e32 v149, 0xbfb8aa3b, v154
	v_exp_f32_e32 v149, v149
	v_mul_f32_e32 v154, 0xbfb8aa3b, v155
	v_exp_f32_e32 v155, v154
	v_and_b32_e32 v163, 0xffff0000, v144
	v_pk_mul_f32 v[158:159], v[106:107], v[148:149] op_sel_hi:[1,0]
	v_add_f32_e32 v149, 1.0, v149
	v_mul_f32_e32 v151, 0xbfb8aa3b, v158
	v_exp_f32_e32 v151, v151
	v_rcp_f32_e32 v154, v149
	v_mul_f32_e32 v144, 0xbfb8aa3b, v156
	v_exp_f32_e32 v144, v144
	v_add_f32_e32 v149, 1.0, v151
	v_rcp_f32_e32 v158, v149
	v_add_f32_e32 v149, 1.0, v155
	v_mul_f32_e32 v151, 0xbfb8aa3b, v159
	v_exp_f32_e32 v151, v151
	v_rcp_f32_e32 v155, v149
	v_mul_f32_e32 v149, 0xbfb8aa3b, v152
	v_exp_f32_e32 v149, v149
	v_add_f32_e32 v142, 1.0, v151
	v_rcp_f32_e32 v159, v142
	v_lshlrev_b32_e32 v156, 16, v143
	v_add_f32_e32 v142, 1.0, v149
	v_mul_f32_e32 v149, 0xbfb8aa3b, v153
	v_exp_f32_e32 v149, v149
	v_rcp_f32_e32 v152, v142
	v_add_f32_e32 v142, 1.0, v144
	v_rcp_f32_e32 v142, v142
	v_add_f32_e32 v144, 1.0, v149
	v_mul_f32_e32 v149, 0xbfb8aa3b, v157
	v_exp_f32_e32 v149, v149
	v_rcp_f32_e32 v153, v144
	v_and_b32_e32 v157, 0xffff0000, v143
	v_lshlrev_b32_e32 v164, 16, v138
	v_add_f32_e32 v143, 1.0, v149
	v_rcp_f32_e32 v143, v143
	v_and_b32_e32 v165, 0xffff0000, v138
	v_lshlrev_b32_e32 v138, 16, v139
	v_and_b32_e32 v139, 0xffff0000, v139
	v_lshlrev_b32_e32 v144, 16, v145
	v_and_b32_e32 v145, 0xffff0000, v145
	v_pk_fma_f32 v[152:153], v[152:153], v[156:157], v[138:139]
	v_pk_fma_f32 v[138:139], v[154:155], v[160:161], v[164:165]
	v_lshlrev_b32_e32 v154, 16, v140
	v_and_b32_e32 v155, 0xffff0000, v140
	v_lshlrev_b32_e32 v140, 16, v141
	v_and_b32_e32 v141, 0xffff0000, v141
	v_pk_fma_f32 v[142:143], v[142:143], v[144:145], v[140:141]
	v_mul_f32_e32 v144, v139, v139
	v_mul_f32_e32 v145, v153, v153
	v_pk_fma_f32 v[140:141], v[158:159], v[162:163], v[154:155]
	v_fmac_f32_e32 v144, v138, v138
	v_fmac_f32_e32 v145, v152, v152
	v_add_f32_e32 v144, v144, v145
	v_mul_f32_e32 v145, v141, v141
	v_fmac_f32_e32 v145, v140, v140
	v_add_f32_e32 v144, v145, v144
	v_mul_f32_e32 v145, v143, v143
	v_fmac_f32_e32 v145, v142, v142
	v_add_f32_e32 v151, v145, v144
	v_cvt_pk_bf16_f32 v138, v138, v139
	v_cvt_pk_bf16_f32 v139, v152, v153
	v_cvt_pk_bf16_f32 v140, v140, v141
	v_cvt_pk_bf16_f32 v141, v142, v143
	v_pk_mul_f32 v[142:143], v[102:103], v[148:149] op_sel_hi:[1,0]
	v_pk_mul_f32 v[144:145], v[104:105], v[148:149] op_sel_hi:[1,0]
	v_pk_mul_f32 v[152:153], v[96:97], v[148:149] op_sel_hi:[1,0]
	v_pk_mul_f32 v[148:149], v[94:95], v[148:149] op_sel_hi:[1,0]
	v_mul_f32_e32 v144, 0xbfb8aa3b, v144
	v_mul_f32_e32 v149, 0xbfb8aa3b, v149
	v_exp_f32_e32 v149, v149
	v_exp_f32_e32 v144, v144
	s_waitcnt vmcnt(2)
; __device__ __forceinline__ float bf_lo(unsigned w) { return __uint_as_float(w << 16); }
; __device__ __forceinline__ float bf_hi(unsigned w) { return __uint_as_float(w & 0xffff0000u); }
; __device__ __forceinline__ float sigm(float v) { return __builtin_amdgcn_rcpf(1.0f + __builtin_amdgcn_exp2f(-1.44269504089f * v)); }
; __device__ __forceinline__ u32x4 pack8(const f32x4& v0, const f32x4& v1) { u32x4 w; w.x = cvt_pk_bf16(v0[0], v0[1]); w.y = cvt_pk_bf16(v0[2], v0[3]); w.z = cvt_pk_bf16(v1[0], v1[1]); w.w = cvt_pk_bf16(v1[2], v1[3]); return w; }
; __device__ __forceinline__ float sumsq8(const f32x4& v0, const f32x4& v1) { return (v0[0] * v0[0] + v0[1] * v0[1]) + (v0[2] * v0[2] + v0[3] * v0[3]) + (v1[0] * v1[0] + v1[1] * v1[1]) + (v1[2] * v1[2] + v1[3] * v1[3]); }
; __device__ __forceinline__ void epi_run(const Epi& E, f32x4 (&acc)[2][2][4][2], const Unit& u, int wr, int wc, int fr, int fq) {
;     ...
;             for (int mh = 0; mh < 2; ++mh) { u32x4 x[2][2], c[2][2];
; #pragma unroll
;                 for (int mm = 0; mm < 2; ++mm)
; #pragma unroll
;                     for (int bj = 0; bj < 2; ++bj) { const size_t off = (size_t)(row0 + ai * 128 + (2 * mh + mm) * 16) * D + col0 + bj * 128; x[mm][bj] = *(const u32x4*)(E.xin16 + off); c[mm][bj] = *(const u32x4*)(E.C16 + off); }
; #pragma unroll
;                 for (int mm = 0; mm < 2; ++mm) { const int m = 2 * mh + mm, row = row0 + ai * 128 + m * 16; float sq = 0.f;
; #pragma unroll
;                     for (int bj = 0; bj < 2; ++bj) { const u32x4 xx = x[mm][bj], cc = c[mm][bj];
;                         const f32x4 c0 = (f32x4){bf_lo(cc.x), bf_hi(cc.x), bf_lo(cc.y), bf_hi(cc.y)}, c1 = (f32x4){bf_lo(cc.z), bf_hi(cc.z), bf_lo(cc.w), bf_hi(cc.w)};
;                         f32x4 v0 = acc[ai][bj][m][0] * rs[ai][m], v1 = acc[ai][bj][m][1] * rs[ai][m];
; #pragma unroll
;                         for (int e = 0; e < 4; ++e) { v0[e] = sigm(v0[e]) * c0[e]; v1[e] = sigm(v1[e]) * c1[e]; }
;                         const f32x4 x0 = (f32x4){bf_lo(xx.x), bf_hi(xx.x), bf_lo(xx.y), bf_hi(xx.y)} + v0, x1 = (f32x4){bf_lo(xx.z), bf_hi(xx.z), bf_lo(xx.w), bf_hi(xx.w)} + v1;
;                         sq += sumsq8(x0, x1); *(u32x4*)(E.xout16 + (size_t)row * D + col0 + bj * 128) = pack8(x0, x1); }
;                     sq += __shfl_xor(sq, 16); sq += __shfl_xor(sq, 32); if (fq == 0) sslot[row] = sq; }
	v_lshlrev_b32_e32 v154, 16, v134
	v_and_b32_e32 v155, 0xffff0000, v134
	v_add_f32_e32 v134, 1.0, v149
	v_rcp_f32_e32 v149, v134
	v_lshlrev_b32_e32 v156, 16, v136
	v_and_b32_e32 v157, 0xffff0000, v136
	v_add_f32_e32 v134, 1.0, v144
	v_mul_f32_e32 v136, 0xbfb8aa3b, v152
	v_mul_f32_e32 v144, 0xbfb8aa3b, v145
	v_exp_f32_e32 v136, v136
	v_exp_f32_e32 v145, v144
	v_mul_f32_e32 v142, 0xbfb8aa3b, v142
	v_mul_f32_e32 v143, 0xbfb8aa3b, v143
	v_exp_f32_e32 v142, v142
	v_exp_f32_e32 v143, v143
	v_rcp_f32_e32 v144, v134
	v_add_f32_e32 v134, 1.0, v136
	v_add_f32_e32 v136, 1.0, v145
	v_mul_f32_e32 v145, 0xbfb8aa3b, v153
	v_mul_f32_e32 v148, 0xbfb8aa3b, v148
	v_exp_f32_e32 v158, v145
	v_exp_f32_e32 v148, v148
	v_add_f32_e32 v142, 1.0, v142
	v_add_f32_e32 v143, 1.0, v143
	v_rcp_f32_e32 v142, v142
	v_rcp_f32_e32 v143, v143
	v_rcp_f32_e32 v145, v136
	v_lshlrev_b32_e32 v152, 16, v135
	v_and_b32_e32 v153, 0xffff0000, v135
	v_add_f32_e32 v135, 1.0, v158
	v_add_f32_e32 v148, 1.0, v148
	v_rcp_f32_e32 v134, v134
	v_rcp_f32_e32 v135, v135
	v_rcp_f32_e32 v148, v148
	v_lshlrev_b32_e32 v158, 16, v130
	v_and_b32_e32 v159, 0xffff0000, v130
	v_lshlrev_b32_e32 v130, 16, v131
	v_and_b32_e32 v131, 0xffff0000, v131
	v_lshlrev_b32_e32 v136, 16, v137
	v_and_b32_e32 v137, 0xffff0000, v137
	v_pk_fma_f32 v[144:145], v[144:145], v[152:153], v[130:131]
	v_pk_fma_f32 v[130:131], v[142:143], v[154:155], v[158:159]
	v_lshlrev_b32_e32 v142, 16, v132
	v_and_b32_e32 v143, 0xffff0000, v132
	v_lshlrev_b32_e32 v132, 16, v133
	v_and_b32_e32 v133, 0xffff0000, v133
	v_pk_fma_f32 v[136:137], v[134:135], v[136:137], v[132:133]
	v_mul_f32_e32 v132, v131, v131
	v_mul_f32_e32 v133, v145, v145
	v_pk_fma_f32 v[134:135], v[148:149], v[156:157], v[142:143]
	v_fmac_f32_e32 v132, v130, v130
	v_fmac_f32_e32 v133, v144, v144
	v_add_f32_e32 v132, v132, v133
	v_mul_f32_e32 v133, v135, v135
	v_fmac_f32_e32 v133, v134, v134
	v_add_f32_e32 v132, v133, v132
	v_mul_f32_e32 v133, v137, v137
	v_fmac_f32_e32 v133, v136, v136
	v_add_f32_e32 v132, v133, v132
	v_add_f32_e32 v148, v151, v132
	ds_bpermute_b32 v149, v171, v148
	v_lshlrev_b64 v[146:147], 11, v[146:147]
	v_lshl_add_u64 v[132:133], s[78:79], 0, v[146:147]
	v_lshl_add_u64 v[142:143], v[212:213], 1, v[132:133]
	v_cvt_pk_bf16_f32 v132, v130, v131
	s_waitcnt lgkmcnt(0)
	v_add_f32_e32 v130, v148, v149
	ds_bpermute_b32 v131, v170, v130
	v_cvt_pk_bf16_f32 v133, v144, v145
	v_cvt_pk_bf16_f32 v134, v134, v135
	v_cvt_pk_bf16_f32 v135, v136, v137
	s_waitcnt lgkmcnt(0)
	global_store_dwordx4 v[228:229], v[222:225], off offset:256
	v_lshl_add_u64 v[226:227], v[142:143], 0, v[230:231]
	ds_bpermute_b32 v218, v243, v138
	ds_bpermute_b32 v219, v243, v139
	ds_bpermute_b32 v220, v243, v140
	ds_bpermute_b32 v221, v243, v141
	s_waitcnt lgkmcnt(0)
	global_store_dwordx4 v[226:227], v[218:221], off
	v_lshl_add_u64 v[228:229], v[142:143], 0, v[230:231]
	ds_bpermute_b32 v222, v243, v132
	ds_bpermute_b32 v223, v243, v133
	ds_bpermute_b32 v224, v243, v134
	ds_bpermute_b32 v225, v243, v135
	s_and_saveexec_b64 s[8:9], s[40:41]
	s_cbranch_execz .LBB0_313
	v_lshl_add_u64 v[132:133], v[210:211], 2, s[44:45]
	s_waitcnt lgkmcnt(0)
	v_add_f32_e32 v130, v130, v131
	global_store_dword v[132:133], v130, off offset:64
.LBB0_313:
	s_or_b64 exec, exec, s[8:9]
	v_or_b32_e32 v164, 32, v210
	v_ashrrev_i32_e32 v165, 31, v164
	s_waitcnt lgkmcnt(0)
	v_lshlrev_b64 v[130:131], 10, v[164:165]
	v_lshl_add_u64 v[130:131], v[130:131], 0, v[212:213]
	v_lshlrev_b64 v[130:131], 1, v[130:131]
	v_lshl_add_u64 v[132:133], s[48:49], 0, v[130:131]
	v_lshl_add_u64 v[134:135], s[62:63], 0, v[130:131]
	global_load_dwordx4 v[154:157], v[132:133], off
	global_load_dwordx4 v[158:161], v[134:135], off
	global_load_dwordx4 v[146:149], v[132:133], off offset:256
	v_or_b32_e32 v130, 0x100, v130
	v_lshl_add_u64 v[130:131], s[62:63], 0, v[130:131]
	v_add_f32_e32 v0, v0, v150
	global_load_dwordx4 v[150:153], v[130:131], off
	v_fmamk_f32 v0, v0, 0x3a800000, v197
	v_rsq_f32_e32 v0, v0
	v_or_b32_e32 v162, 48, v210
	v_ashrrev_i32_e32 v163, 31, v162
	v_lshlrev_b64 v[130:131], 10, v[162:163]
	v_pk_mul_f32 v[166:167], v[98:99], v[0:1] op_sel_hi:[1,0]
	v_pk_mul_f32 v[186:187], v[90:91], v[0:1] op_sel_hi:[1,0]
	v_mul_f32_e32 v167, 0xbfb8aa3b, v167
	v_exp_f32_e32 v167, v167
	v_pk_mul_f32 v[182:183], v[100:101], v[0:1] op_sel_hi:[1,0]
	v_mul_f32_e32 v166, 0xbfb8aa3b, v166
	v_exp_f32_e32 v166, v166
	v_add_f32_e32 v167, 1.0, v167
	v_rcp_f32_e32 v169, v167
	v_pk_mul_f32 v[184:185], v[92:93], v[0:1] op_sel_hi:[1,0]
	v_add_f32_e32 v166, 1.0, v166
	v_rcp_f32_e32 v168, v166
	v_mul_f32_e32 v166, 0xbfb8aa3b, v186
	v_exp_f32_e32 v166, v166
	v_lshl_add_u64 v[130:131], v[130:131], 0, v[212:213]
	v_lshlrev_b64 v[134:135], 1, v[130:131]
	v_lshl_add_u64 v[130:131], s[48:49], 0, v[134:135]
	v_add_f32_e32 v166, 1.0, v166
	v_rcp_f32_e32 v166, v166
	v_lshl_add_u64 v[132:133], s[62:63], 0, v[134:135]
	v_or_b32_e32 v134, 0x100, v134
	v_lshl_add_u64 v[134:135], s[62:63], 0, v[134:135]
	global_load_dwordx4 v[138:141], v[130:131], off
	global_load_dwordx4 v[142:145], v[132:133], off
	s_nop 0
	global_load_dwordx4 v[130:133], v[130:131], off offset:256
	v_lshlrev_b64 v[164:165], 11, v[164:165]
	global_load_dwordx4 v[134:137], v[134:135], off
	s_waitcnt vmcnt(6)
; __device__ __forceinline__ float bf_lo(unsigned w) { return __uint_as_float(w << 16); }
; __device__ __forceinline__ float bf_hi(unsigned w) { return __uint_as_float(w & 0xffff0000u); }
; __device__ __forceinline__ float sigm(float v) { return __builtin_amdgcn_rcpf(1.0f + __builtin_amdgcn_exp2f(-1.44269504089f * v)); }
; __device__ __forceinline__ u32x4 pack8(const f32x4& v0, const f32x4& v1) { u32x4 w; w.x = cvt_pk_bf16(v0[0], v0[1]); w.y = cvt_pk_bf16(v0[2], v0[3]); w.z = cvt_pk_bf16(v1[0], v1[1]); w.w = cvt_pk_bf16(v1[2], v1[3]); return w; }
; __device__ __forceinline__ float sumsq8(const f32x4& v0, const f32x4& v1) { return (v0[0] * v0[0] + v0[1] * v0[1]) + (v0[2] * v0[2] + v0[3] * v0[3]) + (v1[0] * v1[0] + v1[1] * v1[1]) + (v1[2] * v1[2] + v1[3] * v1[3]); }
; __device__ __forceinline__ void epi_run(const Epi& E, f32x4 (&acc)[2][2][4][2], const Unit& u, int wr, int wc, int fr, int fq) {
;     ...
;                 for (int mm = 0; mm < 2; ++mm) { const int m = 2 * mh + mm, row = row0 + ai * 128 + m * 16; float sq = 0.f;
; #pragma unroll
;                     for (int bj = 0; bj < 2; ++bj) { const u32x4 xx = x[mm][bj], cc = c[mm][bj];
;                         const f32x4 c0 = (f32x4){bf_lo(cc.x), bf_hi(cc.x), bf_lo(cc.y), bf_hi(cc.y)}, c1 = (f32x4){bf_lo(cc.z), bf_hi(cc.z), bf_lo(cc.w), bf_hi(cc.w)};
;                         f32x4 v0 = acc[ai][bj][m][0] * rs[ai][m], v1 = acc[ai][bj][m][1] * rs[ai][m];
; #pragma unroll
;                         for (int e = 0; e < 4; ++e) { v0[e] = sigm(v0[e]) * c0[e]; v1[e] = sigm(v1[e]) * c1[e]; }
;                         const f32x4 x0 = (f32x4){bf_lo(xx.x), bf_hi(xx.x), bf_lo(xx.y), bf_hi(xx.y)} + v0, x1 = (f32x4){bf_lo(xx.z), bf_hi(xx.z), bf_lo(xx.w), bf_hi(xx.w)} + v1;
;                         sq += sumsq8(x0, x1); *(u32x4*)(E.xout16 + (size_t)row * D + col0 + bj * 128) = pack8(x0, x1); }
;                     sq += __shfl_xor(sq, 16); sq += __shfl_xor(sq, 32); if (fq == 0) sslot[row] = sq; }
	v_lshlrev_b32_e32 v188, 16, v158
	v_and_b32_e32 v189, 0xffff0000, v158
	v_mul_f32_e32 v158, 0xbfb8aa3b, v187
	v_exp_f32_e32 v158, v158
	v_lshlrev_b32_e32 v186, 16, v160
	v_and_b32_e32 v187, 0xffff0000, v160
	v_mul_f32_e32 v160, 0xbfb8aa3b, v183
	v_add_f32_e32 v158, 1.0, v158
	v_rcp_f32_e32 v167, v158
	v_mul_f32_e32 v158, 0xbfb8aa3b, v182
	v_exp_f32_e32 v158, v158
	v_exp_f32_e32 v160, v160
	v_lshlrev_b32_e32 v190, 16, v159
	v_and_b32_e32 v191, 0xffff0000, v159
	v_add_f32_e32 v158, 1.0, v158
	v_rcp_f32_e32 v182, v158
	v_mul_f32_e32 v158, 0xbfb8aa3b, v184
	v_mul_f32_e32 v159, 0xbfb8aa3b, v185
	v_exp_f32_e32 v158, v158
	v_exp_f32_e32 v159, v159
	v_add_f32_e32 v160, 1.0, v160
	v_rcp_f32_e32 v183, v160
	v_add_f32_e32 v158, 1.0, v158
	v_add_f32_e32 v159, 1.0, v159
	v_rcp_f32_e32 v158, v158
	v_rcp_f32_e32 v159, v159
	v_lshlrev_b32_e32 v184, 16, v154
	v_and_b32_e32 v185, 0xffff0000, v154
	v_lshlrev_b32_e32 v154, 16, v155
	v_and_b32_e32 v155, 0xffff0000, v155
	v_lshlrev_b32_e32 v160, 16, v161
	v_and_b32_e32 v161, 0xffff0000, v161
	v_pk_fma_f32 v[154:155], v[182:183], v[190:191], v[154:155]
	v_pk_fma_f32 v[168:169], v[168:169], v[188:189], v[184:185]
	v_lshlrev_b32_e32 v182, 16, v156
	v_and_b32_e32 v183, 0xffff0000, v156
	v_lshlrev_b32_e32 v156, 16, v157
	v_and_b32_e32 v157, 0xffff0000, v157
	v_pk_fma_f32 v[160:161], v[158:159], v[160:161], v[156:157]
	v_mul_f32_e32 v156, v169, v169
	v_mul_f32_e32 v157, v155, v155
	v_pk_fma_f32 v[158:159], v[166:167], v[186:187], v[182:183]
	v_fmac_f32_e32 v156, v168, v168
	v_fmac_f32_e32 v157, v154, v154
	v_add_f32_e32 v156, v156, v157
	v_mul_f32_e32 v157, v159, v159
	v_fmac_f32_e32 v157, v158, v158
	v_add_f32_e32 v156, v157, v156
	v_mul_f32_e32 v157, v161, v161
	v_fmac_f32_e32 v157, v160, v160
	v_add_f32_e32 v184, v157, v156
	v_cvt_pk_bf16_f32 v157, v154, v155
	v_lshl_add_u64 v[154:155], s[78:79], 0, v[164:165]
	v_cvt_pk_bf16_f32 v156, v168, v169
	v_cvt_pk_bf16_f32 v158, v158, v159
	v_cvt_pk_bf16_f32 v159, v160, v161
	v_lshl_add_u64 v[154:155], v[212:213], 1, v[154:155]
	s_waitcnt lgkmcnt(0)
	global_store_dwordx4 v[228:229], v[222:225], off offset:256
	v_lshl_add_u64 v[226:227], v[154:155], 0, v[230:231]
	ds_bpermute_b32 v218, v243, v156
	ds_bpermute_b32 v219, v243, v157
	ds_bpermute_b32 v220, v243, v158
	ds_bpermute_b32 v221, v243, v159
	v_pk_mul_f32 v[160:161], v[80:81], v[0:1] op_sel_hi:[1,0]
	v_pk_mul_f32 v[164:165], v[78:79], v[0:1] op_sel_hi:[1,0]
	v_pk_mul_f32 v[158:159], v[86:87], v[0:1] op_sel_hi:[1,0]
	v_pk_mul_f32 v[156:157], v[88:89], v[0:1] op_sel_hi:[1,0]
	v_mul_f32_e32 v0, 0xbfb8aa3b, v158
	v_exp_f32_e32 v0, v0
	s_waitcnt vmcnt(5)
	v_lshlrev_b32_e32 v166, 16, v150
	v_and_b32_e32 v167, 0xffff0000, v150
	v_lshlrev_b32_e32 v182, 16, v151
	v_add_f32_e32 v0, 1.0, v0
	v_rcp_f32_e32 v158, v0
	v_mul_f32_e32 v0, 0xbfb8aa3b, v164
	v_exp_f32_e32 v0, v0
	v_and_b32_e32 v183, 0xffff0000, v151
	v_lshlrev_b32_e32 v168, 16, v152
	v_and_b32_e32 v169, 0xffff0000, v152
	v_add_f32_e32 v0, 1.0, v0
	v_rcp_f32_e32 v164, v0
	v_mul_f32_e32 v0, 0xbfb8aa3b, v159
	v_exp_f32_e32 v0, v0
	v_lshlrev_b32_e32 v152, 16, v153
	v_and_b32_e32 v153, 0xffff0000, v153
	v_add_f32_e32 v0, 1.0, v0
	v_rcp_f32_e32 v159, v0
	v_mul_f32_e32 v0, 0xbfb8aa3b, v165
	v_exp_f32_e32 v0, v0
	s_nop 0
	v_add_f32_e32 v0, 1.0, v0
	v_rcp_f32_e32 v165, v0
	v_mul_f32_e32 v0, 0xbfb8aa3b, v156
	v_exp_f32_e32 v0, v0
	s_nop 0
	v_add_f32_e32 v0, 1.0, v0
	v_rcp_f32_e32 v156, v0
	v_mul_f32_e32 v0, 0xbfb8aa3b, v160
	v_exp_f32_e32 v0, v0
	v_lshlrev_b32_e32 v160, 16, v146
	v_add_f32_e32 v0, 1.0, v0
	v_rcp_f32_e32 v150, v0
	v_mul_f32_e32 v0, 0xbfb8aa3b, v157
	v_exp_f32_e32 v0, v0
	s_nop 0
	v_add_f32_e32 v0, 1.0, v0
	v_rcp_f32_e32 v157, v0
	v_mul_f32_e32 v0, 0xbfb8aa3b, v161
	v_exp_f32_e32 v0, v0
	v_and_b32_e32 v161, 0xffff0000, v146
	v_lshlrev_b32_e32 v146, 16, v147
	v_and_b32_e32 v147, 0xffff0000, v147
	v_add_f32_e32 v0, 1.0, v0
	v_rcp_f32_e32 v151, v0
	v_pk_fma_f32 v[156:157], v[156:157], v[182:183], v[146:147]
	v_pk_fma_f32 v[146:147], v[158:159], v[166:167], v[160:161]
	v_lshlrev_b32_e32 v158, 16, v148
	v_and_b32_e32 v159, 0xffff0000, v148
	v_lshlrev_b32_e32 v148, 16, v149
	v_and_b32_e32 v149, 0xffff0000, v149
	v_pk_fma_f32 v[150:151], v[150:151], v[152:153], v[148:149]
	v_mul_f32_e32 v0, v147, v147
	v_mul_f32_e32 v152, v157, v157
	v_pk_fma_f32 v[148:149], v[164:165], v[168:169], v[158:159]
	v_fmac_f32_e32 v0, v146, v146
	v_fmac_f32_e32 v152, v156, v156
	v_add_f32_e32 v0, v0, v152
	v_mul_f32_e32 v152, v149, v149
	v_fmac_f32_e32 v152, v148, v148
	v_add_f32_e32 v0, v152, v0
	v_mul_f32_e32 v152, v151, v151
	v_fmac_f32_e32 v152, v150, v150
	v_add_f32_e32 v0, v152, v0
	v_add_f32_e32 v0, v184, v0
	v_cvt_pk_bf16_f32 v146, v146, v147
	v_cvt_pk_bf16_f32 v147, v156, v157
	v_cvt_pk_bf16_f32 v148, v148, v149
	v_cvt_pk_bf16_f32 v149, v150, v151
	s_waitcnt lgkmcnt(0)
	global_store_dwordx4 v[226:227], v[218:221], off
	v_lshl_add_u64 v[228:229], v[154:155], 0, v[230:231]
	ds_bpermute_b32 v222, v243, v146
	ds_bpermute_b32 v223, v243, v147
	ds_bpermute_b32 v224, v243, v148
	ds_bpermute_b32 v225, v243, v149
	ds_bpermute_b32 v146, v171, v0
	s_waitcnt lgkmcnt(0)
	v_add_f32_e32 v0, v0, v146
	ds_bpermute_b32 v146, v170, v0
	s_and_saveexec_b64 s[8:9], s[40:41]
	s_cbranch_execz .LBB0_315
	v_lshl_add_u64 v[148:149], v[210:211], 2, s[44:45]
	s_waitcnt lgkmcnt(0)
	v_add_f32_e32 v0, v0, v146
	global_store_dword v[148:149], v0, off offset:128
; __device__ __forceinline__ float bf_lo(unsigned w) { return __uint_as_float(w << 16); }
; __device__ __forceinline__ float bf_hi(unsigned w) { return __uint_as_float(w & 0xffff0000u); }
; __device__ __forceinline__ float sigm(float v) { return __builtin_amdgcn_rcpf(1.0f + __builtin_amdgcn_exp2f(-1.44269504089f * v)); }
; __device__ __forceinline__ u32x4 pack8(const f32x4& v0, const f32x4& v1) { u32x4 w; w.x = cvt_pk_bf16(v0[0], v0[1]); w.y = cvt_pk_bf16(v0[2], v0[3]); w.z = cvt_pk_bf16(v1[0], v1[1]); w.w = cvt_pk_bf16(v1[2], v1[3]); return w; }
; __device__ __forceinline__ float sumsq8(const f32x4& v0, const f32x4& v1) { return (v0[0] * v0[0] + v0[1] * v0[1]) + (v0[2] * v0[2] + v0[3] * v0[3]) + (v1[0] * v1[0] + v1[1] * v1[1]) + (v1[2] * v1[2] + v1[3] * v1[3]); }
; __device__ __forceinline__ void epi_run(const Epi& E, f32x4 (&acc)[2][2][4][2], const Unit& u, int wr, int wc, int fr, int fq) {
;     ...
;                 for (int mm = 0; mm < 2; ++mm) { const int m = 2 * mh + mm, row = row0 + ai * 128 + m * 16; float sq = 0.f;
; #pragma unroll
;                     for (int bj = 0; bj < 2; ++bj) { const u32x4 xx = x[mm][bj], cc = c[mm][bj];
;                         const f32x4 c0 = (f32x4){bf_lo(cc.x), bf_hi(cc.x), bf_lo(cc.y), bf_hi(cc.y)}, c1 = (f32x4){bf_lo(cc.z), bf_hi(cc.z), bf_lo(cc.w), bf_hi(cc.w)};
;                         f32x4 v0 = acc[ai][bj][m][0] * rs[ai][m], v1 = acc[ai][bj][m][1] * rs[ai][m];
; #pragma unroll
;                         for (int e = 0; e < 4; ++e) { v0[e] = sigm(v0[e]) * c0[e]; v1[e] = sigm(v1[e]) * c1[e]; }
;                         const f32x4 x0 = (f32x4){bf_lo(xx.x), bf_hi(xx.x), bf_lo(xx.y), bf_hi(xx.y)} + v0, x1 = (f32x4){bf_lo(xx.z), bf_hi(xx.z), bf_lo(xx.w), bf_hi(xx.w)} + v1;
;                         sq += sumsq8(x0, x1); *(u32x4*)(E.xout16 + (size_t)row * D + col0 + bj * 128) = pack8(x0, x1); }
;                     sq += __shfl_xor(sq, 16); sq += __shfl_xor(sq, 32); if (fq == 0) sslot[row] = sq; }
.LBB0_315:
	s_or_b64 exec, exec, s[8:9]
	v_add_f32_e32 v0, v180, v181
	v_fmamk_f32 v0, v0, 0x3a800000, v197
	v_rsq_f32_e32 v0, v0
	s_waitcnt vmcnt(4)
	v_lshlrev_b32_e32 v156, 16, v142
	v_and_b32_e32 v157, 0xffff0000, v142
	v_lshlrev_b32_e32 v158, 16, v144
	v_pk_mul_f32 v[154:155], v[74:75], v[0:1] op_sel_hi:[1,0]
	v_pk_mul_f32 v[148:149], v[84:85], v[0:1] op_sel_hi:[1,0]
	v_mul_f32_e32 v155, 0xbfb8aa3b, v155
	v_exp_f32_e32 v155, v155
	v_mul_f32_e32 v148, 0xbfb8aa3b, v148
	v_exp_f32_e32 v148, v148
	v_pk_mul_f32 v[152:153], v[76:77], v[0:1] op_sel_hi:[1,0]
	v_add_f32_e32 v142, 1.0, v155
	v_rcp_f32_e32 v155, v142
	v_and_b32_e32 v159, 0xffff0000, v144
	v_add_f32_e32 v142, 1.0, v148
	v_mul_f32_e32 v144, 0xbfb8aa3b, v152
	v_mul_f32_e32 v148, 0xbfb8aa3b, v149
	v_exp_f32_e32 v144, v144
	v_exp_f32_e32 v149, v148
	v_pk_mul_f32 v[150:151], v[82:83], v[0:1] op_sel_hi:[1,0]
	v_rcp_f32_e32 v148, v142
	v_mul_f32_e32 v150, 0xbfb8aa3b, v150
	v_mul_f32_e32 v151, 0xbfb8aa3b, v151
	v_exp_f32_e32 v150, v150
	v_exp_f32_e32 v151, v151
	v_add_f32_e32 v142, 1.0, v144
	v_add_f32_e32 v144, 1.0, v149
	v_mul_f32_e32 v149, 0xbfb8aa3b, v153
	v_mul_f32_e32 v154, 0xbfb8aa3b, v154
	v_exp_f32_e32 v160, v149
	v_exp_f32_e32 v154, v154
	v_add_f32_e32 v150, 1.0, v150
	v_add_f32_e32 v151, 1.0, v151
	v_rcp_f32_e32 v150, v150
	v_rcp_f32_e32 v151, v151
	v_rcp_f32_e32 v149, v144
	v_lshlrev_b32_e32 v152, 16, v143
	v_and_b32_e32 v153, 0xffff0000, v143
	v_add_f32_e32 v143, 1.0, v160
	v_add_f32_e32 v154, 1.0, v154
	v_rcp_f32_e32 v142, v142
	v_rcp_f32_e32 v143, v143
	v_rcp_f32_e32 v154, v154
	v_lshlrev_b32_e32 v160, 16, v138
	v_and_b32_e32 v161, 0xffff0000, v138
	v_lshlrev_b32_e32 v138, 16, v139
	v_and_b32_e32 v139, 0xffff0000, v139
	v_lshlrev_b32_e32 v144, 16, v145
	v_and_b32_e32 v145, 0xffff0000, v145
	v_pk_fma_f32 v[148:149], v[148:149], v[152:153], v[138:139]
	v_pk_fma_f32 v[138:139], v[150:151], v[156:157], v[160:161]
	v_lshlrev_b32_e32 v150, 16, v140
	v_and_b32_e32 v151, 0xffff0000, v140
	v_lshlrev_b32_e32 v140, 16, v141
	v_and_b32_e32 v141, 0xffff0000, v141
	v_pk_fma_f32 v[142:143], v[142:143], v[144:145], v[140:141]
	v_mul_f32_e32 v144, v139, v139
	v_mul_f32_e32 v145, v149, v149
	v_pk_fma_f32 v[140:141], v[154:155], v[158:159], v[150:151]
	v_fmac_f32_e32 v144, v138, v138
	v_fmac_f32_e32 v145, v148, v148
	v_add_f32_e32 v144, v144, v145
	v_mul_f32_e32 v145, v141, v141
	v_fmac_f32_e32 v145, v140, v140
	v_add_f32_e32 v144, v145, v144
	v_mul_f32_e32 v145, v143, v143
	v_fmac_f32_e32 v145, v142, v142
	v_cvt_pk_bf16_f32 v140, v140, v141
	v_cvt_pk_bf16_f32 v141, v142, v143
	v_pk_mul_f32 v[142:143], v[70:71], v[0:1] op_sel_hi:[1,0]
	v_pk_mul_f32 v[150:151], v[66:67], v[0:1] op_sel_hi:[1,0]
	v_mul_f32_e32 v142, 0xbfb8aa3b, v142
	v_exp_f32_e32 v142, v142
	v_add_f32_e32 v158, v145, v144
	v_cvt_pk_bf16_f32 v138, v138, v139
	v_cvt_pk_bf16_f32 v139, v148, v149
	v_pk_mul_f32 v[144:145], v[72:73], v[0:1] op_sel_hi:[1,0]
	v_pk_mul_f32 v[148:149], v[68:69], v[0:1] op_sel_hi:[1,0]
	v_add_f32_e32 v0, 1.0, v142
	v_mul_f32_e32 v142, 0xbfb8aa3b, v150
	v_exp_f32_e32 v150, v142
	v_mul_f32_e32 v142, 0xbfb8aa3b, v143
	v_exp_f32_e32 v143, v142
	v_rcp_f32_e32 v142, v0
	v_add_f32_e32 v0, 1.0, v150
	v_rcp_f32_e32 v150, v0
	v_add_f32_e32 v0, 1.0, v143
	v_mul_f32_e32 v143, 0xbfb8aa3b, v151
	v_exp_f32_e32 v151, v143
	s_waitcnt vmcnt(2)
	v_lshlrev_b32_e32 v152, 16, v134
	v_and_b32_e32 v153, 0xffff0000, v134
	v_mul_f32_e32 v134, 0xbfb8aa3b, v144
	v_exp_f32_e32 v134, v134
	v_rcp_f32_e32 v143, v0
	v_add_f32_e32 v0, 1.0, v151
	v_rcp_f32_e32 v151, v0
	v_add_f32_e32 v0, 1.0, v134
	v_mul_f32_e32 v134, 0xbfb8aa3b, v148
	v_lshlrev_b32_e32 v154, 16, v136
	v_and_b32_e32 v155, 0xffff0000, v136
	v_exp_f32_e32 v134, v134
	v_mul_f32_e32 v136, 0xbfb8aa3b, v145
	v_exp_f32_e32 v136, v136
	v_rcp_f32_e32 v144, v0
	v_add_f32_e32 v0, 1.0, v134
	v_rcp_f32_e32 v134, v0
	v_add_f32_e32 v0, 1.0, v136
	v_mul_f32_e32 v136, 0xbfb8aa3b, v149
	v_exp_f32_e32 v136, v136
	v_rcp_f32_e32 v145, v0
	v_lshlrev_b32_e32 v148, 16, v135
	v_and_b32_e32 v149, 0xffff0000, v135
	v_add_f32_e32 v0, 1.0, v136
	v_rcp_f32_e32 v135, v0
	v_lshlrev_b32_e32 v156, 16, v130
	v_and_b32_e32 v157, 0xffff0000, v130
	v_lshlrev_b32_e32 v130, 16, v131
	v_and_b32_e32 v131, 0xffff0000, v131
	v_lshlrev_b32_e32 v136, 16, v137
	v_and_b32_e32 v137, 0xffff0000, v137
	v_pk_fma_f32 v[144:145], v[144:145], v[148:149], v[130:131]
	v_pk_fma_f32 v[130:131], v[142:143], v[152:153], v[156:157]
	v_lshlrev_b32_e32 v142, 16, v132
	v_and_b32_e32 v143, 0xffff0000, v132
	v_lshlrev_b32_e32 v132, 16, v133
	v_and_b32_e32 v133, 0xffff0000, v133
	v_pk_fma_f32 v[136:137], v[134:135], v[136:137], v[132:133]
	v_mul_f32_e32 v0, v131, v131
	v_mul_f32_e32 v132, v145, v145
	v_pk_fma_f32 v[134:135], v[150:151], v[154:155], v[142:143]
	v_fmac_f32_e32 v0, v130, v130
	v_fmac_f32_e32 v132, v144, v144
	v_add_f32_e32 v0, v0, v132
	v_mul_f32_e32 v132, v135, v135
	v_fmac_f32_e32 v132, v134, v134
	v_add_f32_e32 v0, v132, v0
	v_mul_f32_e32 v132, v137, v137
	v_fmac_f32_e32 v132, v136, v136
	v_add_f32_e32 v0, v132, v0
	v_add_f32_e32 v0, v158, v0
	ds_bpermute_b32 v148, v171, v0
	s_waitcnt lgkmcnt(1)
	v_lshlrev_b64 v[146:147], 11, v[162:163]
	v_lshl_add_u64 v[132:133], s[78:79], 0, v[146:147]
	v_lshl_add_u64 v[142:143], v[212:213], 1, v[132:133]
	v_cvt_pk_bf16_f32 v132, v130, v131
	s_waitcnt lgkmcnt(0)
	v_add_f32_e32 v0, v0, v148
	ds_bpermute_b32 v130, v170, v0
	v_cvt_pk_bf16_f32 v133, v144, v145
	v_cvt_pk_bf16_f32 v134, v134, v135
	v_cvt_pk_bf16_f32 v135, v136, v137
	s_waitcnt lgkmcnt(0)
	global_store_dwordx4 v[228:229], v[222:225], off offset:256
	v_lshl_add_u64 v[226:227], v[142:143], 0, v[230:231]
	ds_bpermute_b32 v218, v243, v138
	ds_bpermute_b32 v219, v243, v139
	ds_bpermute_b32 v220, v243, v140
	ds_bpermute_b32 v221, v243, v141
	s_waitcnt lgkmcnt(0)
	global_store_dwordx4 v[226:227], v[218:221], off
	v_lshl_add_u64 v[228:229], v[142:143], 0, v[230:231]
	ds_bpermute_b32 v222, v243, v132
	ds_bpermute_b32 v223, v243, v133
	ds_bpermute_b32 v224, v243, v134
	ds_bpermute_b32 v225, v243, v135
	s_and_saveexec_b64 s[8:9], s[40:41]
	s_cbranch_execz .LBB0_317
	v_lshl_add_u64 v[132:133], v[210:211], 2, s[44:45]
	s_waitcnt lgkmcnt(0)
	v_add_f32_e32 v0, v0, v130
	global_store_dword v[132:133], v0, off offset:192
; __device__ __forceinline__ float bf_lo(unsigned w) { return __uint_as_float(w << 16); }
; __device__ __forceinline__ float bf_hi(unsigned w) { return __uint_as_float(w & 0xffff0000u); }
; __device__ __forceinline__ float sigm(float v) { return __builtin_amdgcn_rcpf(1.0f + __builtin_amdgcn_exp2f(-1.44269504089f * v)); }
; __device__ __forceinline__ u32x4 pack8(const f32x4& v0, const f32x4& v1) { u32x4 w; w.x = cvt_pk_bf16(v0[0], v0[1]); w.y = cvt_pk_bf16(v0[2], v0[3]); w.z = cvt_pk_bf16(v1[0], v1[1]); w.w = cvt_pk_bf16(v1[2], v1[3]); return w; }
; __device__ __forceinline__ float sumsq8(const f32x4& v0, const f32x4& v1) { return (v0[0] * v0[0] + v0[1] * v0[1]) + (v0[2] * v0[2] + v0[3] * v0[3]) + (v1[0] * v1[0] + v1[1] * v1[1]) + (v1[2] * v1[2] + v1[3] * v1[3]); }
; __device__ __forceinline__ void epi_run(const Epi& E, f32x4 (&acc)[2][2][4][2], const Unit& u, int wr, int wc, int fr, int fq) {
;     ...
;             for (int mh = 0; mh < 2; ++mh) { u32x4 x[2][2], c[2][2];
; #pragma unroll
;                 for (int mm = 0; mm < 2; ++mm)
; #pragma unroll
;                     for (int bj = 0; bj < 2; ++bj) { const size_t off = (size_t)(row0 + ai * 128 + (2 * mh + mm) * 16) * D + col0 + bj * 128; x[mm][bj] = *(const u32x4*)(E.xin16 + off); c[mm][bj] = *(const u32x4*)(E.C16 + off); }
; #pragma unroll
;                 for (int mm = 0; mm < 2; ++mm) { const int m = 2 * mh + mm, row = row0 + ai * 128 + m * 16; float sq = 0.f;
; #pragma unroll
;                     for (int bj = 0; bj < 2; ++bj) { const u32x4 xx = x[mm][bj], cc = c[mm][bj];
;                         const f32x4 c0 = (f32x4){bf_lo(cc.x), bf_hi(cc.x), bf_lo(cc.y), bf_hi(cc.y)}, c1 = (f32x4){bf_lo(cc.z), bf_hi(cc.z), bf_lo(cc.w), bf_hi(cc.w)};
;                         f32x4 v0 = acc[ai][bj][m][0] * rs[ai][m], v1 = acc[ai][bj][m][1] * rs[ai][m];
; #pragma unroll
;                         for (int e = 0; e < 4; ++e) { v0[e] = sigm(v0[e]) * c0[e]; v1[e] = sigm(v1[e]) * c1[e]; }
;                         const f32x4 x0 = (f32x4){bf_lo(xx.x), bf_hi(xx.x), bf_lo(xx.y), bf_hi(xx.y)} + v0, x1 = (f32x4){bf_lo(xx.z), bf_hi(xx.z), bf_lo(xx.w), bf_hi(xx.w)} + v1;
;                         sq += sumsq8(x0, x1); *(u32x4*)(E.xout16 + (size_t)row * D + col0 + bj * 128) = pack8(x0, x1); }
;                     sq += __shfl_xor(sq, 16); sq += __shfl_xor(sq, 32); if (fq == 0) sslot[row] = sq; }
.LBB0_317:
	s_or_b64 exec, exec, s[8:9]
	v_add_u32_e32 v164, 0x80, v210
	v_ashrrev_i32_e32 v165, 31, v164
	s_waitcnt lgkmcnt(0)
	v_lshlrev_b64 v[130:131], 10, v[164:165]
	v_lshl_add_u64 v[130:131], v[130:131], 0, v[212:213]
	v_lshlrev_b64 v[130:131], 1, v[130:131]
	v_lshl_add_u64 v[132:133], s[48:49], 0, v[130:131]
	v_lshl_add_u64 v[134:135], s[62:63], 0, v[130:131]
	global_load_dwordx4 v[154:157], v[132:133], off
	global_load_dwordx4 v[158:161], v[134:135], off
	global_load_dwordx4 v[146:149], v[132:133], off offset:256
	v_or_b32_e32 v130, 0x100, v130
	v_lshl_add_u64 v[130:131], s[62:63], 0, v[130:131]
	global_load_dwordx4 v[150:153], v[130:131], off
	v_add_f32_e32 v0, v178, v179
	v_fmamk_f32 v0, v0, 0x3a800000, v197
	v_rsq_f32_e32 v0, v0
	v_add_u32_e32 v162, 0x90, v210
	v_ashrrev_i32_e32 v163, 31, v162
	v_lshlrev_b64 v[130:131], 10, v[162:163]
	v_pk_mul_f32 v[166:167], v[62:63], v[0:1] op_sel_hi:[1,0]
	v_pk_mul_f32 v[182:183], v[58:59], v[0:1] op_sel_hi:[1,0]
	v_mul_f32_e32 v167, 0xbfb8aa3b, v167
	v_exp_f32_e32 v167, v167
	v_pk_mul_f32 v[178:179], v[64:65], v[0:1] op_sel_hi:[1,0]
	v_mul_f32_e32 v166, 0xbfb8aa3b, v166
	v_exp_f32_e32 v166, v166
	v_add_f32_e32 v167, 1.0, v167
	v_rcp_f32_e32 v169, v167
	v_pk_mul_f32 v[180:181], v[60:61], v[0:1] op_sel_hi:[1,0]
	v_add_f32_e32 v166, 1.0, v166
	v_rcp_f32_e32 v168, v166
	v_mul_f32_e32 v166, 0xbfb8aa3b, v182
	v_exp_f32_e32 v166, v166
	v_lshl_add_u64 v[130:131], v[130:131], 0, v[212:213]
	v_lshlrev_b64 v[134:135], 1, v[130:131]
	v_lshl_add_u64 v[130:131], s[48:49], 0, v[134:135]
	v_add_f32_e32 v166, 1.0, v166
	v_rcp_f32_e32 v166, v166
	v_lshl_add_u64 v[132:133], s[62:63], 0, v[134:135]
	v_or_b32_e32 v134, 0x100, v134
	v_lshl_add_u64 v[134:135], s[62:63], 0, v[134:135]
	global_load_dwordx4 v[138:141], v[130:131], off
	global_load_dwordx4 v[142:145], v[132:133], off
	s_nop 0
	global_load_dwordx4 v[130:133], v[130:131], off offset:256
	v_lshlrev_b64 v[164:165], 11, v[164:165]
	global_load_dwordx4 v[134:137], v[134:135], off
	s_waitcnt vmcnt(6)
	v_lshlrev_b32_e32 v184, 16, v158
	v_and_b32_e32 v185, 0xffff0000, v158
	v_mul_f32_e32 v158, 0xbfb8aa3b, v183
	v_exp_f32_e32 v158, v158
	v_lshlrev_b32_e32 v182, 16, v160
	v_and_b32_e32 v183, 0xffff0000, v160
	v_mul_f32_e32 v160, 0xbfb8aa3b, v179
	v_add_f32_e32 v158, 1.0, v158
	v_rcp_f32_e32 v167, v158
	v_mul_f32_e32 v158, 0xbfb8aa3b, v178
	v_exp_f32_e32 v158, v158
	v_exp_f32_e32 v160, v160
	v_lshlrev_b32_e32 v186, 16, v159
	v_and_b32_e32 v187, 0xffff0000, v159
	v_add_f32_e32 v158, 1.0, v158
	v_rcp_f32_e32 v178, v158
	v_mul_f32_e32 v158, 0xbfb8aa3b, v180
	v_mul_f32_e32 v159, 0xbfb8aa3b, v181
	v_exp_f32_e32 v158, v158
	v_exp_f32_e32 v159, v159
	v_add_f32_e32 v160, 1.0, v160
	v_rcp_f32_e32 v179, v160
	v_add_f32_e32 v158, 1.0, v158
	v_add_f32_e32 v159, 1.0, v159
	v_rcp_f32_e32 v158, v158
	v_rcp_f32_e32 v159, v159
	v_lshlrev_b32_e32 v180, 16, v154
	v_and_b32_e32 v181, 0xffff0000, v154
	v_lshlrev_b32_e32 v154, 16, v155
	v_and_b32_e32 v155, 0xffff0000, v155
	v_lshlrev_b32_e32 v160, 16, v161
	v_and_b32_e32 v161, 0xffff0000, v161
	v_pk_fma_f32 v[154:155], v[178:179], v[186:187], v[154:155]
	v_pk_fma_f32 v[168:169], v[168:169], v[184:185], v[180:181]
	v_lshlrev_b32_e32 v178, 16, v156
	v_and_b32_e32 v179, 0xffff0000, v156
	v_lshlrev_b32_e32 v156, 16, v157
	v_and_b32_e32 v157, 0xffff0000, v157
	v_pk_fma_f32 v[160:161], v[158:159], v[160:161], v[156:157]
	v_mul_f32_e32 v156, v169, v169
	v_mul_f32_e32 v157, v155, v155
	v_pk_fma_f32 v[158:159], v[166:167], v[182:183], v[178:179]
	v_fmac_f32_e32 v156, v168, v168
	v_fmac_f32_e32 v157, v154, v154
	v_add_f32_e32 v156, v156, v157
	v_mul_f32_e32 v157, v159, v159
	v_fmac_f32_e32 v157, v158, v158
	v_add_f32_e32 v156, v157, v156
	v_mul_f32_e32 v157, v161, v161
	v_fmac_f32_e32 v157, v160, v160
	v_add_f32_e32 v180, v157, v156
	v_cvt_pk_bf16_f32 v157, v154, v155
	v_lshl_add_u64 v[154:155], s[78:79], 0, v[164:165]
	v_cvt_pk_bf16_f32 v156, v168, v169
	v_cvt_pk_bf16_f32 v158, v158, v159
	v_cvt_pk_bf16_f32 v159, v160, v161
	v_lshl_add_u64 v[154:155], v[212:213], 1, v[154:155]
	s_waitcnt lgkmcnt(0)
	global_store_dwordx4 v[228:229], v[222:225], off offset:256
	v_lshl_add_u64 v[226:227], v[154:155], 0, v[230:231]
	ds_bpermute_b32 v218, v243, v156
	ds_bpermute_b32 v219, v243, v157
	ds_bpermute_b32 v220, v243, v158
	ds_bpermute_b32 v221, v243, v159
	v_pk_mul_f32 v[160:161], v[52:53], v[0:1] op_sel_hi:[1,0]
	v_pk_mul_f32 v[164:165], v[50:51], v[0:1] op_sel_hi:[1,0]
	v_pk_mul_f32 v[158:159], v[54:55], v[0:1] op_sel_hi:[1,0]
	v_pk_mul_f32 v[156:157], v[56:57], v[0:1] op_sel_hi:[1,0]
	v_mul_f32_e32 v0, 0xbfb8aa3b, v158
	v_exp_f32_e32 v0, v0
	s_waitcnt vmcnt(5)
; __device__ __forceinline__ float bf_lo(unsigned w) { return __uint_as_float(w << 16); }
; __device__ __forceinline__ float bf_hi(unsigned w) { return __uint_as_float(w & 0xffff0000u); }
; __device__ __forceinline__ float sigm(float v) { return __builtin_amdgcn_rcpf(1.0f + __builtin_amdgcn_exp2f(-1.44269504089f * v)); }
; __device__ __forceinline__ u32x4 pack8(const f32x4& v0, const f32x4& v1) { u32x4 w; w.x = cvt_pk_bf16(v0[0], v0[1]); w.y = cvt_pk_bf16(v0[2], v0[3]); w.z = cvt_pk_bf16(v1[0], v1[1]); w.w = cvt_pk_bf16(v1[2], v1[3]); return w; }
; __device__ __forceinline__ float sumsq8(const f32x4& v0, const f32x4& v1) { return (v0[0] * v0[0] + v0[1] * v0[1]) + (v0[2] * v0[2] + v0[3] * v0[3]) + (v1[0] * v1[0] + v1[1] * v1[1]) + (v1[2] * v1[2] + v1[3] * v1[3]); }
; __device__ __forceinline__ void epi_run(const Epi& E, f32x4 (&acc)[2][2][4][2], const Unit& u, int wr, int wc, int fr, int fq) {
;     ...
;                 for (int mm = 0; mm < 2; ++mm) { const int m = 2 * mh + mm, row = row0 + ai * 128 + m * 16; float sq = 0.f;
; #pragma unroll
;                     for (int bj = 0; bj < 2; ++bj) { const u32x4 xx = x[mm][bj], cc = c[mm][bj];
;                         const f32x4 c0 = (f32x4){bf_lo(cc.x), bf_hi(cc.x), bf_lo(cc.y), bf_hi(cc.y)}, c1 = (f32x4){bf_lo(cc.z), bf_hi(cc.z), bf_lo(cc.w), bf_hi(cc.w)};
;                         f32x4 v0 = acc[ai][bj][m][0] * rs[ai][m], v1 = acc[ai][bj][m][1] * rs[ai][m];
; #pragma unroll
;                         for (int e = 0; e < 4; ++e) { v0[e] = sigm(v0[e]) * c0[e]; v1[e] = sigm(v1[e]) * c1[e]; }
;                         const f32x4 x0 = (f32x4){bf_lo(xx.x), bf_hi(xx.x), bf_lo(xx.y), bf_hi(xx.y)} + v0, x1 = (f32x4){bf_lo(xx.z), bf_hi(xx.z), bf_lo(xx.w), bf_hi(xx.w)} + v1;
;                         sq += sumsq8(x0, x1); *(u32x4*)(E.xout16 + (size_t)row * D + col0 + bj * 128) = pack8(x0, x1); }
;                     sq += __shfl_xor(sq, 16); sq += __shfl_xor(sq, 32); if (fq == 0) sslot[row] = sq; }
	v_lshlrev_b32_e32 v166, 16, v150
	v_and_b32_e32 v167, 0xffff0000, v150
	v_lshlrev_b32_e32 v178, 16, v151
	v_add_f32_e32 v0, 1.0, v0
	v_rcp_f32_e32 v158, v0
	v_mul_f32_e32 v0, 0xbfb8aa3b, v164
	v_exp_f32_e32 v0, v0
	v_and_b32_e32 v179, 0xffff0000, v151
	v_lshlrev_b32_e32 v168, 16, v152
	v_and_b32_e32 v169, 0xffff0000, v152
	v_add_f32_e32 v0, 1.0, v0
	v_rcp_f32_e32 v164, v0
	v_mul_f32_e32 v0, 0xbfb8aa3b, v159
	v_exp_f32_e32 v0, v0
	v_lshlrev_b32_e32 v152, 16, v153
	v_and_b32_e32 v153, 0xffff0000, v153
	v_add_f32_e32 v0, 1.0, v0
	v_rcp_f32_e32 v159, v0
	v_mul_f32_e32 v0, 0xbfb8aa3b, v165
	v_exp_f32_e32 v0, v0
	s_nop 0
	v_add_f32_e32 v0, 1.0, v0
	v_rcp_f32_e32 v165, v0
	v_mul_f32_e32 v0, 0xbfb8aa3b, v156
	v_exp_f32_e32 v0, v0
	s_nop 0
	v_add_f32_e32 v0, 1.0, v0
	v_rcp_f32_e32 v156, v0
	v_mul_f32_e32 v0, 0xbfb8aa3b, v160
	v_exp_f32_e32 v0, v0
	v_lshlrev_b32_e32 v160, 16, v146
	v_add_f32_e32 v0, 1.0, v0
	v_rcp_f32_e32 v150, v0
	v_mul_f32_e32 v0, 0xbfb8aa3b, v157
	v_exp_f32_e32 v0, v0
	s_nop 0
	v_add_f32_e32 v0, 1.0, v0
	v_rcp_f32_e32 v157, v0
	v_mul_f32_e32 v0, 0xbfb8aa3b, v161
	v_exp_f32_e32 v0, v0
	v_and_b32_e32 v161, 0xffff0000, v146
	v_lshlrev_b32_e32 v146, 16, v147
	v_and_b32_e32 v147, 0xffff0000, v147
	v_add_f32_e32 v0, 1.0, v0
	v_rcp_f32_e32 v151, v0
	v_pk_fma_f32 v[156:157], v[156:157], v[178:179], v[146:147]
	v_pk_fma_f32 v[146:147], v[158:159], v[166:167], v[160:161]
	v_lshlrev_b32_e32 v158, 16, v148
	v_and_b32_e32 v159, 0xffff0000, v148
	v_lshlrev_b32_e32 v148, 16, v149
	v_and_b32_e32 v149, 0xffff0000, v149
	v_pk_fma_f32 v[150:151], v[150:151], v[152:153], v[148:149]
	v_mul_f32_e32 v0, v147, v147
	v_mul_f32_e32 v152, v157, v157
	v_pk_fma_f32 v[148:149], v[164:165], v[168:169], v[158:159]
	v_fmac_f32_e32 v0, v146, v146
	v_fmac_f32_e32 v152, v156, v156
	v_add_f32_e32 v0, v0, v152
	v_mul_f32_e32 v152, v149, v149
	v_fmac_f32_e32 v152, v148, v148
	v_add_f32_e32 v0, v152, v0
	v_mul_f32_e32 v152, v151, v151
	v_fmac_f32_e32 v152, v150, v150
	v_add_f32_e32 v0, v152, v0
	v_add_f32_e32 v0, v180, v0
	v_cvt_pk_bf16_f32 v146, v146, v147
	v_cvt_pk_bf16_f32 v147, v156, v157
	v_cvt_pk_bf16_f32 v148, v148, v149
	v_cvt_pk_bf16_f32 v149, v150, v151
	s_waitcnt lgkmcnt(0)
	global_store_dwordx4 v[226:227], v[218:221], off
	v_lshl_add_u64 v[228:229], v[154:155], 0, v[230:231]
	ds_bpermute_b32 v222, v243, v146
	ds_bpermute_b32 v223, v243, v147
	ds_bpermute_b32 v224, v243, v148
	ds_bpermute_b32 v225, v243, v149
	ds_bpermute_b32 v146, v171, v0
	s_waitcnt lgkmcnt(0)
	v_add_f32_e32 v0, v0, v146
	ds_bpermute_b32 v146, v170, v0
	s_and_saveexec_b64 s[8:9], s[40:41]
	s_cbranch_execz .LBB0_319
	v_lshl_add_u64 v[148:149], v[210:211], 2, s[44:45]
	s_waitcnt lgkmcnt(0)
	v_add_f32_e32 v0, v0, v146
	global_store_dword v[148:149], v0, off offset:512
.LBB0_319:
	s_or_b64 exec, exec, s[8:9]
	v_add_f32_e32 v0, v176, v177
	v_fmamk_f32 v0, v0, 0x3a800000, v197
	v_rsq_f32_e32 v0, v0
	s_waitcnt vmcnt(4)
	v_lshlrev_b32_e32 v156, 16, v142
	v_and_b32_e32 v157, 0xffff0000, v142
	v_lshlrev_b32_e32 v158, 16, v144
	v_pk_mul_f32 v[154:155], v[42:43], v[0:1] op_sel_hi:[1,0]
	v_pk_mul_f32 v[148:149], v[48:49], v[0:1] op_sel_hi:[1,0]
	v_mul_f32_e32 v155, 0xbfb8aa3b, v155
	v_exp_f32_e32 v155, v155
	v_mul_f32_e32 v148, 0xbfb8aa3b, v148
	v_exp_f32_e32 v148, v148
	v_pk_mul_f32 v[152:153], v[44:45], v[0:1] op_sel_hi:[1,0]
	v_add_f32_e32 v142, 1.0, v155
	v_rcp_f32_e32 v155, v142
	v_and_b32_e32 v159, 0xffff0000, v144
	v_add_f32_e32 v142, 1.0, v148
	v_mul_f32_e32 v144, 0xbfb8aa3b, v152
	v_mul_f32_e32 v148, 0xbfb8aa3b, v149
	v_exp_f32_e32 v144, v144
	v_exp_f32_e32 v149, v148
	v_pk_mul_f32 v[150:151], v[46:47], v[0:1] op_sel_hi:[1,0]
	v_rcp_f32_e32 v148, v142
	v_mul_f32_e32 v150, 0xbfb8aa3b, v150
	v_mul_f32_e32 v151, 0xbfb8aa3b, v151
	v_exp_f32_e32 v150, v150
	v_exp_f32_e32 v151, v151
	v_add_f32_e32 v142, 1.0, v144
	v_add_f32_e32 v144, 1.0, v149
	v_mul_f32_e32 v149, 0xbfb8aa3b, v153
	v_mul_f32_e32 v154, 0xbfb8aa3b, v154
	v_exp_f32_e32 v160, v149
	v_exp_f32_e32 v154, v154
	v_add_f32_e32 v150, 1.0, v150
	v_add_f32_e32 v151, 1.0, v151
	v_rcp_f32_e32 v150, v150
	v_rcp_f32_e32 v151, v151
	v_rcp_f32_e32 v149, v144
	v_lshlrev_b32_e32 v152, 16, v143
	v_and_b32_e32 v153, 0xffff0000, v143
	v_add_f32_e32 v143, 1.0, v160
	v_add_f32_e32 v154, 1.0, v154
	v_rcp_f32_e32 v142, v142
	v_rcp_f32_e32 v143, v143
	v_rcp_f32_e32 v154, v154
	v_lshlrev_b32_e32 v160, 16, v138
	v_and_b32_e32 v161, 0xffff0000, v138
	v_lshlrev_b32_e32 v138, 16, v139
	v_and_b32_e32 v139, 0xffff0000, v139
	v_lshlrev_b32_e32 v144, 16, v145
	v_and_b32_e32 v145, 0xffff0000, v145
	v_pk_fma_f32 v[148:149], v[148:149], v[152:153], v[138:139]
	v_pk_fma_f32 v[138:139], v[150:151], v[156:157], v[160:161]
	v_lshlrev_b32_e32 v150, 16, v140
	v_and_b32_e32 v151, 0xffff0000, v140
	v_lshlrev_b32_e32 v140, 16, v141
	v_and_b32_e32 v141, 0xffff0000, v141
	v_pk_fma_f32 v[142:143], v[142:143], v[144:145], v[140:141]
	v_mul_f32_e32 v144, v139, v139
	v_mul_f32_e32 v145, v149, v149
	v_pk_fma_f32 v[140:141], v[154:155], v[158:159], v[150:151]
	v_fmac_f32_e32 v144, v138, v138
	v_fmac_f32_e32 v145, v148, v148
	v_add_f32_e32 v144, v144, v145
	v_mul_f32_e32 v145, v141, v141
	v_fmac_f32_e32 v145, v140, v140
	v_add_f32_e32 v144, v145, v144
	v_mul_f32_e32 v145, v143, v143
	v_fmac_f32_e32 v145, v142, v142
	v_cvt_pk_bf16_f32 v140, v140, v141
	v_cvt_pk_bf16_f32 v141, v142, v143
	v_pk_mul_f32 v[142:143], v[38:39], v[0:1] op_sel_hi:[1,0]
	v_pk_mul_f32 v[150:151], v[34:35], v[0:1] op_sel_hi:[1,0]
	v_mul_f32_e32 v142, 0xbfb8aa3b, v142
	v_exp_f32_e32 v142, v142
	v_add_f32_e32 v158, v145, v144
	v_cvt_pk_bf16_f32 v138, v138, v139
	v_cvt_pk_bf16_f32 v139, v148, v149
	v_pk_mul_f32 v[144:145], v[40:41], v[0:1] op_sel_hi:[1,0]
	v_pk_mul_f32 v[148:149], v[36:37], v[0:1] op_sel_hi:[1,0]
	v_add_f32_e32 v0, 1.0, v142
	v_mul_f32_e32 v142, 0xbfb8aa3b, v150
	v_exp_f32_e32 v150, v142
	v_mul_f32_e32 v142, 0xbfb8aa3b, v143
	v_exp_f32_e32 v143, v142
	v_rcp_f32_e32 v142, v0
	v_add_f32_e32 v0, 1.0, v150
	v_rcp_f32_e32 v150, v0
	v_add_f32_e32 v0, 1.0, v143
	v_mul_f32_e32 v143, 0xbfb8aa3b, v151
	v_exp_f32_e32 v151, v143
	s_waitcnt vmcnt(2)
; __device__ __forceinline__ float bf_lo(unsigned w) { return __uint_as_float(w << 16); }
; __device__ __forceinline__ float bf_hi(unsigned w) { return __uint_as_float(w & 0xffff0000u); }
; __device__ __forceinline__ float sigm(float v) { return __builtin_amdgcn_rcpf(1.0f + __builtin_amdgcn_exp2f(-1.44269504089f * v)); }
; __device__ __forceinline__ u32x4 pack8(const f32x4& v0, const f32x4& v1) { u32x4 w; w.x = cvt_pk_bf16(v0[0], v0[1]); w.y = cvt_pk_bf16(v0[2], v0[3]); w.z = cvt_pk_bf16(v1[0], v1[1]); w.w = cvt_pk_bf16(v1[2], v1[3]); return w; }
; __device__ __forceinline__ float sumsq8(const f32x4& v0, const f32x4& v1) { return (v0[0] * v0[0] + v0[1] * v0[1]) + (v0[2] * v0[2] + v0[3] * v0[3]) + (v1[0] * v1[0] + v1[1] * v1[1]) + (v1[2] * v1[2] + v1[3] * v1[3]); }
; __device__ __forceinline__ void epi_run(const Epi& E, f32x4 (&acc)[2][2][4][2], const Unit& u, int wr, int wc, int fr, int fq) {
;     ...
;             for (int mh = 0; mh < 2; ++mh) { u32x4 x[2][2], c[2][2];
; #pragma unroll
;                 for (int mm = 0; mm < 2; ++mm)
; #pragma unroll
;                     for (int bj = 0; bj < 2; ++bj) { const size_t off = (size_t)(row0 + ai * 128 + (2 * mh + mm) * 16) * D + col0 + bj * 128; x[mm][bj] = *(const u32x4*)(E.xin16 + off); c[mm][bj] = *(const u32x4*)(E.C16 + off); }
; #pragma unroll
;                 for (int mm = 0; mm < 2; ++mm) { const int m = 2 * mh + mm, row = row0 + ai * 128 + m * 16; float sq = 0.f;
; #pragma unroll
;                     for (int bj = 0; bj < 2; ++bj) { const u32x4 xx = x[mm][bj], cc = c[mm][bj];
;                         const f32x4 c0 = (f32x4){bf_lo(cc.x), bf_hi(cc.x), bf_lo(cc.y), bf_hi(cc.y)}, c1 = (f32x4){bf_lo(cc.z), bf_hi(cc.z), bf_lo(cc.w), bf_hi(cc.w)};
;                         f32x4 v0 = acc[ai][bj][m][0] * rs[ai][m], v1 = acc[ai][bj][m][1] * rs[ai][m];
; #pragma unroll
;                         for (int e = 0; e < 4; ++e) { v0[e] = sigm(v0[e]) * c0[e]; v1[e] = sigm(v1[e]) * c1[e]; }
;                         const f32x4 x0 = (f32x4){bf_lo(xx.x), bf_hi(xx.x), bf_lo(xx.y), bf_hi(xx.y)} + v0, x1 = (f32x4){bf_lo(xx.z), bf_hi(xx.z), bf_lo(xx.w), bf_hi(xx.w)} + v1;
;                         sq += sumsq8(x0, x1); *(u32x4*)(E.xout16 + (size_t)row * D + col0 + bj * 128) = pack8(x0, x1); }
;                     sq += __shfl_xor(sq, 16); sq += __shfl_xor(sq, 32); if (fq == 0) sslot[row] = sq; }
	v_lshlrev_b32_e32 v152, 16, v134
	v_and_b32_e32 v153, 0xffff0000, v134
	v_mul_f32_e32 v134, 0xbfb8aa3b, v144
	v_exp_f32_e32 v134, v134
	v_rcp_f32_e32 v143, v0
	v_add_f32_e32 v0, 1.0, v151
	v_rcp_f32_e32 v151, v0
	v_add_f32_e32 v0, 1.0, v134
	v_mul_f32_e32 v134, 0xbfb8aa3b, v148
	v_lshlrev_b32_e32 v154, 16, v136
	v_and_b32_e32 v155, 0xffff0000, v136
	v_exp_f32_e32 v134, v134
	v_mul_f32_e32 v136, 0xbfb8aa3b, v145
	v_exp_f32_e32 v136, v136
	v_rcp_f32_e32 v144, v0
	v_add_f32_e32 v0, 1.0, v134
	v_rcp_f32_e32 v134, v0
	v_add_f32_e32 v0, 1.0, v136
	v_mul_f32_e32 v136, 0xbfb8aa3b, v149
	v_exp_f32_e32 v136, v136
	v_rcp_f32_e32 v145, v0
	v_lshlrev_b32_e32 v148, 16, v135
	v_and_b32_e32 v149, 0xffff0000, v135
	v_add_f32_e32 v0, 1.0, v136
	v_rcp_f32_e32 v135, v0
	v_lshlrev_b32_e32 v156, 16, v130
	v_and_b32_e32 v157, 0xffff0000, v130
	v_lshlrev_b32_e32 v130, 16, v131
	v_and_b32_e32 v131, 0xffff0000, v131
	v_lshlrev_b32_e32 v136, 16, v137
	v_and_b32_e32 v137, 0xffff0000, v137
	v_pk_fma_f32 v[144:145], v[144:145], v[148:149], v[130:131]
	v_pk_fma_f32 v[130:131], v[142:143], v[152:153], v[156:157]
	v_lshlrev_b32_e32 v142, 16, v132
	v_and_b32_e32 v143, 0xffff0000, v132
	v_lshlrev_b32_e32 v132, 16, v133
	v_and_b32_e32 v133, 0xffff0000, v133
	v_pk_fma_f32 v[136:137], v[134:135], v[136:137], v[132:133]
	v_mul_f32_e32 v0, v131, v131
	v_mul_f32_e32 v132, v145, v145
	v_pk_fma_f32 v[134:135], v[150:151], v[154:155], v[142:143]
	v_fmac_f32_e32 v0, v130, v130
	v_fmac_f32_e32 v132, v144, v144
	v_add_f32_e32 v0, v0, v132
	v_mul_f32_e32 v132, v135, v135
	v_fmac_f32_e32 v132, v134, v134
	v_add_f32_e32 v0, v132, v0
	v_mul_f32_e32 v132, v137, v137
	v_fmac_f32_e32 v132, v136, v136
	v_add_f32_e32 v0, v132, v0
	v_add_f32_e32 v0, v158, v0
	ds_bpermute_b32 v148, v171, v0
	s_waitcnt lgkmcnt(1)
	v_lshlrev_b64 v[146:147], 11, v[162:163]
	v_lshl_add_u64 v[132:133], s[78:79], 0, v[146:147]
	v_lshl_add_u64 v[142:143], v[212:213], 1, v[132:133]
	v_cvt_pk_bf16_f32 v132, v130, v131
	s_waitcnt lgkmcnt(0)
	v_add_f32_e32 v0, v0, v148
	ds_bpermute_b32 v130, v170, v0
	v_cvt_pk_bf16_f32 v133, v144, v145
	v_cvt_pk_bf16_f32 v134, v134, v135
	v_cvt_pk_bf16_f32 v135, v136, v137
	s_waitcnt lgkmcnt(0)
	global_store_dwordx4 v[228:229], v[222:225], off offset:256
	v_lshl_add_u64 v[226:227], v[142:143], 0, v[230:231]
	ds_bpermute_b32 v218, v243, v138
	ds_bpermute_b32 v219, v243, v139
	ds_bpermute_b32 v220, v243, v140
	ds_bpermute_b32 v221, v243, v141
	s_waitcnt lgkmcnt(0)
	global_store_dwordx4 v[226:227], v[218:221], off
	v_lshl_add_u64 v[228:229], v[142:143], 0, v[230:231]
	ds_bpermute_b32 v222, v243, v132
	ds_bpermute_b32 v223, v243, v133
	ds_bpermute_b32 v224, v243, v134
	ds_bpermute_b32 v225, v243, v135
	s_and_saveexec_b64 s[8:9], s[40:41]
	s_cbranch_execz .LBB0_321
	v_lshl_add_u64 v[132:133], v[210:211], 2, s[44:45]
	s_waitcnt lgkmcnt(0)
	v_add_f32_e32 v0, v0, v130
	global_store_dword v[132:133], v0, off offset:576
.LBB0_321:
	s_or_b64 exec, exec, s[8:9]
	v_add_u32_e32 v164, 0xa0, v210
	v_ashrrev_i32_e32 v165, 31, v164
	s_waitcnt lgkmcnt(0)
	v_lshlrev_b64 v[130:131], 10, v[164:165]
	v_lshl_add_u64 v[130:131], v[130:131], 0, v[212:213]
	v_lshlrev_b64 v[130:131], 1, v[130:131]
	v_lshl_add_u64 v[132:133], s[48:49], 0, v[130:131]
	v_lshl_add_u64 v[134:135], s[62:63], 0, v[130:131]
	global_load_dwordx4 v[154:157], v[132:133], off
	global_load_dwordx4 v[158:161], v[134:135], off
	global_load_dwordx4 v[146:149], v[132:133], off offset:256
	v_or_b32_e32 v130, 0x100, v130
	v_lshl_add_u64 v[130:131], s[62:63], 0, v[130:131]
	global_load_dwordx4 v[150:153], v[130:131], off
	v_add_f32_e32 v0, v174, v175
	v_fmamk_f32 v0, v0, 0x3a800000, v197
	v_rsq_f32_e32 v0, v0
	v_add_u32_e32 v162, 0xb0, v210
	v_ashrrev_i32_e32 v163, 31, v162
	v_lshlrev_b64 v[130:131], 10, v[162:163]
	v_pk_mul_f32 v[166:167], v[30:31], v[0:1] op_sel_hi:[1,0]
	v_pk_mul_f32 v[178:179], v[26:27], v[0:1] op_sel_hi:[1,0]
	v_mul_f32_e32 v167, 0xbfb8aa3b, v167
	v_exp_f32_e32 v167, v167
	v_pk_mul_f32 v[174:175], v[32:33], v[0:1] op_sel_hi:[1,0]
	v_mul_f32_e32 v166, 0xbfb8aa3b, v166
	v_exp_f32_e32 v166, v166
	v_add_f32_e32 v167, 1.0, v167
	v_rcp_f32_e32 v169, v167
	v_pk_mul_f32 v[176:177], v[28:29], v[0:1] op_sel_hi:[1,0]
	v_add_f32_e32 v166, 1.0, v166
	v_rcp_f32_e32 v168, v166
	v_mul_f32_e32 v166, 0xbfb8aa3b, v178
	v_exp_f32_e32 v166, v166
	v_lshl_add_u64 v[130:131], v[130:131], 0, v[212:213]
	v_lshlrev_b64 v[134:135], 1, v[130:131]
	v_lshl_add_u64 v[130:131], s[48:49], 0, v[134:135]
	v_add_f32_e32 v166, 1.0, v166
	v_rcp_f32_e32 v166, v166
	v_lshl_add_u64 v[132:133], s[62:63], 0, v[134:135]
	v_or_b32_e32 v134, 0x100, v134
	v_lshl_add_u64 v[134:135], s[62:63], 0, v[134:135]
	global_load_dwordx4 v[138:141], v[130:131], off
	global_load_dwordx4 v[142:145], v[132:133], off
	s_nop 0
	global_load_dwordx4 v[130:133], v[130:131], off offset:256
	v_lshlrev_b64 v[164:165], 11, v[164:165]
	global_load_dwordx4 v[134:137], v[134:135], off
	s_waitcnt vmcnt(6)
; __device__ __forceinline__ float bf_lo(unsigned w) { return __uint_as_float(w << 16); }
; __device__ __forceinline__ float bf_hi(unsigned w) { return __uint_as_float(w & 0xffff0000u); }
; __device__ __forceinline__ float sigm(float v) { return __builtin_amdgcn_rcpf(1.0f + __builtin_amdgcn_exp2f(-1.44269504089f * v)); }
; __device__ __forceinline__ u32x4 pack8(const f32x4& v0, const f32x4& v1) { u32x4 w; w.x = cvt_pk_bf16(v0[0], v0[1]); w.y = cvt_pk_bf16(v0[2], v0[3]); w.z = cvt_pk_bf16(v1[0], v1[1]); w.w = cvt_pk_bf16(v1[2], v1[3]); return w; }
; __device__ __forceinline__ float sumsq8(const f32x4& v0, const f32x4& v1) { return (v0[0] * v0[0] + v0[1] * v0[1]) + (v0[2] * v0[2] + v0[3] * v0[3]) + (v1[0] * v1[0] + v1[1] * v1[1]) + (v1[2] * v1[2] + v1[3] * v1[3]); }
; __device__ __forceinline__ void epi_run(const Epi& E, f32x4 (&acc)[2][2][4][2], const Unit& u, int wr, int wc, int fr, int fq) {
;     ...
;                 for (int mm = 0; mm < 2; ++mm) { const int m = 2 * mh + mm, row = row0 + ai * 128 + m * 16; float sq = 0.f;
; #pragma unroll
;                     for (int bj = 0; bj < 2; ++bj) { const u32x4 xx = x[mm][bj], cc = c[mm][bj];
;                         const f32x4 c0 = (f32x4){bf_lo(cc.x), bf_hi(cc.x), bf_lo(cc.y), bf_hi(cc.y)}, c1 = (f32x4){bf_lo(cc.z), bf_hi(cc.z), bf_lo(cc.w), bf_hi(cc.w)};
;                         f32x4 v0 = acc[ai][bj][m][0] * rs[ai][m], v1 = acc[ai][bj][m][1] * rs[ai][m];
; #pragma unroll
;                         for (int e = 0; e < 4; ++e) { v0[e] = sigm(v0[e]) * c0[e]; v1[e] = sigm(v1[e]) * c1[e]; }
;                         const f32x4 x0 = (f32x4){bf_lo(xx.x), bf_hi(xx.x), bf_lo(xx.y), bf_hi(xx.y)} + v0, x1 = (f32x4){bf_lo(xx.z), bf_hi(xx.z), bf_lo(xx.w), bf_hi(xx.w)} + v1;
;                         sq += sumsq8(x0, x1); *(u32x4*)(E.xout16 + (size_t)row * D + col0 + bj * 128) = pack8(x0, x1); }
;                     sq += __shfl_xor(sq, 16); sq += __shfl_xor(sq, 32); if (fq == 0) sslot[row] = sq; }
	v_lshlrev_b32_e32 v180, 16, v158
	v_and_b32_e32 v181, 0xffff0000, v158
	v_mul_f32_e32 v158, 0xbfb8aa3b, v179
	v_exp_f32_e32 v158, v158
	v_lshlrev_b32_e32 v178, 16, v160
	v_and_b32_e32 v179, 0xffff0000, v160
	v_mul_f32_e32 v160, 0xbfb8aa3b, v175
	v_add_f32_e32 v158, 1.0, v158
	v_rcp_f32_e32 v167, v158
	v_mul_f32_e32 v158, 0xbfb8aa3b, v174
	v_exp_f32_e32 v158, v158
	v_exp_f32_e32 v160, v160
	v_lshlrev_b32_e32 v182, 16, v159
	v_and_b32_e32 v183, 0xffff0000, v159
	v_add_f32_e32 v158, 1.0, v158
	v_rcp_f32_e32 v174, v158
	v_mul_f32_e32 v158, 0xbfb8aa3b, v176
	v_mul_f32_e32 v159, 0xbfb8aa3b, v177
	v_exp_f32_e32 v158, v158
	v_exp_f32_e32 v159, v159
	v_add_f32_e32 v160, 1.0, v160
	v_rcp_f32_e32 v175, v160
	v_add_f32_e32 v158, 1.0, v158
	v_add_f32_e32 v159, 1.0, v159
	v_rcp_f32_e32 v158, v158
	v_rcp_f32_e32 v159, v159
	v_lshlrev_b32_e32 v176, 16, v154
	v_and_b32_e32 v177, 0xffff0000, v154
	v_lshlrev_b32_e32 v154, 16, v155
	v_and_b32_e32 v155, 0xffff0000, v155
	v_lshlrev_b32_e32 v160, 16, v161
	v_and_b32_e32 v161, 0xffff0000, v161
	v_pk_fma_f32 v[154:155], v[174:175], v[182:183], v[154:155]
	v_pk_fma_f32 v[168:169], v[168:169], v[180:181], v[176:177]
	v_lshlrev_b32_e32 v174, 16, v156
	v_and_b32_e32 v175, 0xffff0000, v156
	v_lshlrev_b32_e32 v156, 16, v157
	v_and_b32_e32 v157, 0xffff0000, v157
	v_pk_fma_f32 v[160:161], v[158:159], v[160:161], v[156:157]
	v_mul_f32_e32 v156, v169, v169
	v_mul_f32_e32 v157, v155, v155
	v_pk_fma_f32 v[158:159], v[166:167], v[178:179], v[174:175]
	v_fmac_f32_e32 v156, v168, v168
	v_fmac_f32_e32 v157, v154, v154
	v_add_f32_e32 v156, v156, v157
	v_mul_f32_e32 v157, v159, v159
	v_fmac_f32_e32 v157, v158, v158
	v_add_f32_e32 v156, v157, v156
	v_mul_f32_e32 v157, v161, v161
	v_fmac_f32_e32 v157, v160, v160
	v_add_f32_e32 v176, v157, v156
	v_cvt_pk_bf16_f32 v157, v154, v155
	v_lshl_add_u64 v[154:155], s[78:79], 0, v[164:165]
	v_cvt_pk_bf16_f32 v156, v168, v169
	v_cvt_pk_bf16_f32 v158, v158, v159
	v_cvt_pk_bf16_f32 v159, v160, v161
	v_lshl_add_u64 v[154:155], v[212:213], 1, v[154:155]
	s_waitcnt lgkmcnt(0)
	global_store_dwordx4 v[228:229], v[222:225], off offset:256
	v_lshl_add_u64 v[226:227], v[154:155], 0, v[230:231]
	ds_bpermute_b32 v218, v243, v156
	ds_bpermute_b32 v219, v243, v157
	ds_bpermute_b32 v220, v243, v158
	ds_bpermute_b32 v221, v243, v159
	v_pk_mul_f32 v[160:161], v[20:21], v[0:1] op_sel_hi:[1,0]
	v_pk_mul_f32 v[164:165], v[18:19], v[0:1] op_sel_hi:[1,0]
	v_pk_mul_f32 v[158:159], v[22:23], v[0:1] op_sel_hi:[1,0]
	v_pk_mul_f32 v[156:157], v[24:25], v[0:1] op_sel_hi:[1,0]
	v_mul_f32_e32 v0, 0xbfb8aa3b, v158
	v_exp_f32_e32 v0, v0
	s_waitcnt vmcnt(5)
	v_lshlrev_b32_e32 v166, 16, v150
	v_and_b32_e32 v167, 0xffff0000, v150
	v_lshlrev_b32_e32 v174, 16, v151
	v_add_f32_e32 v0, 1.0, v0
	v_rcp_f32_e32 v158, v0
	v_mul_f32_e32 v0, 0xbfb8aa3b, v164
	v_exp_f32_e32 v0, v0
	v_and_b32_e32 v175, 0xffff0000, v151
	v_lshlrev_b32_e32 v168, 16, v152
	v_and_b32_e32 v169, 0xffff0000, v152
	v_add_f32_e32 v0, 1.0, v0
	v_rcp_f32_e32 v164, v0
	v_mul_f32_e32 v0, 0xbfb8aa3b, v159
	v_exp_f32_e32 v0, v0
	v_lshlrev_b32_e32 v152, 16, v153
	v_and_b32_e32 v153, 0xffff0000, v153
	v_add_f32_e32 v0, 1.0, v0
	v_rcp_f32_e32 v159, v0
	v_mul_f32_e32 v0, 0xbfb8aa3b, v165
	v_exp_f32_e32 v0, v0
	s_nop 0
	v_add_f32_e32 v0, 1.0, v0
	v_rcp_f32_e32 v165, v0
	v_mul_f32_e32 v0, 0xbfb8aa3b, v156
	v_exp_f32_e32 v0, v0
	s_nop 0
	v_add_f32_e32 v0, 1.0, v0
	v_rcp_f32_e32 v156, v0
	v_mul_f32_e32 v0, 0xbfb8aa3b, v160
	v_exp_f32_e32 v0, v0
	v_lshlrev_b32_e32 v160, 16, v146
	v_add_f32_e32 v0, 1.0, v0
	v_rcp_f32_e32 v150, v0
	v_mul_f32_e32 v0, 0xbfb8aa3b, v157
	v_exp_f32_e32 v0, v0
	s_nop 0
	v_add_f32_e32 v0, 1.0, v0
	v_rcp_f32_e32 v157, v0
	v_mul_f32_e32 v0, 0xbfb8aa3b, v161
	v_exp_f32_e32 v0, v0
	v_and_b32_e32 v161, 0xffff0000, v146
	v_lshlrev_b32_e32 v146, 16, v147
	v_and_b32_e32 v147, 0xffff0000, v147
	v_add_f32_e32 v0, 1.0, v0
	v_rcp_f32_e32 v151, v0
	v_pk_fma_f32 v[156:157], v[156:157], v[174:175], v[146:147]
	v_pk_fma_f32 v[146:147], v[158:159], v[166:167], v[160:161]
	v_lshlrev_b32_e32 v158, 16, v148
	v_and_b32_e32 v159, 0xffff0000, v148
	v_lshlrev_b32_e32 v148, 16, v149
	v_and_b32_e32 v149, 0xffff0000, v149
	v_pk_fma_f32 v[150:151], v[150:151], v[152:153], v[148:149]
	v_mul_f32_e32 v0, v147, v147
	v_mul_f32_e32 v152, v157, v157
	v_pk_fma_f32 v[148:149], v[164:165], v[168:169], v[158:159]
	v_fmac_f32_e32 v0, v146, v146
	v_fmac_f32_e32 v152, v156, v156
	v_add_f32_e32 v0, v0, v152
	v_mul_f32_e32 v152, v149, v149
	v_fmac_f32_e32 v152, v148, v148
	v_add_f32_e32 v0, v152, v0
	v_mul_f32_e32 v152, v151, v151
	v_fmac_f32_e32 v152, v150, v150
	v_add_f32_e32 v0, v152, v0
	v_add_f32_e32 v0, v176, v0
	v_cvt_pk_bf16_f32 v146, v146, v147
	v_cvt_pk_bf16_f32 v147, v156, v157
	v_cvt_pk_bf16_f32 v148, v148, v149
	v_cvt_pk_bf16_f32 v149, v150, v151
	s_waitcnt lgkmcnt(0)
	global_store_dwordx4 v[226:227], v[218:221], off
	v_lshl_add_u64 v[228:229], v[154:155], 0, v[230:231]
	ds_bpermute_b32 v222, v243, v146
	ds_bpermute_b32 v223, v243, v147
	ds_bpermute_b32 v224, v243, v148
	ds_bpermute_b32 v225, v243, v149
	ds_bpermute_b32 v146, v171, v0
	s_waitcnt lgkmcnt(0)
	v_add_f32_e32 v0, v0, v146
	ds_bpermute_b32 v146, v170, v0
	s_and_saveexec_b64 s[8:9], s[40:41]
	s_cbranch_execz .LBB0_323
	v_lshl_add_u64 v[148:149], v[210:211], 2, s[44:45]
	s_waitcnt lgkmcnt(0)
	v_add_f32_e32 v0, v0, v146
	global_store_dword v[148:149], v0, off offset:640
; __device__ __forceinline__ float bf_lo(unsigned w) { return __uint_as_float(w << 16); }
; __device__ __forceinline__ float bf_hi(unsigned w) { return __uint_as_float(w & 0xffff0000u); }
; __device__ __forceinline__ float sigm(float v) { return __builtin_amdgcn_rcpf(1.0f + __builtin_amdgcn_exp2f(-1.44269504089f * v)); }
; __device__ __forceinline__ u32x4 pack8(const f32x4& v0, const f32x4& v1) { u32x4 w; w.x = cvt_pk_bf16(v0[0], v0[1]); w.y = cvt_pk_bf16(v0[2], v0[3]); w.z = cvt_pk_bf16(v1[0], v1[1]); w.w = cvt_pk_bf16(v1[2], v1[3]); return w; }
; __device__ __forceinline__ float sumsq8(const f32x4& v0, const f32x4& v1) { return (v0[0] * v0[0] + v0[1] * v0[1]) + (v0[2] * v0[2] + v0[3] * v0[3]) + (v1[0] * v1[0] + v1[1] * v1[1]) + (v1[2] * v1[2] + v1[3] * v1[3]); }
; __device__ __forceinline__ void epi_run(const Epi& E, f32x4 (&acc)[2][2][4][2], const Unit& u, int wr, int wc, int fr, int fq) {
;     ...
;                 for (int mm = 0; mm < 2; ++mm) { const int m = 2 * mh + mm, row = row0 + ai * 128 + m * 16; float sq = 0.f;
; #pragma unroll
;                     for (int bj = 0; bj < 2; ++bj) { const u32x4 xx = x[mm][bj], cc = c[mm][bj];
;                         const f32x4 c0 = (f32x4){bf_lo(cc.x), bf_hi(cc.x), bf_lo(cc.y), bf_hi(cc.y)}, c1 = (f32x4){bf_lo(cc.z), bf_hi(cc.z), bf_lo(cc.w), bf_hi(cc.w)};
;                         f32x4 v0 = acc[ai][bj][m][0] * rs[ai][m], v1 = acc[ai][bj][m][1] * rs[ai][m];
; #pragma unroll
;                         for (int e = 0; e < 4; ++e) { v0[e] = sigm(v0[e]) * c0[e]; v1[e] = sigm(v1[e]) * c1[e]; }
;                         const f32x4 x0 = (f32x4){bf_lo(xx.x), bf_hi(xx.x), bf_lo(xx.y), bf_hi(xx.y)} + v0, x1 = (f32x4){bf_lo(xx.z), bf_hi(xx.z), bf_lo(xx.w), bf_hi(xx.w)} + v1;
;                         sq += sumsq8(x0, x1); *(u32x4*)(E.xout16 + (size_t)row * D + col0 + bj * 128) = pack8(x0, x1); }
;                     sq += __shfl_xor(sq, 16); sq += __shfl_xor(sq, 32); if (fq == 0) sslot[row] = sq; }
.LBB0_323:
	s_or_b64 exec, exec, s[8:9]
	v_add_f32_e32 v0, v172, v173
	v_fmamk_f32 v0, v0, 0x3a800000, v197
	v_rsq_f32_e32 v0, v0
	s_waitcnt vmcnt(4)
	v_lshlrev_b32_e32 v156, 16, v142
	v_and_b32_e32 v157, 0xffff0000, v142
	v_lshlrev_b32_e32 v158, 16, v144
	v_pk_mul_f32 v[154:155], v[10:11], v[0:1] op_sel_hi:[1,0]
	v_pk_mul_f32 v[148:149], v[16:17], v[0:1] op_sel_hi:[1,0]
	v_mul_f32_e32 v155, 0xbfb8aa3b, v155
	v_exp_f32_e32 v155, v155
	v_mul_f32_e32 v148, 0xbfb8aa3b, v148
	v_exp_f32_e32 v148, v148
	v_pk_mul_f32 v[152:153], v[12:13], v[0:1] op_sel_hi:[1,0]
	v_add_f32_e32 v142, 1.0, v155
	v_rcp_f32_e32 v155, v142
	v_and_b32_e32 v159, 0xffff0000, v144
	v_add_f32_e32 v142, 1.0, v148
	v_mul_f32_e32 v144, 0xbfb8aa3b, v152
	v_mul_f32_e32 v148, 0xbfb8aa3b, v149
	v_exp_f32_e32 v144, v144
	v_exp_f32_e32 v149, v148
	v_pk_mul_f32 v[150:151], v[14:15], v[0:1] op_sel_hi:[1,0]
	v_rcp_f32_e32 v148, v142
	v_mul_f32_e32 v150, 0xbfb8aa3b, v150
	v_mul_f32_e32 v151, 0xbfb8aa3b, v151
	v_exp_f32_e32 v150, v150
	v_exp_f32_e32 v151, v151
	v_add_f32_e32 v142, 1.0, v144
	v_add_f32_e32 v144, 1.0, v149
	v_mul_f32_e32 v149, 0xbfb8aa3b, v153
	v_mul_f32_e32 v154, 0xbfb8aa3b, v154
	v_exp_f32_e32 v160, v149
	v_exp_f32_e32 v154, v154
	v_add_f32_e32 v150, 1.0, v150
	v_add_f32_e32 v151, 1.0, v151
	v_rcp_f32_e32 v150, v150
	v_rcp_f32_e32 v151, v151
	v_rcp_f32_e32 v149, v144
	v_lshlrev_b32_e32 v152, 16, v143
	v_and_b32_e32 v153, 0xffff0000, v143
	v_add_f32_e32 v143, 1.0, v160
	v_add_f32_e32 v154, 1.0, v154
	v_rcp_f32_e32 v142, v142
	v_rcp_f32_e32 v143, v143
	v_rcp_f32_e32 v154, v154
	v_lshlrev_b32_e32 v160, 16, v138
	v_and_b32_e32 v161, 0xffff0000, v138
	v_lshlrev_b32_e32 v138, 16, v139
	v_and_b32_e32 v139, 0xffff0000, v139
	v_lshlrev_b32_e32 v144, 16, v145
	v_and_b32_e32 v145, 0xffff0000, v145
	v_pk_fma_f32 v[148:149], v[148:149], v[152:153], v[138:139]
	v_pk_fma_f32 v[138:139], v[150:151], v[156:157], v[160:161]
	v_lshlrev_b32_e32 v150, 16, v140
	v_and_b32_e32 v151, 0xffff0000, v140
	v_lshlrev_b32_e32 v140, 16, v141
	v_and_b32_e32 v141, 0xffff0000, v141
	v_pk_fma_f32 v[142:143], v[142:143], v[144:145], v[140:141]
	v_mul_f32_e32 v144, v139, v139
	v_mul_f32_e32 v145, v149, v149
	v_pk_fma_f32 v[140:141], v[154:155], v[158:159], v[150:151]
	v_fmac_f32_e32 v144, v138, v138
	v_fmac_f32_e32 v145, v148, v148
	v_add_f32_e32 v144, v144, v145
	v_mul_f32_e32 v145, v141, v141
	v_fmac_f32_e32 v145, v140, v140
	v_add_f32_e32 v144, v145, v144
	v_mul_f32_e32 v145, v143, v143
	v_fmac_f32_e32 v145, v142, v142
	v_cvt_pk_bf16_f32 v140, v140, v141
	v_cvt_pk_bf16_f32 v141, v142, v143
	v_pk_mul_f32 v[142:143], v[6:7], v[0:1] op_sel_hi:[1,0]
	v_pk_mul_f32 v[150:151], v[2:3], v[0:1] op_sel_hi:[1,0]
	v_mul_f32_e32 v142, 0xbfb8aa3b, v142
	v_exp_f32_e32 v142, v142
	v_add_f32_e32 v158, v145, v144
	v_cvt_pk_bf16_f32 v138, v138, v139
	v_cvt_pk_bf16_f32 v139, v148, v149
	v_pk_mul_f32 v[144:145], v[8:9], v[0:1] op_sel_hi:[1,0]
	v_pk_mul_f32 v[148:149], v[4:5], v[0:1] op_sel_hi:[1,0]
	v_add_f32_e32 v0, 1.0, v142
	v_mul_f32_e32 v142, 0xbfb8aa3b, v150
	v_exp_f32_e32 v150, v142
	v_mul_f32_e32 v142, 0xbfb8aa3b, v143
	v_exp_f32_e32 v143, v142
	v_rcp_f32_e32 v142, v0
	v_add_f32_e32 v0, 1.0, v150
	v_rcp_f32_e32 v150, v0
	v_add_f32_e32 v0, 1.0, v143
	v_mul_f32_e32 v143, 0xbfb8aa3b, v151
	v_exp_f32_e32 v151, v143
	s_waitcnt vmcnt(2)
	v_lshlrev_b32_e32 v152, 16, v134
	v_and_b32_e32 v153, 0xffff0000, v134
	v_mul_f32_e32 v134, 0xbfb8aa3b, v144
	v_exp_f32_e32 v134, v134
	v_rcp_f32_e32 v143, v0
	v_add_f32_e32 v0, 1.0, v151
	v_rcp_f32_e32 v151, v0
	v_add_f32_e32 v0, 1.0, v134
	v_mul_f32_e32 v134, 0xbfb8aa3b, v148
	v_lshlrev_b32_e32 v154, 16, v136
	v_and_b32_e32 v155, 0xffff0000, v136
	v_exp_f32_e32 v134, v134
	v_mul_f32_e32 v136, 0xbfb8aa3b, v145
	v_exp_f32_e32 v136, v136
	v_rcp_f32_e32 v144, v0
	v_add_f32_e32 v0, 1.0, v134
	v_rcp_f32_e32 v134, v0
	v_add_f32_e32 v0, 1.0, v136
	v_mul_f32_e32 v136, 0xbfb8aa3b, v149
	v_exp_f32_e32 v136, v136
	v_rcp_f32_e32 v145, v0
	v_lshlrev_b32_e32 v148, 16, v135
	v_and_b32_e32 v149, 0xffff0000, v135
	v_add_f32_e32 v0, 1.0, v136
	v_rcp_f32_e32 v135, v0
	v_lshlrev_b32_e32 v156, 16, v130
	v_and_b32_e32 v157, 0xffff0000, v130
	v_lshlrev_b32_e32 v130, 16, v131
	v_and_b32_e32 v131, 0xffff0000, v131
	v_lshlrev_b32_e32 v136, 16, v137
	v_and_b32_e32 v137, 0xffff0000, v137
	v_pk_fma_f32 v[144:145], v[144:145], v[148:149], v[130:131]
	v_pk_fma_f32 v[130:131], v[142:143], v[152:153], v[156:157]
	v_lshlrev_b32_e32 v142, 16, v132
	v_and_b32_e32 v143, 0xffff0000, v132
	v_lshlrev_b32_e32 v132, 16, v133
	v_and_b32_e32 v133, 0xffff0000, v133
	v_pk_fma_f32 v[136:137], v[134:135], v[136:137], v[132:133]
	v_mul_f32_e32 v0, v131, v131
	v_mul_f32_e32 v132, v145, v145
	v_pk_fma_f32 v[134:135], v[150:151], v[154:155], v[142:143]
	v_fmac_f32_e32 v0, v130, v130
	v_fmac_f32_e32 v132, v144, v144
	v_add_f32_e32 v0, v0, v132
	v_mul_f32_e32 v132, v135, v135
	v_fmac_f32_e32 v132, v134, v134
	v_add_f32_e32 v0, v132, v0
	v_mul_f32_e32 v132, v137, v137
	v_fmac_f32_e32 v132, v136, v136
	v_add_f32_e32 v0, v132, v0
	v_add_f32_e32 v0, v158, v0
	ds_bpermute_b32 v148, v171, v0
	s_waitcnt lgkmcnt(1)
	v_lshlrev_b64 v[146:147], 11, v[162:163]
	v_lshl_add_u64 v[132:133], s[78:79], 0, v[146:147]
	v_lshl_add_u64 v[142:143], v[212:213], 1, v[132:133]
	v_cvt_pk_bf16_f32 v132, v130, v131
	s_waitcnt lgkmcnt(0)
	v_add_f32_e32 v0, v0, v148
	ds_bpermute_b32 v130, v170, v0
	v_cvt_pk_bf16_f32 v133, v144, v145
	v_cvt_pk_bf16_f32 v134, v134, v135
	v_cvt_pk_bf16_f32 v135, v136, v137
	s_waitcnt lgkmcnt(0)
	global_store_dwordx4 v[228:229], v[222:225], off offset:256
	v_lshl_add_u64 v[226:227], v[142:143], 0, v[230:231]
	ds_bpermute_b32 v218, v243, v138
	ds_bpermute_b32 v219, v243, v139
	ds_bpermute_b32 v220, v243, v140
	ds_bpermute_b32 v221, v243, v141
	s_waitcnt lgkmcnt(0)
	global_store_dwordx4 v[226:227], v[218:221], off
	v_lshl_add_u64 v[228:229], v[142:143], 0, v[230:231]
	ds_bpermute_b32 v222, v243, v132
	ds_bpermute_b32 v223, v243, v133
	ds_bpermute_b32 v224, v243, v134
	ds_bpermute_b32 v225, v243, v135
	s_waitcnt lgkmcnt(0)
	global_store_dwordx4 v[228:229], v[222:225], off offset:256
	s_and_saveexec_b64 s[8:9], s[40:41]
	s_cbranch_execz .LBB0_325
	v_lshl_add_u64 v[132:133], v[210:211], 2, s[44:45]
	s_waitcnt lgkmcnt(0)
	v_add_f32_e32 v0, v0, v130
	global_store_dword v[132:133], v0, off offset:704

; __device__ __forceinline__ float sigm(float v) { return __builtin_amdgcn_rcpf(1.0f + __builtin_amdgcn_exp2f(-1.44269504089f * v)); }
; __device__ __forceinline__ u32x4 pack8(const f32x4& v0, const f32x4& v1) { u32x4 w; w.x = cvt_pk_bf16(v0[0], v0[1]); w.y = cvt_pk_bf16(v0[2], v0[3]); w.z = cvt_pk_bf16(v1[0], v1[1]); w.w = cvt_pk_bf16(v1[2], v1[3]); return w; }
; __device__ __forceinline__ float sumsq8(const f32x4& v0, const f32x4& v1) { return (v0[0] * v0[0] + v0[1] * v0[1]) + (v0[2] * v0[2] + v0[3] * v0[3]) + (v1[0] * v1[0] + v1[1] * v1[1]) + (v1[2] * v1[2] + v1[3] * v1[3]); }
; __device__ __forceinline__ f32x2 gelu_pk(f32x2 v) {
;     const f32x2 av = __builtin_elementwise_abs(v), d = av * 0.2316418882f + 1.0f;
;     f32x2 t; t.x = __builtin_amdgcn_rcpf(d.x); t.y = __builtin_amdgcn_rcpf(d.y);
;     f32x2 q = t * 0.5307027145f + (-0.7265760135f); q = q * t + 0.7107068705f; q = q * t + (-0.142248368f); q = q * t + 0.127414796f; q = q * t;
;     const f32x2 s = (v * v) * (-0.72134752044f);
;     f32x2 e; e.x = __builtin_amdgcn_exp2f(s.x); e.y = __builtin_amdgcn_exp2f(s.y);
;     const f32x2 m = v * (q * e), r = v - m;
;     f32x2 o; o.x = v.x < 0.f ? m.x : r.x; o.y = v.y < 0.f ? m.y : r.y; return o;
; }
; template <int ACT> __device__ __forceinline__ void epi_act_store(f32x4 (&acc)[2][2][4][2], const float (&rs)[2][4], bf16_t* out, int ld, int row0, int col0, float* ssqv_slot, bool want_ssq, int fq) {
;     ...
;         for (int m = 0; m < 4; ++m) { const int row = row0 + ai * 128 + m * 16; float sq = 0.f;
; #pragma unroll
;             for (int bj = 0; bj < 2; ++bj) { f32x4 v0 = acc[ai][bj][m][0] * rs[ai][m], v1 = acc[ai][bj][m][1] * rs[ai][m];
;                 if (ACT == 1) { f32x2 a = gelu_pk((f32x2){v0[0], v0[1]}), b = gelu_pk((f32x2){v0[2], v0[3]}), c = gelu_pk((f32x2){v1[0], v1[1]}), d = gelu_pk((f32x2){v1[2], v1[3]});
;                     v0 = (f32x4){a.x, a.y, b.x, b.y}; v1 = (f32x4){c.x, c.y, d.x, d.y}; sq += sumsq8(v0, v1); }
;                 if (ACT == 2) {
; #pragma unroll
;                     for (int e = 0; e < 4; ++e) { v0[e] = sigm(v0[e]); v1[e] = sigm(v1[e]); } }
;                 *(u32x4*)(out + (size_t)row * ld + col0 + bj * 128) = pack8(v0, v1); }
;             if (ACT == 1) { if (want_ssq) { sq += __shfl_xor(sq, 16); sq += __shfl_xor(sq, 32); if (fq == 0) ssqv_slot[row] = sq; } } }
.LBB0_330:
	s_andn2_b64 vcc, exec, s[8:9]
	s_cbranch_vccnz .LBB0_348
	v_lshrrev_b32_e32 v168, 2, v201
	v_and_b32_e32 v169, 3, v201
	v_lshl_add_u32 v167, v169, 4, v168
	v_lshlrev_b32_e32 v167, 2, v167
	v_and_b32_e32 v170, 15, v201
	v_sub_u32_e32 v168, v168, v170
	v_lshrrev_b32_e32 v170, 4, v201
	v_sub_u32_e32 v169, v169, v170
	v_lshlrev_b32_e32 v169, 4, v169
	v_mul_lo_u32 v168, v168, s69
	v_add_u32_e32 v180, v168, v169
	v_ashrrev_i32_e32 v181, 31, v180
	v_pk_mul_f32 v[154:155], v[126:127], v[130:131] op_sel_hi:[1,0]
	s_lshl_b32 s2, s23, 16
	v_and_b32_e32 v149, 0x7fffffff, v155
	v_and_b32_e32 v148, 0x7fffffff, v154
	v_pk_fma_f32 v[148:149], v[148:149], s[14:15], 1.0 op_sel_hi:[1,0,0]
	v_readlane_b32 s8, v250, 30
	v_rcp_f32_e32 v158, v148
	v_rcp_f32_e32 v159, v149
	s_add_i32 s30, s8, s2
	s_mov_b32 s2, 0xbf3a00e3
	v_mov_b64_e32 v[148:149], s[2:3]
	v_pk_mul_f32 v[162:163], v[154:155], v[154:155]
	v_pk_fma_f32 v[160:161], v[158:159], s[38:39], v[148:149] op_sel_hi:[1,0,0]
	v_pk_mul_f32 v[162:163], v[162:163], s[18:19] op_sel_hi:[1,0]
	v_pk_fma_f32 v[160:161], v[158:159], v[160:161], s[10:11] op_sel_hi:[1,1,0]
	v_exp_f32_e32 v162, v162
	v_exp_f32_e32 v163, v163
	v_pk_fma_f32 v[160:161], v[158:159], v[160:161], s[56:57] op_sel_hi:[1,1,0]
	v_pk_mul_f32 v[152:153], v[128:129], v[130:131] op_sel_hi:[1,0]
	v_pk_fma_f32 v[160:161], v[158:159], v[160:161], s[64:65] op_sel_hi:[1,1,0]
	v_cmp_gt_f32_e32 vcc, 0, v154
	v_pk_mul_f32 v[158:159], v[158:159], v[160:161]
	v_pk_mul_f32 v[160:161], v[152:153], v[152:153]
	v_pk_mul_f32 v[158:159], v[162:163], v[158:159]
	v_pk_mul_f32 v[156:157], v[122:123], v[130:131] op_sel_hi:[1,0]
	v_pk_mul_f32 v[162:163], v[154:155], v[158:159]
	v_pk_fma_f32 v[158:159], v[154:155], v[158:159], v[154:155] neg_lo:[1,0,0] neg_hi:[1,0,0]
	v_and_b32_e32 v154, 0x7fffffff, v152
	v_cndmask_b32_e32 v135, v158, v162, vcc
	v_cmp_gt_f32_e32 vcc, 0, v155
	v_and_b32_e32 v155, 0x7fffffff, v153
	v_pk_fma_f32 v[154:155], v[154:155], s[14:15], 1.0 op_sel_hi:[1,0,0]
	v_cndmask_b32_e32 v137, v159, v163, vcc
	v_rcp_f32_e32 v154, v154
	v_rcp_f32_e32 v155, v155
	v_cmp_gt_f32_e32 vcc, 0, v152
	v_pk_mul_f32 v[150:151], v[124:125], v[130:131] op_sel_hi:[1,0]
	s_lshl_b64 s[8:9], s[30:31], 2
	v_pk_fma_f32 v[158:159], v[154:155], s[38:39], v[148:149] op_sel_hi:[1,0,0]
	v_readlane_b32 s20, v250, 5
	v_pk_fma_f32 v[158:159], v[154:155], v[158:159], s[10:11] op_sel_hi:[1,1,0]
	v_mov_b32_e32 v213, v1
	v_pk_fma_f32 v[158:159], v[154:155], v[158:159], s[56:57] op_sel_hi:[1,1,0]
	v_readlane_b32 s21, v250, 6
	v_pk_fma_f32 v[158:159], v[154:155], v[158:159], s[64:65] op_sel_hi:[1,1,0]
	s_add_u32 s20, s20, s8
	v_pk_mul_f32 v[154:155], v[154:155], v[158:159]
	v_pk_mul_f32 v[158:159], v[160:161], s[18:19] op_sel_hi:[1,0]
	v_lshl_add_u64 v[146:147], v[212:213], 1, s[70:71]
	v_exp_f32_e32 v158, v158
	v_exp_f32_e32 v159, v159
	s_addc_u32 s21, s21, s9
	v_mad_i64_i32 v[144:145], s[8:9], v210, s69, v[146:147]
	v_pk_mul_f32 v[154:155], v[158:159], v[154:155]
	s_nop 0
	v_pk_mul_f32 v[158:159], v[152:153], v[154:155]
	v_pk_fma_f32 v[154:155], v[152:153], v[154:155], v[152:153] neg_lo:[1,0,0] neg_hi:[1,0,0]
	v_and_b32_e32 v152, 0x7fffffff, v156
	v_cndmask_b32_e32 v139, v154, v158, vcc
	v_cmp_gt_f32_e32 vcc, 0, v153
	v_and_b32_e32 v153, 0x7fffffff, v157
	v_pk_fma_f32 v[152:153], v[152:153], s[14:15], 1.0 op_sel_hi:[1,0,0]
	v_cndmask_b32_e32 v141, v155, v159, vcc
	v_rcp_f32_e32 v152, v152
	v_rcp_f32_e32 v153, v153
	v_pk_mul_f32 v[158:159], v[156:157], v[156:157]
	v_cmp_gt_f32_e32 vcc, 0, v156
	v_pk_mul_f32 v[158:159], v[158:159], s[18:19] op_sel_hi:[1,0]
	v_pk_fma_f32 v[154:155], v[152:153], s[38:39], v[148:149] op_sel_hi:[1,0,0]
	v_exp_f32_e32 v158, v158
	v_pk_fma_f32 v[154:155], v[152:153], v[154:155], s[10:11] op_sel_hi:[1,1,0]
	v_exp_f32_e32 v159, v159
	v_pk_fma_f32 v[154:155], v[152:153], v[154:155], s[56:57] op_sel_hi:[1,1,0]
	s_nop 0
	v_pk_fma_f32 v[154:155], v[152:153], v[154:155], s[64:65] op_sel_hi:[1,1,0]
	s_nop 0
	v_pk_mul_f32 v[152:153], v[152:153], v[154:155]
	v_pk_mul_f32 v[154:155], v[150:151], v[150:151]
	v_pk_mul_f32 v[152:153], v[158:159], v[152:153]
	v_pk_mul_f32 v[154:155], v[154:155], s[18:19] op_sel_hi:[1,0]
	v_pk_mul_f32 v[158:159], v[156:157], v[152:153]
	v_pk_fma_f32 v[152:153], v[156:157], v[152:153], v[156:157] neg_lo:[1,0,0] neg_hi:[1,0,0]
	v_exp_f32_e32 v154, v154
	v_cndmask_b32_e32 v143, v152, v158, vcc
	v_cmp_gt_f32_e32 vcc, 0, v157
	v_and_b32_e32 v152, 0x7fffffff, v150
	v_exp_f32_e32 v155, v155
	v_cndmask_b32_e32 v158, v153, v159, vcc
	v_and_b32_e32 v153, 0x7fffffff, v151
	v_pk_fma_f32 v[152:153], v[152:153], s[14:15], 1.0 op_sel_hi:[1,0,0]
	v_cmp_gt_f32_e32 vcc, 0, v150
	v_rcp_f32_e32 v152, v152
	v_rcp_f32_e32 v153, v153
	s_nop 0
	v_pk_fma_f32 v[156:157], v[152:153], s[38:39], v[148:149] op_sel_hi:[1,0,0]
	s_nop 0
	v_pk_fma_f32 v[156:157], v[152:153], v[156:157], s[10:11] op_sel_hi:[1,1,0]
	s_nop 0
	v_pk_fma_f32 v[156:157], v[152:153], v[156:157], s[56:57] op_sel_hi:[1,1,0]
	s_nop 0
	v_pk_fma_f32 v[156:157], v[152:153], v[156:157], s[64:65] op_sel_hi:[1,1,0]
	s_nop 0
	v_pk_mul_f32 v[152:153], v[152:153], v[156:157]
	v_pk_mul_f32 v[156:157], v[114:115], v[130:131] op_sel_hi:[1,0]
	v_pk_mul_f32 v[152:153], v[154:155], v[152:153]
	s_nop 0
	v_pk_mul_f32 v[154:155], v[150:151], v[152:153]
	v_pk_fma_f32 v[152:153], v[150:151], v[152:153], v[150:151] neg_lo:[1,0,0] neg_hi:[1,0,0]
	v_mul_f32_e32 v150, v137, v137
	v_cndmask_b32_e32 v154, v152, v154, vcc
	v_cmp_gt_f32_e32 vcc, 0, v151
	v_mul_f32_e32 v151, v141, v141
	v_fmac_f32_e32 v150, v135, v135
	v_fmac_f32_e32 v151, v139, v139
	v_add_f32_e32 v150, v150, v151
	v_mul_f32_e32 v151, v158, v158
; __device__ __forceinline__ float sigm(float v) { return __builtin_amdgcn_rcpf(1.0f + __builtin_amdgcn_exp2f(-1.44269504089f * v)); }
; __device__ __forceinline__ u32x4 pack8(const f32x4& v0, const f32x4& v1) { u32x4 w; w.x = cvt_pk_bf16(v0[0], v0[1]); w.y = cvt_pk_bf16(v0[2], v0[3]); w.z = cvt_pk_bf16(v1[0], v1[1]); w.w = cvt_pk_bf16(v1[2], v1[3]); return w; }
; __device__ __forceinline__ float sumsq8(const f32x4& v0, const f32x4& v1) { return (v0[0] * v0[0] + v0[1] * v0[1]) + (v0[2] * v0[2] + v0[3] * v0[3]) + (v1[0] * v1[0] + v1[1] * v1[1]) + (v1[2] * v1[2] + v1[3] * v1[3]); }
; template <int ACT> __device__ __forceinline__ void epi_act_store(f32x4 (&acc)[2][2][4][2], const float (&rs)[2][4], bf16_t* out, int ld, int row0, int col0, float* ssqv_slot, bool want_ssq, int fq) {
;     ...
;         for (int m = 0; m < 4; ++m) { const int row = row0 + ai * 128 + m * 16; float sq = 0.f;
; #pragma unroll
;             for (int bj = 0; bj < 2; ++bj) { f32x4 v0 = acc[ai][bj][m][0] * rs[ai][m], v1 = acc[ai][bj][m][1] * rs[ai][m];
;                 if (ACT == 1) { f32x2 a = gelu_pk((f32x2){v0[0], v0[1]}), b = gelu_pk((f32x2){v0[2], v0[3]}), c = gelu_pk((f32x2){v1[0], v1[1]}), d = gelu_pk((f32x2){v1[2], v1[3]});
;                     v0 = (f32x4){a.x, a.y, b.x, b.y}; v1 = (f32x4){c.x, c.y, d.x, d.y}; sq += sumsq8(v0, v1); }
;                 if (ACT == 2) {
; #pragma unroll
;                     for (int e = 0; e < 4; ++e) { v0[e] = sigm(v0[e]); v1[e] = sigm(v1[e]); } }
;                 *(u32x4*)(out + (size_t)row * ld + col0 + bj * 128) = pack8(v0, v1); }
;             if (ACT == 1) { if (want_ssq) { sq += __shfl_xor(sq, 16); sq += __shfl_xor(sq, 32); if (fq == 0) ssqv_slot[row] = sq; } } }
	v_cndmask_b32_e32 v153, v153, v155, vcc
	v_fmac_f32_e32 v151, v143, v143
	v_add_f32_e32 v150, v151, v150
	v_mul_f32_e32 v151, v153, v153
	v_fmac_f32_e32 v151, v154, v154
	v_cvt_pk_bf16_f32 v153, v154, v153
	v_pk_mul_f32 v[154:155], v[118:119], v[130:131] op_sel_hi:[1,0]
	v_cvt_pk_bf16_f32 v152, v143, v158
	v_and_b32_e32 v159, 0x7fffffff, v155
	v_and_b32_e32 v158, 0x7fffffff, v154
	v_pk_fma_f32 v[158:159], v[158:159], s[14:15], 1.0 op_sel_hi:[1,0,0]
	v_pk_mul_f32 v[162:163], v[154:155], v[154:155]
	v_rcp_f32_e32 v158, v158
	v_rcp_f32_e32 v159, v159
	v_pk_mul_f32 v[162:163], v[162:163], s[18:19] op_sel_hi:[1,0]
	v_add_f32_e32 v164, v151, v150
	v_exp_f32_e32 v162, v162
	v_pk_fma_f32 v[160:161], v[158:159], s[38:39], v[148:149] op_sel_hi:[1,0,0]
	v_exp_f32_e32 v163, v163
	v_pk_fma_f32 v[160:161], v[158:159], v[160:161], s[10:11] op_sel_hi:[1,1,0]
	v_cvt_pk_bf16_f32 v150, v135, v137
	v_pk_fma_f32 v[160:161], v[158:159], v[160:161], s[56:57] op_sel_hi:[1,1,0]
	v_cvt_pk_bf16_f32 v151, v139, v141
	v_pk_fma_f32 v[160:161], v[158:159], v[160:161], s[64:65] op_sel_hi:[1,1,0]
	v_lshl_add_u64 v[176:177], v[144:145], 0, v[180:181]
	ds_bpermute_b32 v168, v167, v150
	ds_bpermute_b32 v169, v167, v151
	ds_bpermute_b32 v170, v167, v152
	ds_bpermute_b32 v171, v167, v153
	v_pk_mul_f32 v[158:159], v[158:159], v[160:161]
	v_cmp_gt_f32_e32 vcc, 0, v154
	v_pk_mul_f32 v[158:159], v[162:163], v[158:159]
	v_pk_mul_f32 v[152:153], v[120:121], v[130:131] op_sel_hi:[1,0]
	v_pk_mul_f32 v[162:163], v[154:155], v[158:159]
	v_pk_fma_f32 v[158:159], v[154:155], v[158:159], v[154:155] neg_lo:[1,0,0] neg_hi:[1,0,0]
	v_and_b32_e32 v154, 0x7fffffff, v152
	v_cndmask_b32_e32 v135, v158, v162, vcc
	v_cmp_gt_f32_e32 vcc, 0, v155
	v_and_b32_e32 v155, 0x7fffffff, v153
	v_pk_fma_f32 v[154:155], v[154:155], s[14:15], 1.0 op_sel_hi:[1,0,0]
	v_cndmask_b32_e32 v137, v159, v163, vcc
	v_rcp_f32_e32 v154, v154
	v_rcp_f32_e32 v155, v155
	v_pk_mul_f32 v[160:161], v[152:153], v[152:153]
	v_cmp_gt_f32_e32 vcc, 0, v152
	v_pk_mul_f32 v[150:151], v[116:117], v[130:131] op_sel_hi:[1,0]
	v_pk_fma_f32 v[158:159], v[154:155], s[38:39], v[148:149] op_sel_hi:[1,0,0]
	s_nop 0
	v_pk_fma_f32 v[158:159], v[154:155], v[158:159], s[10:11] op_sel_hi:[1,1,0]
	s_nop 0
	v_pk_fma_f32 v[158:159], v[154:155], v[158:159], s[56:57] op_sel_hi:[1,1,0]
	s_nop 0
	v_pk_fma_f32 v[158:159], v[154:155], v[158:159], s[64:65] op_sel_hi:[1,1,0]
	s_nop 0
	v_pk_mul_f32 v[154:155], v[154:155], v[158:159]
	v_pk_mul_f32 v[158:159], v[160:161], s[18:19] op_sel_hi:[1,0]
	s_nop 0
	v_exp_f32_e32 v158, v158
	v_exp_f32_e32 v159, v159
	s_nop 0
	v_pk_mul_f32 v[154:155], v[158:159], v[154:155]
	s_nop 0
	v_pk_mul_f32 v[158:159], v[152:153], v[154:155]
	v_pk_fma_f32 v[154:155], v[152:153], v[154:155], v[152:153] neg_lo:[1,0,0] neg_hi:[1,0,0]
	v_and_b32_e32 v152, 0x7fffffff, v156
	v_cndmask_b32_e32 v139, v154, v158, vcc
	v_cmp_gt_f32_e32 vcc, 0, v153
	v_and_b32_e32 v153, 0x7fffffff, v157
	v_pk_fma_f32 v[152:153], v[152:153], s[14:15], 1.0 op_sel_hi:[1,0,0]
	v_cndmask_b32_e32 v141, v155, v159, vcc
	v_rcp_f32_e32 v152, v152
	v_rcp_f32_e32 v153, v153
	v_pk_mul_f32 v[158:159], v[156:157], v[156:157]
	v_cmp_gt_f32_e32 vcc, 0, v156
	v_pk_mul_f32 v[158:159], v[158:159], s[18:19] op_sel_hi:[1,0]
	v_pk_fma_f32 v[154:155], v[152:153], s[38:39], v[148:149] op_sel_hi:[1,0,0]
	v_exp_f32_e32 v158, v158
	v_pk_fma_f32 v[154:155], v[152:153], v[154:155], s[10:11] op_sel_hi:[1,1,0]
	v_exp_f32_e32 v159, v159
	v_pk_fma_f32 v[154:155], v[152:153], v[154:155], s[56:57] op_sel_hi:[1,1,0]
	s_nop 0
	v_pk_fma_f32 v[154:155], v[152:153], v[154:155], s[64:65] op_sel_hi:[1,1,0]
	s_nop 0
	v_pk_mul_f32 v[152:153], v[152:153], v[154:155]
	v_pk_mul_f32 v[154:155], v[150:151], v[150:151]
	v_pk_mul_f32 v[152:153], v[158:159], v[152:153]
	s_nop 0
	v_pk_mul_f32 v[158:159], v[156:157], v[152:153]
	v_pk_fma_f32 v[152:153], v[156:157], v[152:153], v[156:157] neg_lo:[1,0,0] neg_hi:[1,0,0]
	s_nop 0
	v_cndmask_b32_e32 v143, v152, v158, vcc
	v_cmp_gt_f32_e32 vcc, 0, v157
	v_and_b32_e32 v152, 0x7fffffff, v150
	s_nop 0
	v_cndmask_b32_e32 v156, v153, v159, vcc
	v_and_b32_e32 v153, 0x7fffffff, v151
	v_pk_fma_f32 v[152:153], v[152:153], s[14:15], 1.0 op_sel_hi:[1,0,0]
	v_cmp_gt_f32_e32 vcc, 0, v150
	v_rcp_f32_e32 v152, v152
	v_rcp_f32_e32 v153, v153
	s_nop 0
	v_pk_fma_f32 v[148:149], v[152:153], s[38:39], v[148:149] op_sel_hi:[1,0,0]
	s_nop 0
	v_pk_fma_f32 v[148:149], v[152:153], v[148:149], s[10:11] op_sel_hi:[1,1,0]
	s_nop 0
	v_pk_fma_f32 v[148:149], v[152:153], v[148:149], s[56:57] op_sel_hi:[1,1,0]
	s_nop 0
	v_pk_fma_f32 v[148:149], v[152:153], v[148:149], s[64:65] op_sel_hi:[1,1,0]
	s_nop 0
	v_pk_mul_f32 v[148:149], v[152:153], v[148:149]
	v_pk_mul_f32 v[152:153], v[154:155], s[18:19] op_sel_hi:[1,0]
	s_nop 0
	v_exp_f32_e32 v152, v152
	v_exp_f32_e32 v153, v153
	s_nop 0
	v_pk_mul_f32 v[148:149], v[152:153], v[148:149]
	s_nop 0
	v_pk_mul_f32 v[152:153], v[150:151], v[148:149]
	v_pk_fma_f32 v[148:149], v[150:151], v[148:149], v[150:151] neg_lo:[1,0,0] neg_hi:[1,0,0]
	v_cvt_pk_bf16_f32 v150, v143, v156
	v_cndmask_b32_e32 v152, v148, v152, vcc
	v_cmp_gt_f32_e32 vcc, 0, v151
	v_mul_f32_e32 v148, v137, v137
	v_fmac_f32_e32 v148, v135, v135
	v_cndmask_b32_e32 v151, v149, v153, vcc
	v_mul_f32_e32 v149, v141, v141
	v_fmac_f32_e32 v149, v139, v139
	v_add_f32_e32 v148, v148, v149
	v_mul_f32_e32 v149, v156, v156
	v_fmac_f32_e32 v149, v143, v143
	v_add_f32_e32 v148, v149, v148
	v_mul_f32_e32 v149, v151, v151
	v_fmac_f32_e32 v149, v152, v152
	v_add_f32_e32 v148, v149, v148
	v_add_f32_e32 v153, v164, v148
	v_cvt_pk_bf16_f32 v148, v135, v137
	ds_bpermute_b32 v135, v133, v153
	v_cvt_pk_bf16_f32 v149, v139, v141
	v_cvt_pk_bf16_f32 v151, v152, v151
	s_waitcnt lgkmcnt(0)
	global_store_dwordx4 v[176:177], v[168:171], off
	v_lshl_add_u64 v[178:179], v[144:145], 0, v[180:181]
	ds_bpermute_b32 v172, v167, v148
	ds_bpermute_b32 v173, v167, v149
	ds_bpermute_b32 v174, v167, v150
	ds_bpermute_b32 v175, v167, v151
	v_lshl_add_u64 v[144:145], v[210:211], 2, s[20:21]
	s_waitcnt lgkmcnt(0)
	v_add_f32_e32 v135, v153, v135
	ds_bpermute_b32 v137, v131, v135
	s_and_saveexec_b64 s[8:9], s[40:41]
	s_cbranch_execz .LBB0_333
	s_waitcnt lgkmcnt(0)
	v_add_f32_e32 v135, v135, v137
	global_store_dword v[144:145], v135, off
; __device__ __forceinline__ float sigm(float v) { return __builtin_amdgcn_rcpf(1.0f + __builtin_amdgcn_exp2f(-1.44269504089f * v)); }
; __device__ __forceinline__ u32x4 pack8(const f32x4& v0, const f32x4& v1) { u32x4 w; w.x = cvt_pk_bf16(v0[0], v0[1]); w.y = cvt_pk_bf16(v0[2], v0[3]); w.z = cvt_pk_bf16(v1[0], v1[1]); w.w = cvt_pk_bf16(v1[2], v1[3]); return w; }
; __device__ __forceinline__ float sumsq8(const f32x4& v0, const f32x4& v1) { return (v0[0] * v0[0] + v0[1] * v0[1]) + (v0[2] * v0[2] + v0[3] * v0[3]) + (v1[0] * v1[0] + v1[1] * v1[1]) + (v1[2] * v1[2] + v1[3] * v1[3]); }
; __device__ __forceinline__ f32x2 gelu_pk(f32x2 v) {
;     const f32x2 av = __builtin_elementwise_abs(v), d = av * 0.2316418882f + 1.0f;
;     f32x2 t; t.x = __builtin_amdgcn_rcpf(d.x); t.y = __builtin_amdgcn_rcpf(d.y);
;     f32x2 q = t * 0.5307027145f + (-0.7265760135f); q = q * t + 0.7107068705f; q = q * t + (-0.142248368f); q = q * t + 0.127414796f; q = q * t;
;     const f32x2 s = (v * v) * (-0.72134752044f);
;     f32x2 e; e.x = __builtin_amdgcn_exp2f(s.x); e.y = __builtin_amdgcn_exp2f(s.y);
;     const f32x2 m = v * (q * e), r = v - m;
;     f32x2 o; o.x = v.x < 0.f ? m.x : r.x; o.y = v.y < 0.f ? m.y : r.y; return o;
; }
; template <int ACT> __device__ __forceinline__ void epi_act_store(f32x4 (&acc)[2][2][4][2], const float (&rs)[2][4], bf16_t* out, int ld, int row0, int col0, float* ssqv_slot, bool want_ssq, int fq) {
;     ...
;         for (int m = 0; m < 4; ++m) { const int row = row0 + ai * 128 + m * 16; float sq = 0.f;
; #pragma unroll
;             for (int bj = 0; bj < 2; ++bj) { f32x4 v0 = acc[ai][bj][m][0] * rs[ai][m], v1 = acc[ai][bj][m][1] * rs[ai][m];
;                 if (ACT == 1) { f32x2 a = gelu_pk((f32x2){v0[0], v0[1]}), b = gelu_pk((f32x2){v0[2], v0[3]}), c = gelu_pk((f32x2){v1[0], v1[1]}), d = gelu_pk((f32x2){v1[2], v1[3]});
;                     v0 = (f32x4){a.x, a.y, b.x, b.y}; v1 = (f32x4){c.x, c.y, d.x, d.y}; sq += sumsq8(v0, v1); }
;                 if (ACT == 2) {
; #pragma unroll
;                     for (int e = 0; e < 4; ++e) { v0[e] = sigm(v0[e]); v1[e] = sigm(v1[e]); } }
;                 *(u32x4*)(out + (size_t)row * ld + col0 + bj * 128) = pack8(v0, v1); }
;             if (ACT == 1) { if (want_ssq) { sq += __shfl_xor(sq, 16); sq += __shfl_xor(sq, 32); if (fq == 0) ssqv_slot[row] = sq; } } }
.LBB0_333:
	s_or_b64 exec, exec, s[8:9]
	v_pk_mul_f32 v[156:157], v[110:111], v[0:1] op_sel_hi:[1,0]
	v_or_b32_e32 v135, 16, v210
	v_and_b32_e32 v151, 0x7fffffff, v157
	v_and_b32_e32 v150, 0x7fffffff, v156
	v_pk_fma_f32 v[150:151], v[150:151], s[14:15], 1.0 op_sel_hi:[1,0,0]
	v_pk_mul_f32 v[164:165], v[156:157], v[156:157]
	v_rcp_f32_e32 v160, v150
	v_rcp_f32_e32 v161, v151
	v_mov_b64_e32 v[150:151], s[2:3]
	v_pk_mul_f32 v[164:165], v[164:165], s[18:19] op_sel_hi:[1,0]
	v_pk_mul_f32 v[154:155], v[112:113], v[0:1] op_sel_hi:[1,0]
	v_pk_fma_f32 v[162:163], v[160:161], s[38:39], v[150:151] op_sel_hi:[1,0,0]
	v_exp_f32_e32 v164, v164
	v_pk_fma_f32 v[162:163], v[160:161], v[162:163], s[10:11] op_sel_hi:[1,1,0]
	v_exp_f32_e32 v165, v165
	v_pk_fma_f32 v[162:163], v[160:161], v[162:163], s[56:57] op_sel_hi:[1,1,0]
	v_cmp_gt_f32_e32 vcc, 0, v156
	v_pk_fma_f32 v[162:163], v[160:161], v[162:163], s[64:65] op_sel_hi:[1,1,0]
	v_mad_i64_i32 v[148:149], s[8:9], v135, s69, v[146:147]
	v_pk_mul_f32 v[160:161], v[160:161], v[162:163]
	v_pk_mul_f32 v[162:163], v[154:155], v[154:155]
	v_pk_mul_f32 v[160:161], v[164:165], v[160:161]
	v_pk_mul_f32 v[158:159], v[106:107], v[0:1] op_sel_hi:[1,0]
	v_pk_mul_f32 v[164:165], v[156:157], v[160:161]
	v_pk_fma_f32 v[160:161], v[156:157], v[160:161], v[156:157] neg_lo:[1,0,0] neg_hi:[1,0,0]
	v_and_b32_e32 v156, 0x7fffffff, v154
	v_cndmask_b32_e32 v135, v160, v164, vcc
	v_cmp_gt_f32_e32 vcc, 0, v157
	v_and_b32_e32 v157, 0x7fffffff, v155
	v_pk_fma_f32 v[156:157], v[156:157], s[14:15], 1.0 op_sel_hi:[1,0,0]
	s_waitcnt lgkmcnt(0)
	v_cndmask_b32_e32 v137, v161, v165, vcc
	v_rcp_f32_e32 v156, v156
	v_rcp_f32_e32 v157, v157
	v_cmp_gt_f32_e32 vcc, 0, v154
	v_pk_mul_f32 v[152:153], v[108:109], v[0:1] op_sel_hi:[1,0]
	v_pk_fma_f32 v[160:161], v[156:157], s[38:39], v[150:151] op_sel_hi:[1,0,0]
	s_nop 0
	v_pk_fma_f32 v[160:161], v[156:157], v[160:161], s[10:11] op_sel_hi:[1,1,0]
	s_nop 0
	v_pk_fma_f32 v[160:161], v[156:157], v[160:161], s[56:57] op_sel_hi:[1,1,0]
	s_nop 0
	v_pk_fma_f32 v[160:161], v[156:157], v[160:161], s[64:65] op_sel_hi:[1,1,0]
	s_nop 0
	v_pk_mul_f32 v[156:157], v[156:157], v[160:161]
	v_pk_mul_f32 v[160:161], v[162:163], s[18:19] op_sel_hi:[1,0]
	s_nop 0
	v_exp_f32_e32 v160, v160
	v_exp_f32_e32 v161, v161
	s_nop 0
	v_pk_mul_f32 v[156:157], v[160:161], v[156:157]
	s_nop 0
	v_pk_mul_f32 v[160:161], v[154:155], v[156:157]
	v_pk_fma_f32 v[156:157], v[154:155], v[156:157], v[154:155] neg_lo:[1,0,0] neg_hi:[1,0,0]
	v_and_b32_e32 v154, 0x7fffffff, v158
	v_cndmask_b32_e32 v139, v156, v160, vcc
	v_cmp_gt_f32_e32 vcc, 0, v155
	v_and_b32_e32 v155, 0x7fffffff, v159
	v_pk_fma_f32 v[154:155], v[154:155], s[14:15], 1.0 op_sel_hi:[1,0,0]
	v_cndmask_b32_e32 v141, v157, v161, vcc
	v_rcp_f32_e32 v154, v154
	v_rcp_f32_e32 v155, v155
	v_pk_mul_f32 v[160:161], v[158:159], v[158:159]
	v_cmp_gt_f32_e32 vcc, 0, v158
	v_pk_mul_f32 v[160:161], v[160:161], s[18:19] op_sel_hi:[1,0]
	v_pk_fma_f32 v[156:157], v[154:155], s[38:39], v[150:151] op_sel_hi:[1,0,0]
	v_exp_f32_e32 v160, v160
	v_pk_fma_f32 v[156:157], v[154:155], v[156:157], s[10:11] op_sel_hi:[1,1,0]
	v_exp_f32_e32 v161, v161
	v_pk_fma_f32 v[156:157], v[154:155], v[156:157], s[56:57] op_sel_hi:[1,1,0]
	s_nop 0
	v_pk_fma_f32 v[156:157], v[154:155], v[156:157], s[64:65] op_sel_hi:[1,1,0]
	s_nop 0
	v_pk_mul_f32 v[154:155], v[154:155], v[156:157]
	v_pk_mul_f32 v[156:157], v[152:153], v[152:153]
	v_pk_mul_f32 v[154:155], v[160:161], v[154:155]
	v_pk_mul_f32 v[156:157], v[156:157], s[18:19] op_sel_hi:[1,0]
	v_pk_mul_f32 v[160:161], v[158:159], v[154:155]
	v_pk_fma_f32 v[154:155], v[158:159], v[154:155], v[158:159] neg_lo:[1,0,0] neg_hi:[1,0,0]
	v_exp_f32_e32 v156, v156
	v_cndmask_b32_e32 v143, v154, v160, vcc
	v_cmp_gt_f32_e32 vcc, 0, v159
	v_and_b32_e32 v154, 0x7fffffff, v152
	v_exp_f32_e32 v157, v157
	v_cndmask_b32_e32 v160, v155, v161, vcc
	v_and_b32_e32 v155, 0x7fffffff, v153
	v_pk_fma_f32 v[154:155], v[154:155], s[14:15], 1.0 op_sel_hi:[1,0,0]
	v_cmp_gt_f32_e32 vcc, 0, v152
	v_rcp_f32_e32 v154, v154
	v_rcp_f32_e32 v155, v155
	s_nop 0
	v_pk_fma_f32 v[158:159], v[154:155], s[38:39], v[150:151] op_sel_hi:[1,0,0]
	s_nop 0
	v_pk_fma_f32 v[158:159], v[154:155], v[158:159], s[10:11] op_sel_hi:[1,1,0]
	s_nop 0
	v_pk_fma_f32 v[158:159], v[154:155], v[158:159], s[56:57] op_sel_hi:[1,1,0]
	s_nop 0
	v_pk_fma_f32 v[158:159], v[154:155], v[158:159], s[64:65] op_sel_hi:[1,1,0]
	s_nop 0
	v_pk_mul_f32 v[154:155], v[154:155], v[158:159]
	v_pk_mul_f32 v[158:159], v[94:95], v[0:1] op_sel_hi:[1,0]
	v_pk_mul_f32 v[154:155], v[156:157], v[154:155]
	s_nop 0
	v_pk_mul_f32 v[156:157], v[152:153], v[154:155]
	v_pk_fma_f32 v[154:155], v[152:153], v[154:155], v[152:153] neg_lo:[1,0,0] neg_hi:[1,0,0]
	v_mul_f32_e32 v152, v137, v137
	v_cndmask_b32_e32 v156, v154, v156, vcc
	v_cmp_gt_f32_e32 vcc, 0, v153
	v_mul_f32_e32 v153, v141, v141
	v_fmac_f32_e32 v152, v135, v135
	v_fmac_f32_e32 v153, v139, v139
	v_add_f32_e32 v152, v152, v153
	v_mul_f32_e32 v153, v160, v160
	v_cndmask_b32_e32 v155, v155, v157, vcc
	v_fmac_f32_e32 v153, v143, v143
	v_add_f32_e32 v152, v153, v152
	v_mul_f32_e32 v153, v155, v155
	v_fmac_f32_e32 v153, v156, v156
	v_cvt_pk_bf16_f32 v155, v156, v155
	v_pk_mul_f32 v[156:157], v[102:103], v[0:1] op_sel_hi:[1,0]
	v_cvt_pk_bf16_f32 v154, v143, v160
	v_and_b32_e32 v161, 0x7fffffff, v157
	v_and_b32_e32 v160, 0x7fffffff, v156
	v_pk_fma_f32 v[160:161], v[160:161], s[14:15], 1.0 op_sel_hi:[1,0,0]
	v_pk_mul_f32 v[164:165], v[156:157], v[156:157]
	v_rcp_f32_e32 v160, v160
	v_rcp_f32_e32 v161, v161
	v_pk_mul_f32 v[164:165], v[164:165], s[18:19] op_sel_hi:[1,0]
	v_add_f32_e32 v166, v153, v152
	v_exp_f32_e32 v164, v164
	v_pk_fma_f32 v[162:163], v[160:161], s[38:39], v[150:151] op_sel_hi:[1,0,0]
	v_exp_f32_e32 v165, v165
	v_pk_fma_f32 v[162:163], v[160:161], v[162:163], s[10:11] op_sel_hi:[1,1,0]
	v_cvt_pk_bf16_f32 v152, v135, v137
	v_pk_fma_f32 v[162:163], v[160:161], v[162:163], s[56:57] op_sel_hi:[1,1,0]
	v_cvt_pk_bf16_f32 v153, v139, v141
	v_pk_fma_f32 v[162:163], v[160:161], v[162:163], s[64:65] op_sel_hi:[1,1,0]
	s_waitcnt lgkmcnt(0)
; __device__ __forceinline__ float sigm(float v) { return __builtin_amdgcn_rcpf(1.0f + __builtin_amdgcn_exp2f(-1.44269504089f * v)); }
; __device__ __forceinline__ u32x4 pack8(const f32x4& v0, const f32x4& v1) { u32x4 w; w.x = cvt_pk_bf16(v0[0], v0[1]); w.y = cvt_pk_bf16(v0[2], v0[3]); w.z = cvt_pk_bf16(v1[0], v1[1]); w.w = cvt_pk_bf16(v1[2], v1[3]); return w; }
; __device__ __forceinline__ float sumsq8(const f32x4& v0, const f32x4& v1) { return (v0[0] * v0[0] + v0[1] * v0[1]) + (v0[2] * v0[2] + v0[3] * v0[3]) + (v1[0] * v1[0] + v1[1] * v1[1]) + (v1[2] * v1[2] + v1[3] * v1[3]); }
; template <int ACT> __device__ __forceinline__ void epi_act_store(f32x4 (&acc)[2][2][4][2], const float (&rs)[2][4], bf16_t* out, int ld, int row0, int col0, float* ssqv_slot, bool want_ssq, int fq) {
;     ...
;         for (int m = 0; m < 4; ++m) { const int row = row0 + ai * 128 + m * 16; float sq = 0.f;
; #pragma unroll
;             for (int bj = 0; bj < 2; ++bj) { f32x4 v0 = acc[ai][bj][m][0] * rs[ai][m], v1 = acc[ai][bj][m][1] * rs[ai][m];
;                 if (ACT == 1) { f32x2 a = gelu_pk((f32x2){v0[0], v0[1]}), b = gelu_pk((f32x2){v0[2], v0[3]}), c = gelu_pk((f32x2){v1[0], v1[1]}), d = gelu_pk((f32x2){v1[2], v1[3]});
;                     v0 = (f32x4){a.x, a.y, b.x, b.y}; v1 = (f32x4){c.x, c.y, d.x, d.y}; sq += sumsq8(v0, v1); }
;                 if (ACT == 2) {
; #pragma unroll
;                     for (int e = 0; e < 4; ++e) { v0[e] = sigm(v0[e]); v1[e] = sigm(v1[e]); } }
;                 *(u32x4*)(out + (size_t)row * ld + col0 + bj * 128) = pack8(v0, v1); }
;             if (ACT == 1) { if (want_ssq) { sq += __shfl_xor(sq, 16); sq += __shfl_xor(sq, 32); if (fq == 0) ssqv_slot[row] = sq; } } }
	global_store_dwordx4 v[178:179], v[172:175], off offset:256
	v_lshl_add_u64 v[176:177], v[148:149], 0, v[180:181]
	ds_bpermute_b32 v168, v167, v152
	ds_bpermute_b32 v169, v167, v153
	ds_bpermute_b32 v170, v167, v154
	ds_bpermute_b32 v171, v167, v155
	v_pk_mul_f32 v[160:161], v[160:161], v[162:163]
	v_cmp_gt_f32_e32 vcc, 0, v156
	v_pk_mul_f32 v[160:161], v[164:165], v[160:161]
	v_pk_mul_f32 v[154:155], v[104:105], v[0:1] op_sel_hi:[1,0]
	v_pk_mul_f32 v[164:165], v[156:157], v[160:161]
	v_pk_fma_f32 v[160:161], v[156:157], v[160:161], v[156:157] neg_lo:[1,0,0] neg_hi:[1,0,0]
	v_and_b32_e32 v156, 0x7fffffff, v154
	v_cndmask_b32_e32 v135, v160, v164, vcc
	v_cmp_gt_f32_e32 vcc, 0, v157
	v_and_b32_e32 v157, 0x7fffffff, v155
	v_pk_fma_f32 v[156:157], v[156:157], s[14:15], 1.0 op_sel_hi:[1,0,0]
	v_cndmask_b32_e32 v137, v161, v165, vcc
	v_rcp_f32_e32 v156, v156
	v_rcp_f32_e32 v157, v157
	v_pk_mul_f32 v[162:163], v[154:155], v[154:155]
	v_cmp_gt_f32_e32 vcc, 0, v154
	v_pk_mul_f32 v[152:153], v[96:97], v[0:1] op_sel_hi:[1,0]
	v_pk_fma_f32 v[160:161], v[156:157], s[38:39], v[150:151] op_sel_hi:[1,0,0]
	s_nop 0
	v_pk_fma_f32 v[160:161], v[156:157], v[160:161], s[10:11] op_sel_hi:[1,1,0]
	s_nop 0
	v_pk_fma_f32 v[160:161], v[156:157], v[160:161], s[56:57] op_sel_hi:[1,1,0]
	s_nop 0
	v_pk_fma_f32 v[160:161], v[156:157], v[160:161], s[64:65] op_sel_hi:[1,1,0]
	s_nop 0
	v_pk_mul_f32 v[156:157], v[156:157], v[160:161]
	v_pk_mul_f32 v[160:161], v[162:163], s[18:19] op_sel_hi:[1,0]
	s_nop 0
	v_exp_f32_e32 v160, v160
	v_exp_f32_e32 v161, v161
	s_nop 0
	v_pk_mul_f32 v[156:157], v[160:161], v[156:157]
	s_nop 0
	v_pk_mul_f32 v[160:161], v[154:155], v[156:157]
	v_pk_fma_f32 v[156:157], v[154:155], v[156:157], v[154:155] neg_lo:[1,0,0] neg_hi:[1,0,0]
	v_and_b32_e32 v154, 0x7fffffff, v158
	v_cndmask_b32_e32 v139, v156, v160, vcc
	v_cmp_gt_f32_e32 vcc, 0, v155
	v_and_b32_e32 v155, 0x7fffffff, v159
	v_pk_fma_f32 v[154:155], v[154:155], s[14:15], 1.0 op_sel_hi:[1,0,0]
	v_cndmask_b32_e32 v141, v157, v161, vcc
	v_rcp_f32_e32 v154, v154
	v_rcp_f32_e32 v155, v155
	v_pk_mul_f32 v[160:161], v[158:159], v[158:159]
	v_cmp_gt_f32_e32 vcc, 0, v158
	v_pk_mul_f32 v[160:161], v[160:161], s[18:19] op_sel_hi:[1,0]
	v_pk_fma_f32 v[156:157], v[154:155], s[38:39], v[150:151] op_sel_hi:[1,0,0]
	v_exp_f32_e32 v160, v160
	v_pk_fma_f32 v[156:157], v[154:155], v[156:157], s[10:11] op_sel_hi:[1,1,0]
	v_exp_f32_e32 v161, v161
	v_pk_fma_f32 v[156:157], v[154:155], v[156:157], s[56:57] op_sel_hi:[1,1,0]
	s_nop 0
	v_pk_fma_f32 v[156:157], v[154:155], v[156:157], s[64:65] op_sel_hi:[1,1,0]
	s_nop 0
	v_pk_mul_f32 v[154:155], v[154:155], v[156:157]
	v_pk_mul_f32 v[156:157], v[152:153], v[152:153]
	v_pk_mul_f32 v[154:155], v[160:161], v[154:155]
	s_nop 0
	v_pk_mul_f32 v[160:161], v[158:159], v[154:155]
	v_pk_fma_f32 v[154:155], v[158:159], v[154:155], v[158:159] neg_lo:[1,0,0] neg_hi:[1,0,0]
	s_nop 0
	v_cndmask_b32_e32 v143, v154, v160, vcc
	v_cmp_gt_f32_e32 vcc, 0, v159
	v_and_b32_e32 v154, 0x7fffffff, v152
	s_nop 0
	v_cndmask_b32_e32 v158, v155, v161, vcc
	v_and_b32_e32 v155, 0x7fffffff, v153
	v_pk_fma_f32 v[154:155], v[154:155], s[14:15], 1.0 op_sel_hi:[1,0,0]
	v_cmp_gt_f32_e32 vcc, 0, v152
	v_rcp_f32_e32 v154, v154
	v_rcp_f32_e32 v155, v155
	s_nop 0
	v_pk_fma_f32 v[150:151], v[154:155], s[38:39], v[150:151] op_sel_hi:[1,0,0]
	s_nop 0
	v_pk_fma_f32 v[150:151], v[154:155], v[150:151], s[10:11] op_sel_hi:[1,1,0]
	s_nop 0
	v_pk_fma_f32 v[150:151], v[154:155], v[150:151], s[56:57] op_sel_hi:[1,1,0]
	s_nop 0
	v_pk_fma_f32 v[150:151], v[154:155], v[150:151], s[64:65] op_sel_hi:[1,1,0]
	s_nop 0
	v_pk_mul_f32 v[150:151], v[154:155], v[150:151]
	v_pk_mul_f32 v[154:155], v[156:157], s[18:19] op_sel_hi:[1,0]
	s_nop 0
	v_exp_f32_e32 v154, v154
	v_exp_f32_e32 v155, v155
	s_nop 0
	v_pk_mul_f32 v[150:151], v[154:155], v[150:151]
	s_nop 0
	v_pk_mul_f32 v[154:155], v[152:153], v[150:151]
	v_pk_fma_f32 v[150:151], v[152:153], v[150:151], v[152:153] neg_lo:[1,0,0] neg_hi:[1,0,0]
	v_cvt_pk_bf16_f32 v152, v143, v158
	v_cndmask_b32_e32 v154, v150, v154, vcc
	v_cmp_gt_f32_e32 vcc, 0, v153
	v_mul_f32_e32 v150, v137, v137
	v_fmac_f32_e32 v150, v135, v135
	v_cndmask_b32_e32 v153, v151, v155, vcc
	v_mul_f32_e32 v151, v141, v141
	v_fmac_f32_e32 v151, v139, v139
	v_add_f32_e32 v150, v150, v151
	v_mul_f32_e32 v151, v158, v158
	v_fmac_f32_e32 v151, v143, v143
	v_add_f32_e32 v150, v151, v150
	v_mul_f32_e32 v151, v153, v153
	v_fmac_f32_e32 v151, v154, v154
	v_add_f32_e32 v150, v151, v150
	v_add_f32_e32 v155, v166, v150
	v_cvt_pk_bf16_f32 v150, v135, v137
	ds_bpermute_b32 v135, v133, v155
	v_cvt_pk_bf16_f32 v151, v139, v141
	v_cvt_pk_bf16_f32 v153, v154, v153
	s_waitcnt lgkmcnt(0)
	global_store_dwordx4 v[176:177], v[168:171], off
	v_lshl_add_u64 v[178:179], v[148:149], 0, v[180:181]
	ds_bpermute_b32 v172, v167, v150
	ds_bpermute_b32 v173, v167, v151
	ds_bpermute_b32 v174, v167, v152
	ds_bpermute_b32 v175, v167, v153
	s_waitcnt lgkmcnt(0)
	v_add_f32_e32 v135, v155, v135
	ds_bpermute_b32 v137, v131, v135
	s_and_saveexec_b64 s[8:9], s[40:41]
	s_cbranch_execz .LBB0_335
	s_waitcnt lgkmcnt(0)
	v_add_f32_e32 v135, v135, v137
	global_store_dword v[144:145], v135, off offset:64
; __device__ __forceinline__ float sigm(float v) { return __builtin_amdgcn_rcpf(1.0f + __builtin_amdgcn_exp2f(-1.44269504089f * v)); }
; __device__ __forceinline__ u32x4 pack8(const f32x4& v0, const f32x4& v1) { u32x4 w; w.x = cvt_pk_bf16(v0[0], v0[1]); w.y = cvt_pk_bf16(v0[2], v0[3]); w.z = cvt_pk_bf16(v1[0], v1[1]); w.w = cvt_pk_bf16(v1[2], v1[3]); return w; }
; __device__ __forceinline__ float sumsq8(const f32x4& v0, const f32x4& v1) { return (v0[0] * v0[0] + v0[1] * v0[1]) + (v0[2] * v0[2] + v0[3] * v0[3]) + (v1[0] * v1[0] + v1[1] * v1[1]) + (v1[2] * v1[2] + v1[3] * v1[3]); }
; __device__ __forceinline__ f32x2 gelu_pk(f32x2 v) {
;     const f32x2 av = __builtin_elementwise_abs(v), d = av * 0.2316418882f + 1.0f;
;     f32x2 t; t.x = __builtin_amdgcn_rcpf(d.x); t.y = __builtin_amdgcn_rcpf(d.y);
;     f32x2 q = t * 0.5307027145f + (-0.7265760135f); q = q * t + 0.7107068705f; q = q * t + (-0.142248368f); q = q * t + 0.127414796f; q = q * t;
;     const f32x2 s = (v * v) * (-0.72134752044f);
;     f32x2 e; e.x = __builtin_amdgcn_exp2f(s.x); e.y = __builtin_amdgcn_exp2f(s.y);
;     const f32x2 m = v * (q * e), r = v - m;
;     f32x2 o; o.x = v.x < 0.f ? m.x : r.x; o.y = v.y < 0.f ? m.y : r.y; return o;
; }
; template <int ACT> __device__ __forceinline__ void epi_act_store(f32x4 (&acc)[2][2][4][2], const float (&rs)[2][4], bf16_t* out, int ld, int row0, int col0, float* ssqv_slot, bool want_ssq, int fq) {
;     ...
;         for (int m = 0; m < 4; ++m) { const int row = row0 + ai * 128 + m * 16; float sq = 0.f;
; #pragma unroll
;             for (int bj = 0; bj < 2; ++bj) { f32x4 v0 = acc[ai][bj][m][0] * rs[ai][m], v1 = acc[ai][bj][m][1] * rs[ai][m];
;                 if (ACT == 1) { f32x2 a = gelu_pk((f32x2){v0[0], v0[1]}), b = gelu_pk((f32x2){v0[2], v0[3]}), c = gelu_pk((f32x2){v1[0], v1[1]}), d = gelu_pk((f32x2){v1[2], v1[3]});
;                     v0 = (f32x4){a.x, a.y, b.x, b.y}; v1 = (f32x4){c.x, c.y, d.x, d.y}; sq += sumsq8(v0, v1); }
;                 if (ACT == 2) {
; #pragma unroll
;                     for (int e = 0; e < 4; ++e) { v0[e] = sigm(v0[e]); v1[e] = sigm(v1[e]); } }
;                 *(u32x4*)(out + (size_t)row * ld + col0 + bj * 128) = pack8(v0, v1); }
;             if (ACT == 1) { if (want_ssq) { sq += __shfl_xor(sq, 16); sq += __shfl_xor(sq, 32); if (fq == 0) ssqv_slot[row] = sq; } } }
.LBB0_335:
	s_or_b64 exec, exec, s[8:9]
	v_pk_mul_f32 v[156:157], v[98:99], v[132:133] op_sel_hi:[1,0]
	v_or_b32_e32 v135, 32, v210
	v_and_b32_e32 v151, 0x7fffffff, v157
	v_and_b32_e32 v150, 0x7fffffff, v156
	v_pk_fma_f32 v[150:151], v[150:151], s[14:15], 1.0 op_sel_hi:[1,0,0]
	v_pk_mul_f32 v[164:165], v[156:157], v[156:157]
	v_rcp_f32_e32 v160, v150
	v_rcp_f32_e32 v161, v151
	v_mov_b64_e32 v[150:151], s[2:3]
	v_pk_mul_f32 v[164:165], v[164:165], s[18:19] op_sel_hi:[1,0]
	v_pk_mul_f32 v[154:155], v[100:101], v[132:133] op_sel_hi:[1,0]
	v_pk_fma_f32 v[162:163], v[160:161], s[38:39], v[150:151] op_sel_hi:[1,0,0]
	v_exp_f32_e32 v164, v164
	v_pk_fma_f32 v[162:163], v[160:161], v[162:163], s[10:11] op_sel_hi:[1,1,0]
	v_exp_f32_e32 v165, v165
	v_pk_fma_f32 v[162:163], v[160:161], v[162:163], s[56:57] op_sel_hi:[1,1,0]
	v_cmp_gt_f32_e32 vcc, 0, v156
	v_pk_fma_f32 v[162:163], v[160:161], v[162:163], s[64:65] op_sel_hi:[1,1,0]
	v_mad_i64_i32 v[148:149], s[8:9], v135, s69, v[146:147]
	v_pk_mul_f32 v[160:161], v[160:161], v[162:163]
	v_pk_mul_f32 v[162:163], v[154:155], v[154:155]
	v_pk_mul_f32 v[160:161], v[164:165], v[160:161]
	v_pk_mul_f32 v[158:159], v[90:91], v[132:133] op_sel_hi:[1,0]
	v_pk_mul_f32 v[164:165], v[156:157], v[160:161]
	v_pk_fma_f32 v[160:161], v[156:157], v[160:161], v[156:157] neg_lo:[1,0,0] neg_hi:[1,0,0]
	v_and_b32_e32 v156, 0x7fffffff, v154
	v_cndmask_b32_e32 v135, v160, v164, vcc
	v_cmp_gt_f32_e32 vcc, 0, v157
	v_and_b32_e32 v157, 0x7fffffff, v155
	v_pk_fma_f32 v[156:157], v[156:157], s[14:15], 1.0 op_sel_hi:[1,0,0]
	s_waitcnt lgkmcnt(0)
	v_cndmask_b32_e32 v137, v161, v165, vcc
	v_rcp_f32_e32 v156, v156
	v_rcp_f32_e32 v157, v157
	v_cmp_gt_f32_e32 vcc, 0, v154
	v_pk_mul_f32 v[152:153], v[92:93], v[132:133] op_sel_hi:[1,0]
	v_pk_fma_f32 v[160:161], v[156:157], s[38:39], v[150:151] op_sel_hi:[1,0,0]
	s_nop 0
	v_pk_fma_f32 v[160:161], v[156:157], v[160:161], s[10:11] op_sel_hi:[1,1,0]
	s_nop 0
	v_pk_fma_f32 v[160:161], v[156:157], v[160:161], s[56:57] op_sel_hi:[1,1,0]
	s_nop 0
	v_pk_fma_f32 v[160:161], v[156:157], v[160:161], s[64:65] op_sel_hi:[1,1,0]
	s_nop 0
	v_pk_mul_f32 v[156:157], v[156:157], v[160:161]
	v_pk_mul_f32 v[160:161], v[162:163], s[18:19] op_sel_hi:[1,0]
	s_nop 0
	v_exp_f32_e32 v160, v160
	v_exp_f32_e32 v161, v161
	s_nop 0
	v_pk_mul_f32 v[156:157], v[160:161], v[156:157]
	s_nop 0
	v_pk_mul_f32 v[160:161], v[154:155], v[156:157]
	v_pk_fma_f32 v[156:157], v[154:155], v[156:157], v[154:155] neg_lo:[1,0,0] neg_hi:[1,0,0]
	v_and_b32_e32 v154, 0x7fffffff, v158
	v_cndmask_b32_e32 v139, v156, v160, vcc
	v_cmp_gt_f32_e32 vcc, 0, v155
	v_and_b32_e32 v155, 0x7fffffff, v159
	v_pk_fma_f32 v[154:155], v[154:155], s[14:15], 1.0 op_sel_hi:[1,0,0]
	v_cndmask_b32_e32 v141, v157, v161, vcc
	v_rcp_f32_e32 v154, v154
	v_rcp_f32_e32 v155, v155
	v_pk_mul_f32 v[160:161], v[158:159], v[158:159]
	v_cmp_gt_f32_e32 vcc, 0, v158
	v_pk_mul_f32 v[160:161], v[160:161], s[18:19] op_sel_hi:[1,0]
	v_pk_fma_f32 v[156:157], v[154:155], s[38:39], v[150:151] op_sel_hi:[1,0,0]
	v_exp_f32_e32 v160, v160
	v_pk_fma_f32 v[156:157], v[154:155], v[156:157], s[10:11] op_sel_hi:[1,1,0]
	v_exp_f32_e32 v161, v161
	v_pk_fma_f32 v[156:157], v[154:155], v[156:157], s[56:57] op_sel_hi:[1,1,0]
	s_nop 0
	v_pk_fma_f32 v[156:157], v[154:155], v[156:157], s[64:65] op_sel_hi:[1,1,0]
	s_nop 0
	v_pk_mul_f32 v[154:155], v[154:155], v[156:157]
	v_pk_mul_f32 v[156:157], v[152:153], v[152:153]
	v_pk_mul_f32 v[154:155], v[160:161], v[154:155]
	v_pk_mul_f32 v[156:157], v[156:157], s[18:19] op_sel_hi:[1,0]
	v_pk_mul_f32 v[160:161], v[158:159], v[154:155]
	v_pk_fma_f32 v[154:155], v[158:159], v[154:155], v[158:159] neg_lo:[1,0,0] neg_hi:[1,0,0]
	v_exp_f32_e32 v156, v156
	v_cndmask_b32_e32 v143, v154, v160, vcc
	v_cmp_gt_f32_e32 vcc, 0, v159
	v_and_b32_e32 v154, 0x7fffffff, v152
	v_exp_f32_e32 v157, v157
	v_cndmask_b32_e32 v160, v155, v161, vcc
	v_and_b32_e32 v155, 0x7fffffff, v153
	v_pk_fma_f32 v[154:155], v[154:155], s[14:15], 1.0 op_sel_hi:[1,0,0]
	v_cmp_gt_f32_e32 vcc, 0, v152
	v_rcp_f32_e32 v154, v154
	v_rcp_f32_e32 v155, v155
	s_nop 0
	v_pk_fma_f32 v[158:159], v[154:155], s[38:39], v[150:151] op_sel_hi:[1,0,0]
	s_nop 0
	v_pk_fma_f32 v[158:159], v[154:155], v[158:159], s[10:11] op_sel_hi:[1,1,0]
	s_nop 0
	v_pk_fma_f32 v[158:159], v[154:155], v[158:159], s[56:57] op_sel_hi:[1,1,0]
	s_nop 0
	v_pk_fma_f32 v[158:159], v[154:155], v[158:159], s[64:65] op_sel_hi:[1,1,0]
	s_nop 0
	v_pk_mul_f32 v[154:155], v[154:155], v[158:159]
	v_pk_mul_f32 v[158:159], v[78:79], v[132:133] op_sel_hi:[1,0]
	v_pk_mul_f32 v[154:155], v[156:157], v[154:155]
	s_nop 0
	v_pk_mul_f32 v[156:157], v[152:153], v[154:155]
	v_pk_fma_f32 v[154:155], v[152:153], v[154:155], v[152:153] neg_lo:[1,0,0] neg_hi:[1,0,0]
	v_mul_f32_e32 v152, v137, v137
	v_cndmask_b32_e32 v156, v154, v156, vcc
	v_cmp_gt_f32_e32 vcc, 0, v153
	v_mul_f32_e32 v153, v141, v141
	v_fmac_f32_e32 v152, v135, v135
	v_fmac_f32_e32 v153, v139, v139
	v_add_f32_e32 v152, v152, v153
	v_mul_f32_e32 v153, v160, v160
	v_cndmask_b32_e32 v155, v155, v157, vcc
	v_fmac_f32_e32 v153, v143, v143
	v_add_f32_e32 v152, v153, v152
	v_mul_f32_e32 v153, v155, v155
	v_fmac_f32_e32 v153, v156, v156
	v_cvt_pk_bf16_f32 v155, v156, v155
	v_pk_mul_f32 v[156:157], v[86:87], v[132:133] op_sel_hi:[1,0]
	v_cvt_pk_bf16_f32 v154, v143, v160
	v_and_b32_e32 v161, 0x7fffffff, v157
	v_and_b32_e32 v160, 0x7fffffff, v156
	v_pk_fma_f32 v[160:161], v[160:161], s[14:15], 1.0 op_sel_hi:[1,0,0]
	v_pk_mul_f32 v[164:165], v[156:157], v[156:157]
	v_rcp_f32_e32 v160, v160
	v_rcp_f32_e32 v161, v161
	v_pk_mul_f32 v[164:165], v[164:165], s[18:19] op_sel_hi:[1,0]
	v_add_f32_e32 v166, v153, v152
	v_exp_f32_e32 v164, v164
	v_pk_fma_f32 v[162:163], v[160:161], s[38:39], v[150:151] op_sel_hi:[1,0,0]
	v_exp_f32_e32 v165, v165
	v_pk_fma_f32 v[162:163], v[160:161], v[162:163], s[10:11] op_sel_hi:[1,1,0]
	v_cvt_pk_bf16_f32 v152, v135, v137
	v_pk_fma_f32 v[162:163], v[160:161], v[162:163], s[56:57] op_sel_hi:[1,1,0]
	v_cvt_pk_bf16_f32 v153, v139, v141
	v_pk_fma_f32 v[162:163], v[160:161], v[162:163], s[64:65] op_sel_hi:[1,1,0]
	s_waitcnt lgkmcnt(0)
; __device__ __forceinline__ float sigm(float v) { return __builtin_amdgcn_rcpf(1.0f + __builtin_amdgcn_exp2f(-1.44269504089f * v)); }
; __device__ __forceinline__ u32x4 pack8(const f32x4& v0, const f32x4& v1) { u32x4 w; w.x = cvt_pk_bf16(v0[0], v0[1]); w.y = cvt_pk_bf16(v0[2], v0[3]); w.z = cvt_pk_bf16(v1[0], v1[1]); w.w = cvt_pk_bf16(v1[2], v1[3]); return w; }
; __device__ __forceinline__ float sumsq8(const f32x4& v0, const f32x4& v1) { return (v0[0] * v0[0] + v0[1] * v0[1]) + (v0[2] * v0[2] + v0[3] * v0[3]) + (v1[0] * v1[0] + v1[1] * v1[1]) + (v1[2] * v1[2] + v1[3] * v1[3]); }
; template <int ACT> __device__ __forceinline__ void epi_act_store(f32x4 (&acc)[2][2][4][2], const float (&rs)[2][4], bf16_t* out, int ld, int row0, int col0, float* ssqv_slot, bool want_ssq, int fq) {
;     ...
;         for (int m = 0; m < 4; ++m) { const int row = row0 + ai * 128 + m * 16; float sq = 0.f;
; #pragma unroll
;             for (int bj = 0; bj < 2; ++bj) { f32x4 v0 = acc[ai][bj][m][0] * rs[ai][m], v1 = acc[ai][bj][m][1] * rs[ai][m];
;                 if (ACT == 1) { f32x2 a = gelu_pk((f32x2){v0[0], v0[1]}), b = gelu_pk((f32x2){v0[2], v0[3]}), c = gelu_pk((f32x2){v1[0], v1[1]}), d = gelu_pk((f32x2){v1[2], v1[3]});
;                     v0 = (f32x4){a.x, a.y, b.x, b.y}; v1 = (f32x4){c.x, c.y, d.x, d.y}; sq += sumsq8(v0, v1); }
;                 if (ACT == 2) {
; #pragma unroll
;                     for (int e = 0; e < 4; ++e) { v0[e] = sigm(v0[e]); v1[e] = sigm(v1[e]); } }
;                 *(u32x4*)(out + (size_t)row * ld + col0 + bj * 128) = pack8(v0, v1); }
;             if (ACT == 1) { if (want_ssq) { sq += __shfl_xor(sq, 16); sq += __shfl_xor(sq, 32); if (fq == 0) ssqv_slot[row] = sq; } } }
	global_store_dwordx4 v[178:179], v[172:175], off offset:256
	v_lshl_add_u64 v[176:177], v[148:149], 0, v[180:181]
	ds_bpermute_b32 v168, v167, v152
	ds_bpermute_b32 v169, v167, v153
	ds_bpermute_b32 v170, v167, v154
	ds_bpermute_b32 v171, v167, v155
	v_pk_mul_f32 v[160:161], v[160:161], v[162:163]
	v_cmp_gt_f32_e32 vcc, 0, v156
	v_pk_mul_f32 v[160:161], v[164:165], v[160:161]
	v_pk_mul_f32 v[154:155], v[88:89], v[132:133] op_sel_hi:[1,0]
	v_pk_mul_f32 v[164:165], v[156:157], v[160:161]
	v_pk_fma_f32 v[160:161], v[156:157], v[160:161], v[156:157] neg_lo:[1,0,0] neg_hi:[1,0,0]
	v_and_b32_e32 v156, 0x7fffffff, v154
	v_cndmask_b32_e32 v135, v160, v164, vcc
	v_cmp_gt_f32_e32 vcc, 0, v157
	v_and_b32_e32 v157, 0x7fffffff, v155
	v_pk_fma_f32 v[156:157], v[156:157], s[14:15], 1.0 op_sel_hi:[1,0,0]
	v_cndmask_b32_e32 v137, v161, v165, vcc
	v_rcp_f32_e32 v156, v156
	v_rcp_f32_e32 v157, v157
	v_pk_mul_f32 v[162:163], v[154:155], v[154:155]
	v_cmp_gt_f32_e32 vcc, 0, v154
	v_pk_mul_f32 v[152:153], v[80:81], v[132:133] op_sel_hi:[1,0]
	v_pk_fma_f32 v[160:161], v[156:157], s[38:39], v[150:151] op_sel_hi:[1,0,0]
	s_nop 0
	v_pk_fma_f32 v[160:161], v[156:157], v[160:161], s[10:11] op_sel_hi:[1,1,0]
	s_nop 0
	v_pk_fma_f32 v[160:161], v[156:157], v[160:161], s[56:57] op_sel_hi:[1,1,0]
	s_nop 0
	v_pk_fma_f32 v[160:161], v[156:157], v[160:161], s[64:65] op_sel_hi:[1,1,0]
	s_nop 0
	v_pk_mul_f32 v[156:157], v[156:157], v[160:161]
	v_pk_mul_f32 v[160:161], v[162:163], s[18:19] op_sel_hi:[1,0]
	s_nop 0
	v_exp_f32_e32 v160, v160
	v_exp_f32_e32 v161, v161
	s_nop 0
	v_pk_mul_f32 v[156:157], v[160:161], v[156:157]
	s_nop 0
	v_pk_mul_f32 v[160:161], v[154:155], v[156:157]
	v_pk_fma_f32 v[156:157], v[154:155], v[156:157], v[154:155] neg_lo:[1,0,0] neg_hi:[1,0,0]
	v_and_b32_e32 v154, 0x7fffffff, v158
	v_cndmask_b32_e32 v139, v156, v160, vcc
	v_cmp_gt_f32_e32 vcc, 0, v155
	v_and_b32_e32 v155, 0x7fffffff, v159
	v_pk_fma_f32 v[154:155], v[154:155], s[14:15], 1.0 op_sel_hi:[1,0,0]
	v_cndmask_b32_e32 v141, v157, v161, vcc
	v_rcp_f32_e32 v154, v154
	v_rcp_f32_e32 v155, v155
	v_pk_mul_f32 v[160:161], v[158:159], v[158:159]
	v_cmp_gt_f32_e32 vcc, 0, v158
	v_pk_mul_f32 v[160:161], v[160:161], s[18:19] op_sel_hi:[1,0]
	v_pk_fma_f32 v[156:157], v[154:155], s[38:39], v[150:151] op_sel_hi:[1,0,0]
	v_exp_f32_e32 v160, v160
	v_pk_fma_f32 v[156:157], v[154:155], v[156:157], s[10:11] op_sel_hi:[1,1,0]
	v_exp_f32_e32 v161, v161
	v_pk_fma_f32 v[156:157], v[154:155], v[156:157], s[56:57] op_sel_hi:[1,1,0]
	s_nop 0
	v_pk_fma_f32 v[156:157], v[154:155], v[156:157], s[64:65] op_sel_hi:[1,1,0]
	s_nop 0
	v_pk_mul_f32 v[154:155], v[154:155], v[156:157]
	v_pk_mul_f32 v[156:157], v[152:153], v[152:153]
	v_pk_mul_f32 v[154:155], v[160:161], v[154:155]
	s_nop 0
	v_pk_mul_f32 v[160:161], v[158:159], v[154:155]
	v_pk_fma_f32 v[154:155], v[158:159], v[154:155], v[158:159] neg_lo:[1,0,0] neg_hi:[1,0,0]
	s_nop 0
	v_cndmask_b32_e32 v143, v154, v160, vcc
	v_cmp_gt_f32_e32 vcc, 0, v159
	v_and_b32_e32 v154, 0x7fffffff, v152
	s_nop 0
	v_cndmask_b32_e32 v158, v155, v161, vcc
	v_and_b32_e32 v155, 0x7fffffff, v153
	v_pk_fma_f32 v[154:155], v[154:155], s[14:15], 1.0 op_sel_hi:[1,0,0]
	v_cmp_gt_f32_e32 vcc, 0, v152
	v_rcp_f32_e32 v154, v154
	v_rcp_f32_e32 v155, v155
	s_nop 0
	v_pk_fma_f32 v[150:151], v[154:155], s[38:39], v[150:151] op_sel_hi:[1,0,0]
	s_nop 0
	v_pk_fma_f32 v[150:151], v[154:155], v[150:151], s[10:11] op_sel_hi:[1,1,0]
	s_nop 0
	v_pk_fma_f32 v[150:151], v[154:155], v[150:151], s[56:57] op_sel_hi:[1,1,0]
	s_nop 0
	v_pk_fma_f32 v[150:151], v[154:155], v[150:151], s[64:65] op_sel_hi:[1,1,0]
	s_nop 0
	v_pk_mul_f32 v[150:151], v[154:155], v[150:151]
	v_pk_mul_f32 v[154:155], v[156:157], s[18:19] op_sel_hi:[1,0]
	s_nop 0
	v_exp_f32_e32 v154, v154
	v_exp_f32_e32 v155, v155
	s_nop 0
	v_pk_mul_f32 v[150:151], v[154:155], v[150:151]
	s_nop 0
	v_pk_mul_f32 v[154:155], v[152:153], v[150:151]
	v_pk_fma_f32 v[150:151], v[152:153], v[150:151], v[152:153] neg_lo:[1,0,0] neg_hi:[1,0,0]
	v_cvt_pk_bf16_f32 v152, v143, v158
	v_cndmask_b32_e32 v154, v150, v154, vcc
	v_cmp_gt_f32_e32 vcc, 0, v153
	v_mul_f32_e32 v150, v137, v137
	v_fmac_f32_e32 v150, v135, v135
	v_cndmask_b32_e32 v153, v151, v155, vcc
	v_mul_f32_e32 v151, v141, v141
	v_fmac_f32_e32 v151, v139, v139
	v_add_f32_e32 v150, v150, v151
	v_mul_f32_e32 v151, v158, v158
	v_fmac_f32_e32 v151, v143, v143
	v_add_f32_e32 v150, v151, v150
	v_mul_f32_e32 v151, v153, v153
	v_fmac_f32_e32 v151, v154, v154
	v_add_f32_e32 v150, v151, v150
	v_add_f32_e32 v155, v166, v150
	v_cvt_pk_bf16_f32 v150, v135, v137
	ds_bpermute_b32 v135, v133, v155
	v_cvt_pk_bf16_f32 v151, v139, v141
	v_cvt_pk_bf16_f32 v153, v154, v153
	s_waitcnt lgkmcnt(0)
	global_store_dwordx4 v[176:177], v[168:171], off
	v_lshl_add_u64 v[178:179], v[148:149], 0, v[180:181]
	ds_bpermute_b32 v172, v167, v150
	ds_bpermute_b32 v173, v167, v151
	ds_bpermute_b32 v174, v167, v152
	ds_bpermute_b32 v175, v167, v153
	s_waitcnt lgkmcnt(0)
	v_add_f32_e32 v135, v155, v135
	ds_bpermute_b32 v137, v131, v135
	s_and_saveexec_b64 s[8:9], s[40:41]
	s_cbranch_execz .LBB0_337
	s_waitcnt lgkmcnt(0)
	v_add_f32_e32 v135, v135, v137
	global_store_dword v[144:145], v135, off offset:128
; __device__ __forceinline__ float sigm(float v) { return __builtin_amdgcn_rcpf(1.0f + __builtin_amdgcn_exp2f(-1.44269504089f * v)); }
; __device__ __forceinline__ u32x4 pack8(const f32x4& v0, const f32x4& v1) { u32x4 w; w.x = cvt_pk_bf16(v0[0], v0[1]); w.y = cvt_pk_bf16(v0[2], v0[3]); w.z = cvt_pk_bf16(v1[0], v1[1]); w.w = cvt_pk_bf16(v1[2], v1[3]); return w; }
; __device__ __forceinline__ float sumsq8(const f32x4& v0, const f32x4& v1) { return (v0[0] * v0[0] + v0[1] * v0[1]) + (v0[2] * v0[2] + v0[3] * v0[3]) + (v1[0] * v1[0] + v1[1] * v1[1]) + (v1[2] * v1[2] + v1[3] * v1[3]); }
; __device__ __forceinline__ f32x2 gelu_pk(f32x2 v) {
;     const f32x2 av = __builtin_elementwise_abs(v), d = av * 0.2316418882f + 1.0f;
;     f32x2 t; t.x = __builtin_amdgcn_rcpf(d.x); t.y = __builtin_amdgcn_rcpf(d.y);
;     f32x2 q = t * 0.5307027145f + (-0.7265760135f); q = q * t + 0.7107068705f; q = q * t + (-0.142248368f); q = q * t + 0.127414796f; q = q * t;
;     const f32x2 s = (v * v) * (-0.72134752044f);
;     f32x2 e; e.x = __builtin_amdgcn_exp2f(s.x); e.y = __builtin_amdgcn_exp2f(s.y);
;     const f32x2 m = v * (q * e), r = v - m;
;     f32x2 o; o.x = v.x < 0.f ? m.x : r.x; o.y = v.y < 0.f ? m.y : r.y; return o;
; }
; template <int ACT> __device__ __forceinline__ void epi_act_store(f32x4 (&acc)[2][2][4][2], const float (&rs)[2][4], bf16_t* out, int ld, int row0, int col0, float* ssqv_slot, bool want_ssq, int fq) {
;     ...
;         for (int m = 0; m < 4; ++m) { const int row = row0 + ai * 128 + m * 16; float sq = 0.f;
; #pragma unroll
;             for (int bj = 0; bj < 2; ++bj) { f32x4 v0 = acc[ai][bj][m][0] * rs[ai][m], v1 = acc[ai][bj][m][1] * rs[ai][m];
;                 if (ACT == 1) { f32x2 a = gelu_pk((f32x2){v0[0], v0[1]}), b = gelu_pk((f32x2){v0[2], v0[3]}), c = gelu_pk((f32x2){v1[0], v1[1]}), d = gelu_pk((f32x2){v1[2], v1[3]});
;                     v0 = (f32x4){a.x, a.y, b.x, b.y}; v1 = (f32x4){c.x, c.y, d.x, d.y}; sq += sumsq8(v0, v1); }
;                 if (ACT == 2) {
; #pragma unroll
;                     for (int e = 0; e < 4; ++e) { v0[e] = sigm(v0[e]); v1[e] = sigm(v1[e]); } }
;                 *(u32x4*)(out + (size_t)row * ld + col0 + bj * 128) = pack8(v0, v1); }
;             if (ACT == 1) { if (want_ssq) { sq += __shfl_xor(sq, 16); sq += __shfl_xor(sq, 32); if (fq == 0) ssqv_slot[row] = sq; } } }
.LBB0_337:
	s_or_b64 exec, exec, s[8:9]
	v_pk_mul_f32 v[156:157], v[82:83], v[142:143] op_sel_hi:[1,0]
	v_or_b32_e32 v135, 48, v210
	v_and_b32_e32 v151, 0x7fffffff, v157
	v_and_b32_e32 v150, 0x7fffffff, v156
	v_pk_fma_f32 v[150:151], v[150:151], s[14:15], 1.0 op_sel_hi:[1,0,0]
	v_pk_mul_f32 v[164:165], v[156:157], v[156:157]
	v_rcp_f32_e32 v160, v150
	v_rcp_f32_e32 v161, v151
	v_mov_b64_e32 v[150:151], s[2:3]
	v_pk_mul_f32 v[164:165], v[164:165], s[18:19] op_sel_hi:[1,0]
	v_pk_mul_f32 v[154:155], v[84:85], v[142:143] op_sel_hi:[1,0]
	v_pk_fma_f32 v[162:163], v[160:161], s[38:39], v[150:151] op_sel_hi:[1,0,0]
	v_exp_f32_e32 v164, v164
	v_pk_fma_f32 v[162:163], v[160:161], v[162:163], s[10:11] op_sel_hi:[1,1,0]
	v_exp_f32_e32 v165, v165
	v_pk_fma_f32 v[162:163], v[160:161], v[162:163], s[56:57] op_sel_hi:[1,1,0]
	v_cmp_gt_f32_e32 vcc, 0, v156
	v_pk_fma_f32 v[162:163], v[160:161], v[162:163], s[64:65] op_sel_hi:[1,1,0]
	v_mad_i64_i32 v[148:149], s[8:9], v135, s69, v[146:147]
	v_pk_mul_f32 v[160:161], v[160:161], v[162:163]
	v_pk_mul_f32 v[162:163], v[154:155], v[154:155]
	v_pk_mul_f32 v[160:161], v[164:165], v[160:161]
	v_pk_mul_f32 v[158:159], v[74:75], v[142:143] op_sel_hi:[1,0]
	v_pk_mul_f32 v[164:165], v[156:157], v[160:161]
	v_pk_fma_f32 v[160:161], v[156:157], v[160:161], v[156:157] neg_lo:[1,0,0] neg_hi:[1,0,0]
	v_and_b32_e32 v156, 0x7fffffff, v154
	v_cndmask_b32_e32 v135, v160, v164, vcc
	v_cmp_gt_f32_e32 vcc, 0, v157
	v_and_b32_e32 v157, 0x7fffffff, v155
	v_pk_fma_f32 v[156:157], v[156:157], s[14:15], 1.0 op_sel_hi:[1,0,0]
	s_waitcnt lgkmcnt(0)
	v_cndmask_b32_e32 v137, v161, v165, vcc
	v_rcp_f32_e32 v156, v156
	v_rcp_f32_e32 v157, v157
	v_cmp_gt_f32_e32 vcc, 0, v154
	v_pk_mul_f32 v[152:153], v[76:77], v[142:143] op_sel_hi:[1,0]
	v_pk_fma_f32 v[160:161], v[156:157], s[38:39], v[150:151] op_sel_hi:[1,0,0]
	s_nop 0
	v_pk_fma_f32 v[160:161], v[156:157], v[160:161], s[10:11] op_sel_hi:[1,1,0]
	s_nop 0
	v_pk_fma_f32 v[160:161], v[156:157], v[160:161], s[56:57] op_sel_hi:[1,1,0]
	s_nop 0
	v_pk_fma_f32 v[160:161], v[156:157], v[160:161], s[64:65] op_sel_hi:[1,1,0]
	s_nop 0
	v_pk_mul_f32 v[156:157], v[156:157], v[160:161]
	v_pk_mul_f32 v[160:161], v[162:163], s[18:19] op_sel_hi:[1,0]
	s_nop 0
	v_exp_f32_e32 v160, v160
	v_exp_f32_e32 v161, v161
	s_nop 0
	v_pk_mul_f32 v[156:157], v[160:161], v[156:157]
	s_nop 0
	v_pk_mul_f32 v[160:161], v[154:155], v[156:157]
	v_pk_fma_f32 v[156:157], v[154:155], v[156:157], v[154:155] neg_lo:[1,0,0] neg_hi:[1,0,0]
	v_and_b32_e32 v154, 0x7fffffff, v158
	v_cndmask_b32_e32 v139, v156, v160, vcc
	v_cmp_gt_f32_e32 vcc, 0, v155
	v_and_b32_e32 v155, 0x7fffffff, v159
	v_pk_fma_f32 v[154:155], v[154:155], s[14:15], 1.0 op_sel_hi:[1,0,0]
	v_cndmask_b32_e32 v141, v157, v161, vcc
	v_rcp_f32_e32 v154, v154
	v_rcp_f32_e32 v155, v155
	v_pk_mul_f32 v[160:161], v[158:159], v[158:159]
	v_cmp_gt_f32_e32 vcc, 0, v158
	v_pk_mul_f32 v[160:161], v[160:161], s[18:19] op_sel_hi:[1,0]
	v_pk_fma_f32 v[156:157], v[154:155], s[38:39], v[150:151] op_sel_hi:[1,0,0]
	v_exp_f32_e32 v160, v160
	v_pk_fma_f32 v[156:157], v[154:155], v[156:157], s[10:11] op_sel_hi:[1,1,0]
	v_exp_f32_e32 v161, v161
	v_pk_fma_f32 v[156:157], v[154:155], v[156:157], s[56:57] op_sel_hi:[1,1,0]
	s_nop 0
	v_pk_fma_f32 v[156:157], v[154:155], v[156:157], s[64:65] op_sel_hi:[1,1,0]
	s_nop 0
	v_pk_mul_f32 v[154:155], v[154:155], v[156:157]
	v_pk_mul_f32 v[156:157], v[152:153], v[152:153]
	v_pk_mul_f32 v[154:155], v[160:161], v[154:155]
	v_pk_mul_f32 v[156:157], v[156:157], s[18:19] op_sel_hi:[1,0]
	v_pk_mul_f32 v[160:161], v[158:159], v[154:155]
	v_pk_fma_f32 v[154:155], v[158:159], v[154:155], v[158:159] neg_lo:[1,0,0] neg_hi:[1,0,0]
	v_exp_f32_e32 v156, v156
	v_cndmask_b32_e32 v143, v154, v160, vcc
	v_cmp_gt_f32_e32 vcc, 0, v159
	v_and_b32_e32 v154, 0x7fffffff, v152
	v_exp_f32_e32 v157, v157
	v_cndmask_b32_e32 v160, v155, v161, vcc
	v_and_b32_e32 v155, 0x7fffffff, v153
	v_pk_fma_f32 v[154:155], v[154:155], s[14:15], 1.0 op_sel_hi:[1,0,0]
	v_cmp_gt_f32_e32 vcc, 0, v152
	v_rcp_f32_e32 v154, v154
	v_rcp_f32_e32 v155, v155
	s_nop 0
	v_pk_fma_f32 v[158:159], v[154:155], s[38:39], v[150:151] op_sel_hi:[1,0,0]
	s_nop 0
	v_pk_fma_f32 v[158:159], v[154:155], v[158:159], s[10:11] op_sel_hi:[1,1,0]
	s_nop 0
	v_pk_fma_f32 v[158:159], v[154:155], v[158:159], s[56:57] op_sel_hi:[1,1,0]
	s_nop 0
	v_pk_fma_f32 v[158:159], v[154:155], v[158:159], s[64:65] op_sel_hi:[1,1,0]
	s_nop 0
	v_pk_mul_f32 v[154:155], v[154:155], v[158:159]
	v_pk_mul_f32 v[158:159], v[66:67], v[142:143] op_sel_hi:[1,0]
	v_pk_mul_f32 v[154:155], v[156:157], v[154:155]
	s_nop 0
	v_pk_mul_f32 v[156:157], v[152:153], v[154:155]
	v_pk_fma_f32 v[154:155], v[152:153], v[154:155], v[152:153] neg_lo:[1,0,0] neg_hi:[1,0,0]
	v_mul_f32_e32 v152, v137, v137
	v_cndmask_b32_e32 v156, v154, v156, vcc
	v_cmp_gt_f32_e32 vcc, 0, v153
	v_mul_f32_e32 v153, v141, v141
	v_fmac_f32_e32 v152, v135, v135
	v_fmac_f32_e32 v153, v139, v139
	v_add_f32_e32 v152, v152, v153
	v_mul_f32_e32 v153, v160, v160
	v_cndmask_b32_e32 v155, v155, v157, vcc
	v_fmac_f32_e32 v153, v143, v143
	v_add_f32_e32 v152, v153, v152
	v_mul_f32_e32 v153, v155, v155
	v_fmac_f32_e32 v153, v156, v156
	v_cvt_pk_bf16_f32 v155, v156, v155
	v_pk_mul_f32 v[156:157], v[70:71], v[142:143] op_sel_hi:[1,0]
	v_cvt_pk_bf16_f32 v154, v143, v160
	v_and_b32_e32 v161, 0x7fffffff, v157
	v_and_b32_e32 v160, 0x7fffffff, v156
	v_pk_fma_f32 v[160:161], v[160:161], s[14:15], 1.0 op_sel_hi:[1,0,0]
	v_pk_mul_f32 v[164:165], v[156:157], v[156:157]
	v_rcp_f32_e32 v160, v160
	v_rcp_f32_e32 v161, v161
	v_pk_mul_f32 v[164:165], v[164:165], s[18:19] op_sel_hi:[1,0]
	v_add_f32_e32 v166, v153, v152
	v_exp_f32_e32 v164, v164
	v_pk_fma_f32 v[162:163], v[160:161], s[38:39], v[150:151] op_sel_hi:[1,0,0]
	v_exp_f32_e32 v165, v165
	v_pk_fma_f32 v[162:163], v[160:161], v[162:163], s[10:11] op_sel_hi:[1,1,0]
	v_cvt_pk_bf16_f32 v152, v135, v137
	v_pk_fma_f32 v[162:163], v[160:161], v[162:163], s[56:57] op_sel_hi:[1,1,0]
	v_cvt_pk_bf16_f32 v153, v139, v141
	v_pk_fma_f32 v[162:163], v[160:161], v[162:163], s[64:65] op_sel_hi:[1,1,0]
	s_waitcnt lgkmcnt(0)
; __device__ __forceinline__ float sigm(float v) { return __builtin_amdgcn_rcpf(1.0f + __builtin_amdgcn_exp2f(-1.44269504089f * v)); }
; __device__ __forceinline__ u32x4 pack8(const f32x4& v0, const f32x4& v1) { u32x4 w; w.x = cvt_pk_bf16(v0[0], v0[1]); w.y = cvt_pk_bf16(v0[2], v0[3]); w.z = cvt_pk_bf16(v1[0], v1[1]); w.w = cvt_pk_bf16(v1[2], v1[3]); return w; }
; __device__ __forceinline__ float sumsq8(const f32x4& v0, const f32x4& v1) { return (v0[0] * v0[0] + v0[1] * v0[1]) + (v0[2] * v0[2] + v0[3] * v0[3]) + (v1[0] * v1[0] + v1[1] * v1[1]) + (v1[2] * v1[2] + v1[3] * v1[3]); }
; template <int ACT> __device__ __forceinline__ void epi_act_store(f32x4 (&acc)[2][2][4][2], const float (&rs)[2][4], bf16_t* out, int ld, int row0, int col0, float* ssqv_slot, bool want_ssq, int fq) {
;     ...
;         for (int m = 0; m < 4; ++m) { const int row = row0 + ai * 128 + m * 16; float sq = 0.f;
; #pragma unroll
;             for (int bj = 0; bj < 2; ++bj) { f32x4 v0 = acc[ai][bj][m][0] * rs[ai][m], v1 = acc[ai][bj][m][1] * rs[ai][m];
;                 if (ACT == 1) { f32x2 a = gelu_pk((f32x2){v0[0], v0[1]}), b = gelu_pk((f32x2){v0[2], v0[3]}), c = gelu_pk((f32x2){v1[0], v1[1]}), d = gelu_pk((f32x2){v1[2], v1[3]});
;                     v0 = (f32x4){a.x, a.y, b.x, b.y}; v1 = (f32x4){c.x, c.y, d.x, d.y}; sq += sumsq8(v0, v1); }
;                 if (ACT == 2) {
; #pragma unroll
;                     for (int e = 0; e < 4; ++e) { v0[e] = sigm(v0[e]); v1[e] = sigm(v1[e]); } }
;                 *(u32x4*)(out + (size_t)row * ld + col0 + bj * 128) = pack8(v0, v1); }
;             if (ACT == 1) { if (want_ssq) { sq += __shfl_xor(sq, 16); sq += __shfl_xor(sq, 32); if (fq == 0) ssqv_slot[row] = sq; } } }
	global_store_dwordx4 v[178:179], v[172:175], off offset:256
	v_lshl_add_u64 v[176:177], v[148:149], 0, v[180:181]
	ds_bpermute_b32 v168, v167, v152
	ds_bpermute_b32 v169, v167, v153
	ds_bpermute_b32 v170, v167, v154
	ds_bpermute_b32 v171, v167, v155
	v_pk_mul_f32 v[160:161], v[160:161], v[162:163]
	v_cmp_gt_f32_e32 vcc, 0, v156
	v_pk_mul_f32 v[160:161], v[164:165], v[160:161]
	v_pk_mul_f32 v[154:155], v[72:73], v[142:143] op_sel_hi:[1,0]
	v_pk_mul_f32 v[164:165], v[156:157], v[160:161]
	v_pk_fma_f32 v[160:161], v[156:157], v[160:161], v[156:157] neg_lo:[1,0,0] neg_hi:[1,0,0]
	v_and_b32_e32 v156, 0x7fffffff, v154
	v_cndmask_b32_e32 v135, v160, v164, vcc
	v_cmp_gt_f32_e32 vcc, 0, v157
	v_and_b32_e32 v157, 0x7fffffff, v155
	v_pk_fma_f32 v[156:157], v[156:157], s[14:15], 1.0 op_sel_hi:[1,0,0]
	v_cndmask_b32_e32 v137, v161, v165, vcc
	v_rcp_f32_e32 v156, v156
	v_rcp_f32_e32 v157, v157
	v_pk_mul_f32 v[162:163], v[154:155], v[154:155]
	v_cmp_gt_f32_e32 vcc, 0, v154
	v_pk_mul_f32 v[152:153], v[68:69], v[142:143] op_sel_hi:[1,0]
	v_pk_fma_f32 v[160:161], v[156:157], s[38:39], v[150:151] op_sel_hi:[1,0,0]
	s_nop 0
	v_pk_fma_f32 v[160:161], v[156:157], v[160:161], s[10:11] op_sel_hi:[1,1,0]
	s_nop 0
	v_pk_fma_f32 v[160:161], v[156:157], v[160:161], s[56:57] op_sel_hi:[1,1,0]
	s_nop 0
	v_pk_fma_f32 v[160:161], v[156:157], v[160:161], s[64:65] op_sel_hi:[1,1,0]
	s_nop 0
	v_pk_mul_f32 v[156:157], v[156:157], v[160:161]
	v_pk_mul_f32 v[160:161], v[162:163], s[18:19] op_sel_hi:[1,0]
	s_nop 0
	v_exp_f32_e32 v160, v160
	v_exp_f32_e32 v161, v161
	s_nop 0
	v_pk_mul_f32 v[156:157], v[160:161], v[156:157]
	s_nop 0
	v_pk_mul_f32 v[160:161], v[154:155], v[156:157]
	v_pk_fma_f32 v[156:157], v[154:155], v[156:157], v[154:155] neg_lo:[1,0,0] neg_hi:[1,0,0]
	v_and_b32_e32 v154, 0x7fffffff, v158
	v_cndmask_b32_e32 v139, v156, v160, vcc
	v_cmp_gt_f32_e32 vcc, 0, v155
	v_and_b32_e32 v155, 0x7fffffff, v159
	v_pk_fma_f32 v[154:155], v[154:155], s[14:15], 1.0 op_sel_hi:[1,0,0]
	v_cndmask_b32_e32 v141, v157, v161, vcc
	v_rcp_f32_e32 v154, v154
	v_rcp_f32_e32 v155, v155
	v_pk_mul_f32 v[160:161], v[158:159], v[158:159]
	v_cmp_gt_f32_e32 vcc, 0, v158
	v_pk_mul_f32 v[160:161], v[160:161], s[18:19] op_sel_hi:[1,0]
	v_pk_fma_f32 v[156:157], v[154:155], s[38:39], v[150:151] op_sel_hi:[1,0,0]
	v_exp_f32_e32 v160, v160
	v_pk_fma_f32 v[156:157], v[154:155], v[156:157], s[10:11] op_sel_hi:[1,1,0]
	v_exp_f32_e32 v161, v161
	v_pk_fma_f32 v[156:157], v[154:155], v[156:157], s[56:57] op_sel_hi:[1,1,0]
	s_nop 0
	v_pk_fma_f32 v[156:157], v[154:155], v[156:157], s[64:65] op_sel_hi:[1,1,0]
	s_nop 0
	v_pk_mul_f32 v[154:155], v[154:155], v[156:157]
	v_pk_mul_f32 v[156:157], v[152:153], v[152:153]
	v_pk_mul_f32 v[154:155], v[160:161], v[154:155]
	s_nop 0
	v_pk_mul_f32 v[160:161], v[158:159], v[154:155]
	v_pk_fma_f32 v[154:155], v[158:159], v[154:155], v[158:159] neg_lo:[1,0,0] neg_hi:[1,0,0]
	s_nop 0
	v_cndmask_b32_e32 v143, v154, v160, vcc
	v_cmp_gt_f32_e32 vcc, 0, v159
	v_and_b32_e32 v154, 0x7fffffff, v152
	s_nop 0
	v_cndmask_b32_e32 v158, v155, v161, vcc
	v_and_b32_e32 v155, 0x7fffffff, v153
	v_pk_fma_f32 v[154:155], v[154:155], s[14:15], 1.0 op_sel_hi:[1,0,0]
	v_cmp_gt_f32_e32 vcc, 0, v152
	v_rcp_f32_e32 v154, v154
	v_rcp_f32_e32 v155, v155
	s_nop 0
	v_pk_fma_f32 v[150:151], v[154:155], s[38:39], v[150:151] op_sel_hi:[1,0,0]
	s_nop 0
	v_pk_fma_f32 v[150:151], v[154:155], v[150:151], s[10:11] op_sel_hi:[1,1,0]
	s_nop 0
	v_pk_fma_f32 v[150:151], v[154:155], v[150:151], s[56:57] op_sel_hi:[1,1,0]
	s_nop 0
	v_pk_fma_f32 v[150:151], v[154:155], v[150:151], s[64:65] op_sel_hi:[1,1,0]
	s_nop 0
	v_pk_mul_f32 v[150:151], v[154:155], v[150:151]
	v_pk_mul_f32 v[154:155], v[156:157], s[18:19] op_sel_hi:[1,0]
	s_nop 0
	v_exp_f32_e32 v154, v154
	v_exp_f32_e32 v155, v155
	s_nop 0
	v_pk_mul_f32 v[150:151], v[154:155], v[150:151]
	s_nop 0
	v_pk_mul_f32 v[154:155], v[152:153], v[150:151]
	v_pk_fma_f32 v[150:151], v[152:153], v[150:151], v[152:153] neg_lo:[1,0,0] neg_hi:[1,0,0]
	v_cvt_pk_bf16_f32 v152, v143, v158
	v_cndmask_b32_e32 v154, v150, v154, vcc
	v_cmp_gt_f32_e32 vcc, 0, v153
	v_mul_f32_e32 v150, v137, v137
	v_fmac_f32_e32 v150, v135, v135
	v_cndmask_b32_e32 v153, v151, v155, vcc
	v_mul_f32_e32 v151, v141, v141
	v_fmac_f32_e32 v151, v139, v139
	v_add_f32_e32 v150, v150, v151
	v_mul_f32_e32 v151, v158, v158
	v_fmac_f32_e32 v151, v143, v143
	v_add_f32_e32 v150, v151, v150
	v_mul_f32_e32 v151, v153, v153
	v_fmac_f32_e32 v151, v154, v154
	v_add_f32_e32 v150, v151, v150
	v_add_f32_e32 v155, v166, v150
	v_cvt_pk_bf16_f32 v150, v135, v137
	ds_bpermute_b32 v135, v133, v155
	v_cvt_pk_bf16_f32 v151, v139, v141
	v_cvt_pk_bf16_f32 v153, v154, v153
	s_waitcnt lgkmcnt(0)
	global_store_dwordx4 v[176:177], v[168:171], off
	v_lshl_add_u64 v[178:179], v[148:149], 0, v[180:181]
	ds_bpermute_b32 v172, v167, v150
	ds_bpermute_b32 v173, v167, v151
	ds_bpermute_b32 v174, v167, v152
	ds_bpermute_b32 v175, v167, v153
	s_waitcnt lgkmcnt(0)
	v_add_f32_e32 v135, v155, v135
	ds_bpermute_b32 v137, v131, v135
	s_and_saveexec_b64 s[8:9], s[40:41]
	s_cbranch_execz .LBB0_339
	s_waitcnt lgkmcnt(0)
	v_add_f32_e32 v135, v135, v137
	global_store_dword v[144:145], v135, off offset:192
; __device__ __forceinline__ float sigm(float v) { return __builtin_amdgcn_rcpf(1.0f + __builtin_amdgcn_exp2f(-1.44269504089f * v)); }
; __device__ __forceinline__ u32x4 pack8(const f32x4& v0, const f32x4& v1) { u32x4 w; w.x = cvt_pk_bf16(v0[0], v0[1]); w.y = cvt_pk_bf16(v0[2], v0[3]); w.z = cvt_pk_bf16(v1[0], v1[1]); w.w = cvt_pk_bf16(v1[2], v1[3]); return w; }
; __device__ __forceinline__ float sumsq8(const f32x4& v0, const f32x4& v1) { return (v0[0] * v0[0] + v0[1] * v0[1]) + (v0[2] * v0[2] + v0[3] * v0[3]) + (v1[0] * v1[0] + v1[1] * v1[1]) + (v1[2] * v1[2] + v1[3] * v1[3]); }
; __device__ __forceinline__ f32x2 gelu_pk(f32x2 v) {
;     const f32x2 av = __builtin_elementwise_abs(v), d = av * 0.2316418882f + 1.0f;
;     f32x2 t; t.x = __builtin_amdgcn_rcpf(d.x); t.y = __builtin_amdgcn_rcpf(d.y);
;     f32x2 q = t * 0.5307027145f + (-0.7265760135f); q = q * t + 0.7107068705f; q = q * t + (-0.142248368f); q = q * t + 0.127414796f; q = q * t;
;     const f32x2 s = (v * v) * (-0.72134752044f);
;     f32x2 e; e.x = __builtin_amdgcn_exp2f(s.x); e.y = __builtin_amdgcn_exp2f(s.y);
;     const f32x2 m = v * (q * e), r = v - m;
;     f32x2 o; o.x = v.x < 0.f ? m.x : r.x; o.y = v.y < 0.f ? m.y : r.y; return o;
; }
; template <int ACT> __device__ __forceinline__ void epi_act_store(f32x4 (&acc)[2][2][4][2], const float (&rs)[2][4], bf16_t* out, int ld, int row0, int col0, float* ssqv_slot, bool want_ssq, int fq) {
;     ...
;         for (int m = 0; m < 4; ++m) { const int row = row0 + ai * 128 + m * 16; float sq = 0.f;
; #pragma unroll
;             for (int bj = 0; bj < 2; ++bj) { f32x4 v0 = acc[ai][bj][m][0] * rs[ai][m], v1 = acc[ai][bj][m][1] * rs[ai][m];
;                 if (ACT == 1) { f32x2 a = gelu_pk((f32x2){v0[0], v0[1]}), b = gelu_pk((f32x2){v0[2], v0[3]}), c = gelu_pk((f32x2){v1[0], v1[1]}), d = gelu_pk((f32x2){v1[2], v1[3]});
;                     v0 = (f32x4){a.x, a.y, b.x, b.y}; v1 = (f32x4){c.x, c.y, d.x, d.y}; sq += sumsq8(v0, v1); }
;                 if (ACT == 2) {
; #pragma unroll
;                     for (int e = 0; e < 4; ++e) { v0[e] = sigm(v0[e]); v1[e] = sigm(v1[e]); } }
;                 *(u32x4*)(out + (size_t)row * ld + col0 + bj * 128) = pack8(v0, v1); }
;             if (ACT == 1) { if (want_ssq) { sq += __shfl_xor(sq, 16); sq += __shfl_xor(sq, 32); if (fq == 0) ssqv_slot[row] = sq; } } }
.LBB0_339:
	s_or_b64 exec, exec, s[8:9]
	v_pk_mul_f32 v[156:157], v[62:63], v[140:141] op_sel_hi:[1,0]
	v_add_u32_e32 v135, 0x80, v210
	v_and_b32_e32 v151, 0x7fffffff, v157
	v_and_b32_e32 v150, 0x7fffffff, v156
	v_pk_fma_f32 v[150:151], v[150:151], s[14:15], 1.0 op_sel_hi:[1,0,0]
	v_pk_mul_f32 v[164:165], v[156:157], v[156:157]
	v_rcp_f32_e32 v160, v150
	v_rcp_f32_e32 v161, v151
	v_mov_b64_e32 v[150:151], s[2:3]
	v_pk_mul_f32 v[164:165], v[164:165], s[18:19] op_sel_hi:[1,0]
	v_pk_mul_f32 v[154:155], v[64:65], v[140:141] op_sel_hi:[1,0]
	v_pk_fma_f32 v[162:163], v[160:161], s[38:39], v[150:151] op_sel_hi:[1,0,0]
	v_exp_f32_e32 v164, v164
	v_pk_fma_f32 v[162:163], v[160:161], v[162:163], s[10:11] op_sel_hi:[1,1,0]
	v_exp_f32_e32 v165, v165
	v_pk_fma_f32 v[162:163], v[160:161], v[162:163], s[56:57] op_sel_hi:[1,1,0]
	v_cmp_gt_f32_e32 vcc, 0, v156
	v_pk_fma_f32 v[162:163], v[160:161], v[162:163], s[64:65] op_sel_hi:[1,1,0]
	v_mad_i64_i32 v[148:149], s[8:9], v135, s69, v[146:147]
	v_pk_mul_f32 v[160:161], v[160:161], v[162:163]
	v_pk_mul_f32 v[162:163], v[154:155], v[154:155]
	v_pk_mul_f32 v[160:161], v[164:165], v[160:161]
	v_pk_mul_f32 v[158:159], v[58:59], v[140:141] op_sel_hi:[1,0]
	v_pk_mul_f32 v[164:165], v[156:157], v[160:161]
	v_pk_fma_f32 v[160:161], v[156:157], v[160:161], v[156:157] neg_lo:[1,0,0] neg_hi:[1,0,0]
	v_and_b32_e32 v156, 0x7fffffff, v154
	v_cndmask_b32_e32 v135, v160, v164, vcc
	v_cmp_gt_f32_e32 vcc, 0, v157
	v_and_b32_e32 v157, 0x7fffffff, v155
	v_pk_fma_f32 v[156:157], v[156:157], s[14:15], 1.0 op_sel_hi:[1,0,0]
	s_waitcnt lgkmcnt(0)
	v_cndmask_b32_e32 v137, v161, v165, vcc
	v_rcp_f32_e32 v156, v156
	v_rcp_f32_e32 v157, v157
	v_cmp_gt_f32_e32 vcc, 0, v154
	v_pk_mul_f32 v[152:153], v[60:61], v[140:141] op_sel_hi:[1,0]
	v_pk_fma_f32 v[160:161], v[156:157], s[38:39], v[150:151] op_sel_hi:[1,0,0]
	s_nop 0
	v_pk_fma_f32 v[160:161], v[156:157], v[160:161], s[10:11] op_sel_hi:[1,1,0]
	s_nop 0
	v_pk_fma_f32 v[160:161], v[156:157], v[160:161], s[56:57] op_sel_hi:[1,1,0]
	s_nop 0
	v_pk_fma_f32 v[160:161], v[156:157], v[160:161], s[64:65] op_sel_hi:[1,1,0]
	s_nop 0
	v_pk_mul_f32 v[156:157], v[156:157], v[160:161]
	v_pk_mul_f32 v[160:161], v[162:163], s[18:19] op_sel_hi:[1,0]
	s_nop 0
	v_exp_f32_e32 v160, v160
	v_exp_f32_e32 v161, v161
	s_nop 0
	v_pk_mul_f32 v[156:157], v[160:161], v[156:157]
	s_nop 0
	v_pk_mul_f32 v[160:161], v[154:155], v[156:157]
	v_pk_fma_f32 v[156:157], v[154:155], v[156:157], v[154:155] neg_lo:[1,0,0] neg_hi:[1,0,0]
	v_and_b32_e32 v154, 0x7fffffff, v158
	v_cndmask_b32_e32 v139, v156, v160, vcc
	v_cmp_gt_f32_e32 vcc, 0, v155
	v_and_b32_e32 v155, 0x7fffffff, v159
	v_pk_fma_f32 v[154:155], v[154:155], s[14:15], 1.0 op_sel_hi:[1,0,0]
	v_cndmask_b32_e32 v141, v157, v161, vcc
	v_rcp_f32_e32 v154, v154
	v_rcp_f32_e32 v155, v155
	v_pk_mul_f32 v[160:161], v[158:159], v[158:159]
	v_cmp_gt_f32_e32 vcc, 0, v158
	v_pk_mul_f32 v[160:161], v[160:161], s[18:19] op_sel_hi:[1,0]
	v_pk_fma_f32 v[156:157], v[154:155], s[38:39], v[150:151] op_sel_hi:[1,0,0]
	v_exp_f32_e32 v160, v160
	v_pk_fma_f32 v[156:157], v[154:155], v[156:157], s[10:11] op_sel_hi:[1,1,0]
	v_exp_f32_e32 v161, v161
	v_pk_fma_f32 v[156:157], v[154:155], v[156:157], s[56:57] op_sel_hi:[1,1,0]
	s_nop 0
	v_pk_fma_f32 v[156:157], v[154:155], v[156:157], s[64:65] op_sel_hi:[1,1,0]
	s_nop 0
	v_pk_mul_f32 v[154:155], v[154:155], v[156:157]
	v_pk_mul_f32 v[156:157], v[152:153], v[152:153]
	v_pk_mul_f32 v[154:155], v[160:161], v[154:155]
	v_pk_mul_f32 v[156:157], v[156:157], s[18:19] op_sel_hi:[1,0]
	v_pk_mul_f32 v[160:161], v[158:159], v[154:155]
	v_pk_fma_f32 v[154:155], v[158:159], v[154:155], v[158:159] neg_lo:[1,0,0] neg_hi:[1,0,0]
	v_exp_f32_e32 v156, v156
	v_cndmask_b32_e32 v143, v154, v160, vcc
	v_cmp_gt_f32_e32 vcc, 0, v159
	v_and_b32_e32 v154, 0x7fffffff, v152
	v_exp_f32_e32 v157, v157
	v_cndmask_b32_e32 v160, v155, v161, vcc
	v_and_b32_e32 v155, 0x7fffffff, v153
	v_pk_fma_f32 v[154:155], v[154:155], s[14:15], 1.0 op_sel_hi:[1,0,0]
	v_cmp_gt_f32_e32 vcc, 0, v152
	v_rcp_f32_e32 v154, v154
	v_rcp_f32_e32 v155, v155
	s_nop 0
	v_pk_fma_f32 v[158:159], v[154:155], s[38:39], v[150:151] op_sel_hi:[1,0,0]
	s_nop 0
	v_pk_fma_f32 v[158:159], v[154:155], v[158:159], s[10:11] op_sel_hi:[1,1,0]
	s_nop 0
	v_pk_fma_f32 v[158:159], v[154:155], v[158:159], s[56:57] op_sel_hi:[1,1,0]
	s_nop 0
	v_pk_fma_f32 v[158:159], v[154:155], v[158:159], s[64:65] op_sel_hi:[1,1,0]
	s_nop 0
	v_pk_mul_f32 v[154:155], v[154:155], v[158:159]
	v_pk_mul_f32 v[158:159], v[50:51], v[140:141] op_sel_hi:[1,0]
	v_pk_mul_f32 v[154:155], v[156:157], v[154:155]
	s_nop 0
	v_pk_mul_f32 v[156:157], v[152:153], v[154:155]
	v_pk_fma_f32 v[154:155], v[152:153], v[154:155], v[152:153] neg_lo:[1,0,0] neg_hi:[1,0,0]
	v_mul_f32_e32 v152, v137, v137
	v_cndmask_b32_e32 v156, v154, v156, vcc
	v_cmp_gt_f32_e32 vcc, 0, v153
	v_mul_f32_e32 v153, v141, v141
	v_fmac_f32_e32 v152, v135, v135
	v_fmac_f32_e32 v153, v139, v139
	v_add_f32_e32 v152, v152, v153
	v_mul_f32_e32 v153, v160, v160
	v_cndmask_b32_e32 v155, v155, v157, vcc
	v_fmac_f32_e32 v153, v143, v143
	v_add_f32_e32 v152, v153, v152
	v_mul_f32_e32 v153, v155, v155
	v_fmac_f32_e32 v153, v156, v156
	v_cvt_pk_bf16_f32 v155, v156, v155
	v_pk_mul_f32 v[156:157], v[54:55], v[140:141] op_sel_hi:[1,0]
	v_cvt_pk_bf16_f32 v154, v143, v160
	v_and_b32_e32 v161, 0x7fffffff, v157
	v_and_b32_e32 v160, 0x7fffffff, v156
	v_pk_fma_f32 v[160:161], v[160:161], s[14:15], 1.0 op_sel_hi:[1,0,0]
	v_pk_mul_f32 v[164:165], v[156:157], v[156:157]
	v_rcp_f32_e32 v160, v160
	v_rcp_f32_e32 v161, v161
	v_pk_mul_f32 v[164:165], v[164:165], s[18:19] op_sel_hi:[1,0]
	v_add_f32_e32 v166, v153, v152
	v_exp_f32_e32 v164, v164
	v_pk_fma_f32 v[162:163], v[160:161], s[38:39], v[150:151] op_sel_hi:[1,0,0]
	v_exp_f32_e32 v165, v165
	v_pk_fma_f32 v[162:163], v[160:161], v[162:163], s[10:11] op_sel_hi:[1,1,0]
	v_cvt_pk_bf16_f32 v152, v135, v137
	v_pk_fma_f32 v[162:163], v[160:161], v[162:163], s[56:57] op_sel_hi:[1,1,0]
	v_cvt_pk_bf16_f32 v153, v139, v141
	v_pk_fma_f32 v[162:163], v[160:161], v[162:163], s[64:65] op_sel_hi:[1,1,0]
	s_waitcnt lgkmcnt(0)
; __device__ __forceinline__ float sigm(float v) { return __builtin_amdgcn_rcpf(1.0f + __builtin_amdgcn_exp2f(-1.44269504089f * v)); }
; __device__ __forceinline__ u32x4 pack8(const f32x4& v0, const f32x4& v1) { u32x4 w; w.x = cvt_pk_bf16(v0[0], v0[1]); w.y = cvt_pk_bf16(v0[2], v0[3]); w.z = cvt_pk_bf16(v1[0], v1[1]); w.w = cvt_pk_bf16(v1[2], v1[3]); return w; }
; __device__ __forceinline__ float sumsq8(const f32x4& v0, const f32x4& v1) { return (v0[0] * v0[0] + v0[1] * v0[1]) + (v0[2] * v0[2] + v0[3] * v0[3]) + (v1[0] * v1[0] + v1[1] * v1[1]) + (v1[2] * v1[2] + v1[3] * v1[3]); }
; __device__ __forceinline__ f32x2 gelu_pk(f32x2 v) {
;     const f32x2 av = __builtin_elementwise_abs(v), d = av * 0.2316418882f + 1.0f;
;     f32x2 t; t.x = __builtin_amdgcn_rcpf(d.x); t.y = __builtin_amdgcn_rcpf(d.y);
;     f32x2 q = t * 0.5307027145f + (-0.7265760135f); q = q * t + 0.7107068705f; q = q * t + (-0.142248368f); q = q * t + 0.127414796f; q = q * t;
;     const f32x2 s = (v * v) * (-0.72134752044f);
;     f32x2 e; e.x = __builtin_amdgcn_exp2f(s.x); e.y = __builtin_amdgcn_exp2f(s.y);
;     const f32x2 m = v * (q * e), r = v - m;
;     f32x2 o; o.x = v.x < 0.f ? m.x : r.x; o.y = v.y < 0.f ? m.y : r.y; return o;
; }
; template <int ACT> __device__ __forceinline__ void epi_act_store(f32x4 (&acc)[2][2][4][2], const float (&rs)[2][4], bf16_t* out, int ld, int row0, int col0, float* ssqv_slot, bool want_ssq, int fq) {
;     ...
;         for (int m = 0; m < 4; ++m) { const int row = row0 + ai * 128 + m * 16; float sq = 0.f;
; #pragma unroll
;             for (int bj = 0; bj < 2; ++bj) { f32x4 v0 = acc[ai][bj][m][0] * rs[ai][m], v1 = acc[ai][bj][m][1] * rs[ai][m];
;                 if (ACT == 1) { f32x2 a = gelu_pk((f32x2){v0[0], v0[1]}), b = gelu_pk((f32x2){v0[2], v0[3]}), c = gelu_pk((f32x2){v1[0], v1[1]}), d = gelu_pk((f32x2){v1[2], v1[3]});
;                     v0 = (f32x4){a.x, a.y, b.x, b.y}; v1 = (f32x4){c.x, c.y, d.x, d.y}; sq += sumsq8(v0, v1); }
;                 if (ACT == 2) {
; #pragma unroll
;                     for (int e = 0; e < 4; ++e) { v0[e] = sigm(v0[e]); v1[e] = sigm(v1[e]); } }
;                 *(u32x4*)(out + (size_t)row * ld + col0 + bj * 128) = pack8(v0, v1); }
;             if (ACT == 1) { if (want_ssq) { sq += __shfl_xor(sq, 16); sq += __shfl_xor(sq, 32); if (fq == 0) ssqv_slot[row] = sq; } } }
	global_store_dwordx4 v[178:179], v[172:175], off offset:256
	v_lshl_add_u64 v[176:177], v[148:149], 0, v[180:181]
	ds_bpermute_b32 v168, v167, v152
	ds_bpermute_b32 v169, v167, v153
	ds_bpermute_b32 v170, v167, v154
	ds_bpermute_b32 v171, v167, v155
	v_pk_mul_f32 v[160:161], v[160:161], v[162:163]
	v_cmp_gt_f32_e32 vcc, 0, v156
	v_pk_mul_f32 v[160:161], v[164:165], v[160:161]
	v_pk_mul_f32 v[154:155], v[56:57], v[140:141] op_sel_hi:[1,0]
	v_pk_mul_f32 v[164:165], v[156:157], v[160:161]
	v_pk_fma_f32 v[160:161], v[156:157], v[160:161], v[156:157] neg_lo:[1,0,0] neg_hi:[1,0,0]
	v_and_b32_e32 v156, 0x7fffffff, v154
	v_cndmask_b32_e32 v135, v160, v164, vcc
	v_cmp_gt_f32_e32 vcc, 0, v157
	v_and_b32_e32 v157, 0x7fffffff, v155
	v_pk_fma_f32 v[156:157], v[156:157], s[14:15], 1.0 op_sel_hi:[1,0,0]
	v_cndmask_b32_e32 v137, v161, v165, vcc
	v_rcp_f32_e32 v156, v156
	v_rcp_f32_e32 v157, v157
	v_pk_mul_f32 v[162:163], v[154:155], v[154:155]
	v_cmp_gt_f32_e32 vcc, 0, v154
	v_pk_mul_f32 v[152:153], v[52:53], v[140:141] op_sel_hi:[1,0]
	v_pk_fma_f32 v[160:161], v[156:157], s[38:39], v[150:151] op_sel_hi:[1,0,0]
	s_nop 0
	v_pk_fma_f32 v[160:161], v[156:157], v[160:161], s[10:11] op_sel_hi:[1,1,0]
	s_nop 0
	v_pk_fma_f32 v[160:161], v[156:157], v[160:161], s[56:57] op_sel_hi:[1,1,0]
	s_nop 0
	v_pk_fma_f32 v[160:161], v[156:157], v[160:161], s[64:65] op_sel_hi:[1,1,0]
	s_nop 0
	v_pk_mul_f32 v[156:157], v[156:157], v[160:161]
	v_pk_mul_f32 v[160:161], v[162:163], s[18:19] op_sel_hi:[1,0]
	s_nop 0
	v_exp_f32_e32 v160, v160
	v_exp_f32_e32 v161, v161
	s_nop 0
	v_pk_mul_f32 v[156:157], v[160:161], v[156:157]
	s_nop 0
	v_pk_mul_f32 v[160:161], v[154:155], v[156:157]
	v_pk_fma_f32 v[156:157], v[154:155], v[156:157], v[154:155] neg_lo:[1,0,0] neg_hi:[1,0,0]
	v_and_b32_e32 v154, 0x7fffffff, v158
	v_cndmask_b32_e32 v139, v156, v160, vcc
	v_cmp_gt_f32_e32 vcc, 0, v155
	v_and_b32_e32 v155, 0x7fffffff, v159
	v_pk_fma_f32 v[154:155], v[154:155], s[14:15], 1.0 op_sel_hi:[1,0,0]
	v_cndmask_b32_e32 v141, v157, v161, vcc
	v_rcp_f32_e32 v154, v154
	v_rcp_f32_e32 v155, v155
	v_pk_mul_f32 v[160:161], v[158:159], v[158:159]
	v_cmp_gt_f32_e32 vcc, 0, v158
	v_pk_mul_f32 v[160:161], v[160:161], s[18:19] op_sel_hi:[1,0]
	v_pk_fma_f32 v[156:157], v[154:155], s[38:39], v[150:151] op_sel_hi:[1,0,0]
	v_exp_f32_e32 v160, v160
	v_pk_fma_f32 v[156:157], v[154:155], v[156:157], s[10:11] op_sel_hi:[1,1,0]
	v_exp_f32_e32 v161, v161
	v_pk_fma_f32 v[156:157], v[154:155], v[156:157], s[56:57] op_sel_hi:[1,1,0]
	s_nop 0
	v_pk_fma_f32 v[156:157], v[154:155], v[156:157], s[64:65] op_sel_hi:[1,1,0]
	s_nop 0
	v_pk_mul_f32 v[154:155], v[154:155], v[156:157]
	v_pk_mul_f32 v[156:157], v[152:153], v[152:153]
	v_pk_mul_f32 v[154:155], v[160:161], v[154:155]
	s_nop 0
	v_pk_mul_f32 v[160:161], v[158:159], v[154:155]
	v_pk_fma_f32 v[154:155], v[158:159], v[154:155], v[158:159] neg_lo:[1,0,0] neg_hi:[1,0,0]
	s_nop 0
	v_cndmask_b32_e32 v143, v154, v160, vcc
	v_cmp_gt_f32_e32 vcc, 0, v159
	v_and_b32_e32 v154, 0x7fffffff, v152
	s_nop 0
	v_cndmask_b32_e32 v158, v155, v161, vcc
	v_and_b32_e32 v155, 0x7fffffff, v153
	v_pk_fma_f32 v[154:155], v[154:155], s[14:15], 1.0 op_sel_hi:[1,0,0]
	v_cmp_gt_f32_e32 vcc, 0, v152
	v_rcp_f32_e32 v154, v154
	v_rcp_f32_e32 v155, v155
	s_nop 0
	v_pk_fma_f32 v[150:151], v[154:155], s[38:39], v[150:151] op_sel_hi:[1,0,0]
	s_nop 0
	v_pk_fma_f32 v[150:151], v[154:155], v[150:151], s[10:11] op_sel_hi:[1,1,0]
	s_nop 0
	v_pk_fma_f32 v[150:151], v[154:155], v[150:151], s[56:57] op_sel_hi:[1,1,0]
	s_nop 0
	v_pk_fma_f32 v[150:151], v[154:155], v[150:151], s[64:65] op_sel_hi:[1,1,0]
	s_nop 0
	v_pk_mul_f32 v[150:151], v[154:155], v[150:151]
	v_pk_mul_f32 v[154:155], v[156:157], s[18:19] op_sel_hi:[1,0]
	s_nop 0
	v_exp_f32_e32 v154, v154
	v_exp_f32_e32 v155, v155
	s_nop 0
	v_pk_mul_f32 v[150:151], v[154:155], v[150:151]
	s_nop 0
	v_pk_mul_f32 v[154:155], v[152:153], v[150:151]
	v_pk_fma_f32 v[150:151], v[152:153], v[150:151], v[152:153] neg_lo:[1,0,0] neg_hi:[1,0,0]
	v_cvt_pk_bf16_f32 v152, v143, v158
	v_cndmask_b32_e32 v154, v150, v154, vcc
	v_cmp_gt_f32_e32 vcc, 0, v153
	v_mul_f32_e32 v150, v137, v137
	v_fmac_f32_e32 v150, v135, v135
	v_cndmask_b32_e32 v153, v151, v155, vcc
	v_mul_f32_e32 v151, v141, v141
	v_fmac_f32_e32 v151, v139, v139
	v_add_f32_e32 v150, v150, v151
	v_mul_f32_e32 v151, v158, v158
	v_fmac_f32_e32 v151, v143, v143
	v_add_f32_e32 v150, v151, v150
	v_mul_f32_e32 v151, v153, v153
	v_fmac_f32_e32 v151, v154, v154
	v_add_f32_e32 v150, v151, v150
	v_add_f32_e32 v155, v166, v150
	v_cvt_pk_bf16_f32 v150, v135, v137
	ds_bpermute_b32 v135, v133, v155
	v_cvt_pk_bf16_f32 v151, v139, v141
	v_cvt_pk_bf16_f32 v153, v154, v153
	s_waitcnt lgkmcnt(0)
	global_store_dwordx4 v[176:177], v[168:171], off
	v_lshl_add_u64 v[178:179], v[148:149], 0, v[180:181]
	ds_bpermute_b32 v172, v167, v150
	ds_bpermute_b32 v173, v167, v151
	ds_bpermute_b32 v174, v167, v152
	ds_bpermute_b32 v175, v167, v153
	s_waitcnt lgkmcnt(0)
	v_add_f32_e32 v135, v155, v135
	ds_bpermute_b32 v137, v131, v135
	s_and_saveexec_b64 s[8:9], s[40:41]
	s_cbranch_execz .LBB0_341
	s_waitcnt lgkmcnt(0)
	v_add_f32_e32 v135, v135, v137
	global_store_dword v[144:145], v135, off offset:512
; __device__ __forceinline__ float sigm(float v) { return __builtin_amdgcn_rcpf(1.0f + __builtin_amdgcn_exp2f(-1.44269504089f * v)); }
; __device__ __forceinline__ u32x4 pack8(const f32x4& v0, const f32x4& v1) { u32x4 w; w.x = cvt_pk_bf16(v0[0], v0[1]); w.y = cvt_pk_bf16(v0[2], v0[3]); w.z = cvt_pk_bf16(v1[0], v1[1]); w.w = cvt_pk_bf16(v1[2], v1[3]); return w; }
; __device__ __forceinline__ float sumsq8(const f32x4& v0, const f32x4& v1) { return (v0[0] * v0[0] + v0[1] * v0[1]) + (v0[2] * v0[2] + v0[3] * v0[3]) + (v1[0] * v1[0] + v1[1] * v1[1]) + (v1[2] * v1[2] + v1[3] * v1[3]); }
; __device__ __forceinline__ f32x2 gelu_pk(f32x2 v) {
;     const f32x2 av = __builtin_elementwise_abs(v), d = av * 0.2316418882f + 1.0f;
;     f32x2 t; t.x = __builtin_amdgcn_rcpf(d.x); t.y = __builtin_amdgcn_rcpf(d.y);
;     f32x2 q = t * 0.5307027145f + (-0.7265760135f); q = q * t + 0.7107068705f; q = q * t + (-0.142248368f); q = q * t + 0.127414796f; q = q * t;
;     const f32x2 s = (v * v) * (-0.72134752044f);
;     f32x2 e; e.x = __builtin_amdgcn_exp2f(s.x); e.y = __builtin_amdgcn_exp2f(s.y);
;     const f32x2 m = v * (q * e), r = v - m;
;     f32x2 o; o.x = v.x < 0.f ? m.x : r.x; o.y = v.y < 0.f ? m.y : r.y; return o;
; }
; template <int ACT> __device__ __forceinline__ void epi_act_store(f32x4 (&acc)[2][2][4][2], const float (&rs)[2][4], bf16_t* out, int ld, int row0, int col0, float* ssqv_slot, bool want_ssq, int fq) {
;     ...
;         for (int m = 0; m < 4; ++m) { const int row = row0 + ai * 128 + m * 16; float sq = 0.f;
; #pragma unroll
;             for (int bj = 0; bj < 2; ++bj) { f32x4 v0 = acc[ai][bj][m][0] * rs[ai][m], v1 = acc[ai][bj][m][1] * rs[ai][m];
;                 if (ACT == 1) { f32x2 a = gelu_pk((f32x2){v0[0], v0[1]}), b = gelu_pk((f32x2){v0[2], v0[3]}), c = gelu_pk((f32x2){v1[0], v1[1]}), d = gelu_pk((f32x2){v1[2], v1[3]});
;                     v0 = (f32x4){a.x, a.y, b.x, b.y}; v1 = (f32x4){c.x, c.y, d.x, d.y}; sq += sumsq8(v0, v1); }
;                 if (ACT == 2) {
; #pragma unroll
;                     for (int e = 0; e < 4; ++e) { v0[e] = sigm(v0[e]); v1[e] = sigm(v1[e]); } }
;                 *(u32x4*)(out + (size_t)row * ld + col0 + bj * 128) = pack8(v0, v1); }
;             if (ACT == 1) { if (want_ssq) { sq += __shfl_xor(sq, 16); sq += __shfl_xor(sq, 32); if (fq == 0) ssqv_slot[row] = sq; } } }
.LBB0_341:
	s_or_b64 exec, exec, s[8:9]
	v_pk_mul_f32 v[156:157], v[46:47], v[138:139] op_sel_hi:[1,0]
	v_add_u32_e32 v135, 0x90, v210
	v_and_b32_e32 v151, 0x7fffffff, v157
	v_and_b32_e32 v150, 0x7fffffff, v156
	v_pk_fma_f32 v[150:151], v[150:151], s[14:15], 1.0 op_sel_hi:[1,0,0]
	v_pk_mul_f32 v[164:165], v[156:157], v[156:157]
	v_rcp_f32_e32 v160, v150
	v_rcp_f32_e32 v161, v151
	v_mov_b64_e32 v[150:151], s[2:3]
	v_pk_mul_f32 v[164:165], v[164:165], s[18:19] op_sel_hi:[1,0]
	v_pk_mul_f32 v[154:155], v[48:49], v[138:139] op_sel_hi:[1,0]
	v_pk_fma_f32 v[162:163], v[160:161], s[38:39], v[150:151] op_sel_hi:[1,0,0]
	v_exp_f32_e32 v164, v164
	v_pk_fma_f32 v[162:163], v[160:161], v[162:163], s[10:11] op_sel_hi:[1,1,0]
	v_exp_f32_e32 v165, v165
	v_pk_fma_f32 v[162:163], v[160:161], v[162:163], s[56:57] op_sel_hi:[1,1,0]
	v_cmp_gt_f32_e32 vcc, 0, v156
	v_pk_fma_f32 v[162:163], v[160:161], v[162:163], s[64:65] op_sel_hi:[1,1,0]
	v_mad_i64_i32 v[148:149], s[8:9], v135, s69, v[146:147]
	v_pk_mul_f32 v[160:161], v[160:161], v[162:163]
	v_pk_mul_f32 v[162:163], v[154:155], v[154:155]
	v_pk_mul_f32 v[160:161], v[164:165], v[160:161]
	v_pk_mul_f32 v[158:159], v[42:43], v[138:139] op_sel_hi:[1,0]
	v_pk_mul_f32 v[164:165], v[156:157], v[160:161]
	v_pk_fma_f32 v[160:161], v[156:157], v[160:161], v[156:157] neg_lo:[1,0,0] neg_hi:[1,0,0]
	v_and_b32_e32 v156, 0x7fffffff, v154
	v_cndmask_b32_e32 v135, v160, v164, vcc
	v_cmp_gt_f32_e32 vcc, 0, v157
	v_and_b32_e32 v157, 0x7fffffff, v155
	v_pk_fma_f32 v[156:157], v[156:157], s[14:15], 1.0 op_sel_hi:[1,0,0]
	s_waitcnt lgkmcnt(0)
	v_cndmask_b32_e32 v137, v161, v165, vcc
	v_rcp_f32_e32 v156, v156
	v_rcp_f32_e32 v157, v157
	v_cmp_gt_f32_e32 vcc, 0, v154
	v_pk_mul_f32 v[152:153], v[44:45], v[138:139] op_sel_hi:[1,0]
	v_pk_fma_f32 v[160:161], v[156:157], s[38:39], v[150:151] op_sel_hi:[1,0,0]
	s_nop 0
	v_pk_fma_f32 v[160:161], v[156:157], v[160:161], s[10:11] op_sel_hi:[1,1,0]
	s_nop 0
	v_pk_fma_f32 v[160:161], v[156:157], v[160:161], s[56:57] op_sel_hi:[1,1,0]
	s_nop 0
	v_pk_fma_f32 v[160:161], v[156:157], v[160:161], s[64:65] op_sel_hi:[1,1,0]
	s_nop 0
	v_pk_mul_f32 v[156:157], v[156:157], v[160:161]
	v_pk_mul_f32 v[160:161], v[162:163], s[18:19] op_sel_hi:[1,0]
	s_nop 0
	v_exp_f32_e32 v160, v160
	v_exp_f32_e32 v161, v161
	s_nop 0
	v_pk_mul_f32 v[156:157], v[160:161], v[156:157]
	s_nop 0
	v_pk_mul_f32 v[160:161], v[154:155], v[156:157]
	v_pk_fma_f32 v[156:157], v[154:155], v[156:157], v[154:155] neg_lo:[1,0,0] neg_hi:[1,0,0]
	v_and_b32_e32 v154, 0x7fffffff, v158
	v_cndmask_b32_e32 v139, v156, v160, vcc
	v_cmp_gt_f32_e32 vcc, 0, v155
	v_and_b32_e32 v155, 0x7fffffff, v159
	v_pk_fma_f32 v[154:155], v[154:155], s[14:15], 1.0 op_sel_hi:[1,0,0]
	v_cndmask_b32_e32 v141, v157, v161, vcc
	v_rcp_f32_e32 v154, v154
	v_rcp_f32_e32 v155, v155
	v_pk_mul_f32 v[160:161], v[158:159], v[158:159]
	v_cmp_gt_f32_e32 vcc, 0, v158
	v_pk_mul_f32 v[160:161], v[160:161], s[18:19] op_sel_hi:[1,0]
	v_pk_fma_f32 v[156:157], v[154:155], s[38:39], v[150:151] op_sel_hi:[1,0,0]
	v_exp_f32_e32 v160, v160
	v_pk_fma_f32 v[156:157], v[154:155], v[156:157], s[10:11] op_sel_hi:[1,1,0]
	v_exp_f32_e32 v161, v161
	v_pk_fma_f32 v[156:157], v[154:155], v[156:157], s[56:57] op_sel_hi:[1,1,0]
	s_nop 0
	v_pk_fma_f32 v[156:157], v[154:155], v[156:157], s[64:65] op_sel_hi:[1,1,0]
	s_nop 0
	v_pk_mul_f32 v[154:155], v[154:155], v[156:157]
	v_pk_mul_f32 v[156:157], v[152:153], v[152:153]
	v_pk_mul_f32 v[154:155], v[160:161], v[154:155]
	v_pk_mul_f32 v[156:157], v[156:157], s[18:19] op_sel_hi:[1,0]
	v_pk_mul_f32 v[160:161], v[158:159], v[154:155]
	v_pk_fma_f32 v[154:155], v[158:159], v[154:155], v[158:159] neg_lo:[1,0,0] neg_hi:[1,0,0]
	v_exp_f32_e32 v156, v156
	v_cndmask_b32_e32 v143, v154, v160, vcc
	v_cmp_gt_f32_e32 vcc, 0, v159
	v_and_b32_e32 v154, 0x7fffffff, v152
	v_exp_f32_e32 v157, v157
	v_cndmask_b32_e32 v160, v155, v161, vcc
	v_and_b32_e32 v155, 0x7fffffff, v153
	v_pk_fma_f32 v[154:155], v[154:155], s[14:15], 1.0 op_sel_hi:[1,0,0]
	v_cmp_gt_f32_e32 vcc, 0, v152
	v_rcp_f32_e32 v154, v154
	v_rcp_f32_e32 v155, v155
	s_nop 0
	v_pk_fma_f32 v[158:159], v[154:155], s[38:39], v[150:151] op_sel_hi:[1,0,0]
	s_nop 0
	v_pk_fma_f32 v[158:159], v[154:155], v[158:159], s[10:11] op_sel_hi:[1,1,0]
	s_nop 0
	v_pk_fma_f32 v[158:159], v[154:155], v[158:159], s[56:57] op_sel_hi:[1,1,0]
	s_nop 0
	v_pk_fma_f32 v[158:159], v[154:155], v[158:159], s[64:65] op_sel_hi:[1,1,0]
	s_nop 0
	v_pk_mul_f32 v[154:155], v[154:155], v[158:159]
	v_pk_mul_f32 v[158:159], v[34:35], v[138:139] op_sel_hi:[1,0]
	v_pk_mul_f32 v[154:155], v[156:157], v[154:155]
	s_nop 0
	v_pk_mul_f32 v[156:157], v[152:153], v[154:155]
	v_pk_fma_f32 v[154:155], v[152:153], v[154:155], v[152:153] neg_lo:[1,0,0] neg_hi:[1,0,0]
	v_mul_f32_e32 v152, v137, v137
	v_cndmask_b32_e32 v156, v154, v156, vcc
	v_cmp_gt_f32_e32 vcc, 0, v153
	v_mul_f32_e32 v153, v141, v141
	v_fmac_f32_e32 v152, v135, v135
	v_fmac_f32_e32 v153, v139, v139
	v_add_f32_e32 v152, v152, v153
	v_mul_f32_e32 v153, v160, v160
	v_cndmask_b32_e32 v155, v155, v157, vcc
	v_fmac_f32_e32 v153, v143, v143
	v_add_f32_e32 v152, v153, v152
	v_mul_f32_e32 v153, v155, v155
	v_fmac_f32_e32 v153, v156, v156
	v_cvt_pk_bf16_f32 v155, v156, v155
	v_pk_mul_f32 v[156:157], v[38:39], v[138:139] op_sel_hi:[1,0]
	v_cvt_pk_bf16_f32 v154, v143, v160
	v_and_b32_e32 v161, 0x7fffffff, v157
	v_and_b32_e32 v160, 0x7fffffff, v156
	v_pk_fma_f32 v[160:161], v[160:161], s[14:15], 1.0 op_sel_hi:[1,0,0]
	v_pk_mul_f32 v[164:165], v[156:157], v[156:157]
	v_rcp_f32_e32 v160, v160
	v_rcp_f32_e32 v161, v161
	v_pk_mul_f32 v[164:165], v[164:165], s[18:19] op_sel_hi:[1,0]
	v_add_f32_e32 v166, v153, v152
	v_exp_f32_e32 v164, v164
	v_pk_fma_f32 v[162:163], v[160:161], s[38:39], v[150:151] op_sel_hi:[1,0,0]
	v_exp_f32_e32 v165, v165
	v_pk_fma_f32 v[162:163], v[160:161], v[162:163], s[10:11] op_sel_hi:[1,1,0]
	v_cvt_pk_bf16_f32 v152, v135, v137
	v_pk_fma_f32 v[162:163], v[160:161], v[162:163], s[56:57] op_sel_hi:[1,1,0]
	v_cvt_pk_bf16_f32 v153, v139, v141
	v_pk_fma_f32 v[162:163], v[160:161], v[162:163], s[64:65] op_sel_hi:[1,1,0]
	s_waitcnt lgkmcnt(0)
; __device__ __forceinline__ float sigm(float v) { return __builtin_amdgcn_rcpf(1.0f + __builtin_amdgcn_exp2f(-1.44269504089f * v)); }
; __device__ __forceinline__ u32x4 pack8(const f32x4& v0, const f32x4& v1) { u32x4 w; w.x = cvt_pk_bf16(v0[0], v0[1]); w.y = cvt_pk_bf16(v0[2], v0[3]); w.z = cvt_pk_bf16(v1[0], v1[1]); w.w = cvt_pk_bf16(v1[2], v1[3]); return w; }
; __device__ __forceinline__ float sumsq8(const f32x4& v0, const f32x4& v1) { return (v0[0] * v0[0] + v0[1] * v0[1]) + (v0[2] * v0[2] + v0[3] * v0[3]) + (v1[0] * v1[0] + v1[1] * v1[1]) + (v1[2] * v1[2] + v1[3] * v1[3]); }
; __device__ __forceinline__ f32x2 gelu_pk(f32x2 v) {
;     const f32x2 av = __builtin_elementwise_abs(v), d = av * 0.2316418882f + 1.0f;
;     f32x2 t; t.x = __builtin_amdgcn_rcpf(d.x); t.y = __builtin_amdgcn_rcpf(d.y);
;     f32x2 q = t * 0.5307027145f + (-0.7265760135f); q = q * t + 0.7107068705f; q = q * t + (-0.142248368f); q = q * t + 0.127414796f; q = q * t;
;     const f32x2 s = (v * v) * (-0.72134752044f);
;     f32x2 e; e.x = __builtin_amdgcn_exp2f(s.x); e.y = __builtin_amdgcn_exp2f(s.y);
;     const f32x2 m = v * (q * e), r = v - m;
;     f32x2 o; o.x = v.x < 0.f ? m.x : r.x; o.y = v.y < 0.f ? m.y : r.y; return o;
; }
; template <int ACT> __device__ __forceinline__ void epi_act_store(f32x4 (&acc)[2][2][4][2], const float (&rs)[2][4], bf16_t* out, int ld, int row0, int col0, float* ssqv_slot, bool want_ssq, int fq) {
;     ...
;         for (int m = 0; m < 4; ++m) { const int row = row0 + ai * 128 + m * 16; float sq = 0.f;
; #pragma unroll
;             for (int bj = 0; bj < 2; ++bj) { f32x4 v0 = acc[ai][bj][m][0] * rs[ai][m], v1 = acc[ai][bj][m][1] * rs[ai][m];
;                 if (ACT == 1) { f32x2 a = gelu_pk((f32x2){v0[0], v0[1]}), b = gelu_pk((f32x2){v0[2], v0[3]}), c = gelu_pk((f32x2){v1[0], v1[1]}), d = gelu_pk((f32x2){v1[2], v1[3]});
;                     v0 = (f32x4){a.x, a.y, b.x, b.y}; v1 = (f32x4){c.x, c.y, d.x, d.y}; sq += sumsq8(v0, v1); }
;                 if (ACT == 2) {
; #pragma unroll
;                     for (int e = 0; e < 4; ++e) { v0[e] = sigm(v0[e]); v1[e] = sigm(v1[e]); } }
;                 *(u32x4*)(out + (size_t)row * ld + col0 + bj * 128) = pack8(v0, v1); }
;             if (ACT == 1) { if (want_ssq) { sq += __shfl_xor(sq, 16); sq += __shfl_xor(sq, 32); if (fq == 0) ssqv_slot[row] = sq; } } }
	global_store_dwordx4 v[178:179], v[172:175], off offset:256
	v_lshl_add_u64 v[176:177], v[148:149], 0, v[180:181]
	ds_bpermute_b32 v168, v167, v152
	ds_bpermute_b32 v169, v167, v153
	ds_bpermute_b32 v170, v167, v154
	ds_bpermute_b32 v171, v167, v155
	v_pk_mul_f32 v[160:161], v[160:161], v[162:163]
	v_cmp_gt_f32_e32 vcc, 0, v156
	v_pk_mul_f32 v[160:161], v[164:165], v[160:161]
	v_pk_mul_f32 v[154:155], v[40:41], v[138:139] op_sel_hi:[1,0]
	v_pk_mul_f32 v[164:165], v[156:157], v[160:161]
	v_pk_fma_f32 v[160:161], v[156:157], v[160:161], v[156:157] neg_lo:[1,0,0] neg_hi:[1,0,0]
	v_and_b32_e32 v156, 0x7fffffff, v154
	v_cndmask_b32_e32 v135, v160, v164, vcc
	v_cmp_gt_f32_e32 vcc, 0, v157
	v_and_b32_e32 v157, 0x7fffffff, v155
	v_pk_fma_f32 v[156:157], v[156:157], s[14:15], 1.0 op_sel_hi:[1,0,0]
	v_cndmask_b32_e32 v137, v161, v165, vcc
	v_rcp_f32_e32 v156, v156
	v_rcp_f32_e32 v157, v157
	v_pk_mul_f32 v[162:163], v[154:155], v[154:155]
	v_cmp_gt_f32_e32 vcc, 0, v154
	v_pk_mul_f32 v[152:153], v[36:37], v[138:139] op_sel_hi:[1,0]
	v_pk_fma_f32 v[160:161], v[156:157], s[38:39], v[150:151] op_sel_hi:[1,0,0]
	s_nop 0
	v_pk_fma_f32 v[160:161], v[156:157], v[160:161], s[10:11] op_sel_hi:[1,1,0]
	s_nop 0
	v_pk_fma_f32 v[160:161], v[156:157], v[160:161], s[56:57] op_sel_hi:[1,1,0]
	s_nop 0
	v_pk_fma_f32 v[160:161], v[156:157], v[160:161], s[64:65] op_sel_hi:[1,1,0]
	s_nop 0
	v_pk_mul_f32 v[156:157], v[156:157], v[160:161]
	v_pk_mul_f32 v[160:161], v[162:163], s[18:19] op_sel_hi:[1,0]
	s_nop 0
	v_exp_f32_e32 v160, v160
	v_exp_f32_e32 v161, v161
	s_nop 0
	v_pk_mul_f32 v[156:157], v[160:161], v[156:157]
	s_nop 0
	v_pk_mul_f32 v[160:161], v[154:155], v[156:157]
	v_pk_fma_f32 v[156:157], v[154:155], v[156:157], v[154:155] neg_lo:[1,0,0] neg_hi:[1,0,0]
	v_and_b32_e32 v154, 0x7fffffff, v158
	v_cndmask_b32_e32 v139, v156, v160, vcc
	v_cmp_gt_f32_e32 vcc, 0, v155
	v_and_b32_e32 v155, 0x7fffffff, v159
	v_pk_fma_f32 v[154:155], v[154:155], s[14:15], 1.0 op_sel_hi:[1,0,0]
	v_cndmask_b32_e32 v141, v157, v161, vcc
	v_rcp_f32_e32 v154, v154
	v_rcp_f32_e32 v155, v155
	v_pk_mul_f32 v[160:161], v[158:159], v[158:159]
	v_cmp_gt_f32_e32 vcc, 0, v158
	v_pk_mul_f32 v[160:161], v[160:161], s[18:19] op_sel_hi:[1,0]
	v_pk_fma_f32 v[156:157], v[154:155], s[38:39], v[150:151] op_sel_hi:[1,0,0]
	v_exp_f32_e32 v160, v160
	v_pk_fma_f32 v[156:157], v[154:155], v[156:157], s[10:11] op_sel_hi:[1,1,0]
	v_exp_f32_e32 v161, v161
	v_pk_fma_f32 v[156:157], v[154:155], v[156:157], s[56:57] op_sel_hi:[1,1,0]
	s_nop 0
	v_pk_fma_f32 v[156:157], v[154:155], v[156:157], s[64:65] op_sel_hi:[1,1,0]
	s_nop 0
	v_pk_mul_f32 v[154:155], v[154:155], v[156:157]
	v_pk_mul_f32 v[156:157], v[152:153], v[152:153]
	v_pk_mul_f32 v[154:155], v[160:161], v[154:155]
	s_nop 0
	v_pk_mul_f32 v[160:161], v[158:159], v[154:155]
	v_pk_fma_f32 v[154:155], v[158:159], v[154:155], v[158:159] neg_lo:[1,0,0] neg_hi:[1,0,0]
	s_nop 0
	v_cndmask_b32_e32 v143, v154, v160, vcc
	v_cmp_gt_f32_e32 vcc, 0, v159
	v_and_b32_e32 v154, 0x7fffffff, v152
	s_nop 0
	v_cndmask_b32_e32 v158, v155, v161, vcc
	v_and_b32_e32 v155, 0x7fffffff, v153
	v_pk_fma_f32 v[154:155], v[154:155], s[14:15], 1.0 op_sel_hi:[1,0,0]
	v_cmp_gt_f32_e32 vcc, 0, v152
	v_rcp_f32_e32 v154, v154
	v_rcp_f32_e32 v155, v155
	s_nop 0
	v_pk_fma_f32 v[150:151], v[154:155], s[38:39], v[150:151] op_sel_hi:[1,0,0]
	s_nop 0
	v_pk_fma_f32 v[150:151], v[154:155], v[150:151], s[10:11] op_sel_hi:[1,1,0]
	s_nop 0
	v_pk_fma_f32 v[150:151], v[154:155], v[150:151], s[56:57] op_sel_hi:[1,1,0]
	s_nop 0
	v_pk_fma_f32 v[150:151], v[154:155], v[150:151], s[64:65] op_sel_hi:[1,1,0]
	s_nop 0
	v_pk_mul_f32 v[150:151], v[154:155], v[150:151]
	v_pk_mul_f32 v[154:155], v[156:157], s[18:19] op_sel_hi:[1,0]
	s_nop 0
	v_exp_f32_e32 v154, v154
	v_exp_f32_e32 v155, v155
	s_nop 0
	v_pk_mul_f32 v[150:151], v[154:155], v[150:151]
	s_nop 0
	v_pk_mul_f32 v[154:155], v[152:153], v[150:151]
	v_pk_fma_f32 v[150:151], v[152:153], v[150:151], v[152:153] neg_lo:[1,0,0] neg_hi:[1,0,0]
	v_cvt_pk_bf16_f32 v152, v143, v158
	v_cndmask_b32_e32 v154, v150, v154, vcc
	v_cmp_gt_f32_e32 vcc, 0, v153
	v_mul_f32_e32 v150, v137, v137
	v_fmac_f32_e32 v150, v135, v135
	v_cndmask_b32_e32 v153, v151, v155, vcc
	v_mul_f32_e32 v151, v141, v141
	v_fmac_f32_e32 v151, v139, v139
	v_add_f32_e32 v150, v150, v151
	v_mul_f32_e32 v151, v158, v158
	v_fmac_f32_e32 v151, v143, v143
	v_add_f32_e32 v150, v151, v150
	v_mul_f32_e32 v151, v153, v153
	v_fmac_f32_e32 v151, v154, v154
	v_add_f32_e32 v150, v151, v150
	v_add_f32_e32 v155, v166, v150
	v_cvt_pk_bf16_f32 v150, v135, v137
	ds_bpermute_b32 v135, v133, v155
	v_cvt_pk_bf16_f32 v151, v139, v141
	v_cvt_pk_bf16_f32 v153, v154, v153
	s_waitcnt lgkmcnt(0)
	global_store_dwordx4 v[176:177], v[168:171], off
	v_lshl_add_u64 v[178:179], v[148:149], 0, v[180:181]
	ds_bpermute_b32 v172, v167, v150
	ds_bpermute_b32 v173, v167, v151
	ds_bpermute_b32 v174, v167, v152
	ds_bpermute_b32 v175, v167, v153
	s_waitcnt lgkmcnt(0)
	v_add_f32_e32 v135, v155, v135
	ds_bpermute_b32 v137, v131, v135
	s_and_saveexec_b64 s[8:9], s[40:41]
	s_cbranch_execz .LBB0_343
	s_waitcnt lgkmcnt(0)
	v_add_f32_e32 v135, v135, v137
	global_store_dword v[144:145], v135, off offset:576
; __device__ __forceinline__ float sigm(float v) { return __builtin_amdgcn_rcpf(1.0f + __builtin_amdgcn_exp2f(-1.44269504089f * v)); }
; __device__ __forceinline__ u32x4 pack8(const f32x4& v0, const f32x4& v1) { u32x4 w; w.x = cvt_pk_bf16(v0[0], v0[1]); w.y = cvt_pk_bf16(v0[2], v0[3]); w.z = cvt_pk_bf16(v1[0], v1[1]); w.w = cvt_pk_bf16(v1[2], v1[3]); return w; }
; __device__ __forceinline__ float sumsq8(const f32x4& v0, const f32x4& v1) { return (v0[0] * v0[0] + v0[1] * v0[1]) + (v0[2] * v0[2] + v0[3] * v0[3]) + (v1[0] * v1[0] + v1[1] * v1[1]) + (v1[2] * v1[2] + v1[3] * v1[3]); }
; __device__ __forceinline__ f32x2 gelu_pk(f32x2 v) {
;     const f32x2 av = __builtin_elementwise_abs(v), d = av * 0.2316418882f + 1.0f;
;     f32x2 t; t.x = __builtin_amdgcn_rcpf(d.x); t.y = __builtin_amdgcn_rcpf(d.y);
;     f32x2 q = t * 0.5307027145f + (-0.7265760135f); q = q * t + 0.7107068705f; q = q * t + (-0.142248368f); q = q * t + 0.127414796f; q = q * t;
;     const f32x2 s = (v * v) * (-0.72134752044f);
;     f32x2 e; e.x = __builtin_amdgcn_exp2f(s.x); e.y = __builtin_amdgcn_exp2f(s.y);
;     const f32x2 m = v * (q * e), r = v - m;
;     f32x2 o; o.x = v.x < 0.f ? m.x : r.x; o.y = v.y < 0.f ? m.y : r.y; return o;
; }
; template <int ACT> __device__ __forceinline__ void epi_act_store(f32x4 (&acc)[2][2][4][2], const float (&rs)[2][4], bf16_t* out, int ld, int row0, int col0, float* ssqv_slot, bool want_ssq, int fq) {
;     ...
;         for (int m = 0; m < 4; ++m) { const int row = row0 + ai * 128 + m * 16; float sq = 0.f;
; #pragma unroll
;             for (int bj = 0; bj < 2; ++bj) { f32x4 v0 = acc[ai][bj][m][0] * rs[ai][m], v1 = acc[ai][bj][m][1] * rs[ai][m];
;                 if (ACT == 1) { f32x2 a = gelu_pk((f32x2){v0[0], v0[1]}), b = gelu_pk((f32x2){v0[2], v0[3]}), c = gelu_pk((f32x2){v1[0], v1[1]}), d = gelu_pk((f32x2){v1[2], v1[3]});
;                     v0 = (f32x4){a.x, a.y, b.x, b.y}; v1 = (f32x4){c.x, c.y, d.x, d.y}; sq += sumsq8(v0, v1); }
;                 if (ACT == 2) {
; #pragma unroll
;                     for (int e = 0; e < 4; ++e) { v0[e] = sigm(v0[e]); v1[e] = sigm(v1[e]); } }
;                 *(u32x4*)(out + (size_t)row * ld + col0 + bj * 128) = pack8(v0, v1); }
;             if (ACT == 1) { if (want_ssq) { sq += __shfl_xor(sq, 16); sq += __shfl_xor(sq, 32); if (fq == 0) ssqv_slot[row] = sq; } } }
.LBB0_343:
	s_or_b64 exec, exec, s[8:9]
	v_add_u32_e32 v135, 0xa0, v210
	v_pk_mul_f32 v[156:157], v[30:31], v[134:135] op_sel_hi:[1,0]
	v_pk_mul_f32 v[154:155], v[32:33], v[134:135] op_sel_hi:[1,0]
	v_and_b32_e32 v151, 0x7fffffff, v157
	v_and_b32_e32 v150, 0x7fffffff, v156
	v_pk_fma_f32 v[150:151], v[150:151], s[14:15], 1.0 op_sel_hi:[1,0,0]
	v_pk_mul_f32 v[164:165], v[156:157], v[156:157]
	v_rcp_f32_e32 v160, v150
	v_rcp_f32_e32 v161, v151
	v_mov_b64_e32 v[150:151], s[2:3]
	v_pk_mul_f32 v[164:165], v[164:165], s[18:19] op_sel_hi:[1,0]
	v_cmp_gt_f32_e32 vcc, 0, v156
	v_pk_fma_f32 v[162:163], v[160:161], s[38:39], v[150:151] op_sel_hi:[1,0,0]
	v_exp_f32_e32 v164, v164
	v_pk_fma_f32 v[162:163], v[160:161], v[162:163], s[10:11] op_sel_hi:[1,1,0]
	v_exp_f32_e32 v165, v165
	v_pk_fma_f32 v[162:163], v[160:161], v[162:163], s[56:57] op_sel_hi:[1,1,0]
	v_mad_i64_i32 v[148:149], s[8:9], v135, s69, v[146:147]
	v_pk_fma_f32 v[162:163], v[160:161], v[162:163], s[64:65] op_sel_hi:[1,1,0]
	v_pk_mul_f32 v[152:153], v[28:29], v[134:135] op_sel_hi:[1,0]
	v_pk_mul_f32 v[160:161], v[160:161], v[162:163]
	v_pk_mul_f32 v[158:159], v[26:27], v[134:135] op_sel_hi:[1,0]
	v_pk_mul_f32 v[160:161], v[164:165], v[160:161]
	v_pk_mul_f32 v[162:163], v[154:155], v[154:155]
	v_pk_mul_f32 v[164:165], v[156:157], v[160:161]
	v_pk_fma_f32 v[160:161], v[156:157], v[160:161], v[156:157] neg_lo:[1,0,0] neg_hi:[1,0,0]
	v_and_b32_e32 v156, 0x7fffffff, v154
	v_cndmask_b32_e32 v135, v160, v164, vcc
	v_cmp_gt_f32_e32 vcc, 0, v157
	v_and_b32_e32 v157, 0x7fffffff, v155
	v_pk_fma_f32 v[156:157], v[156:157], s[14:15], 1.0 op_sel_hi:[1,0,0]
	s_waitcnt lgkmcnt(0)
	v_cndmask_b32_e32 v137, v161, v165, vcc
	v_rcp_f32_e32 v156, v156
	v_rcp_f32_e32 v157, v157
	v_cmp_gt_f32_e32 vcc, 0, v154
	v_pk_fma_f32 v[160:161], v[156:157], s[38:39], v[150:151] op_sel_hi:[1,0,0]
	s_nop 0
	v_pk_fma_f32 v[160:161], v[156:157], v[160:161], s[10:11] op_sel_hi:[1,1,0]
	s_nop 0
	v_pk_fma_f32 v[160:161], v[156:157], v[160:161], s[56:57] op_sel_hi:[1,1,0]
	s_nop 0
	v_pk_fma_f32 v[160:161], v[156:157], v[160:161], s[64:65] op_sel_hi:[1,1,0]
	s_nop 0
	v_pk_mul_f32 v[156:157], v[156:157], v[160:161]
	v_pk_mul_f32 v[160:161], v[162:163], s[18:19] op_sel_hi:[1,0]
	s_nop 0
	v_exp_f32_e32 v160, v160
	v_exp_f32_e32 v161, v161
	s_nop 0
	v_pk_mul_f32 v[156:157], v[160:161], v[156:157]
	s_nop 0
	v_pk_mul_f32 v[160:161], v[154:155], v[156:157]
	v_pk_fma_f32 v[156:157], v[154:155], v[156:157], v[154:155] neg_lo:[1,0,0] neg_hi:[1,0,0]
	v_and_b32_e32 v154, 0x7fffffff, v158
	v_cndmask_b32_e32 v139, v156, v160, vcc
	v_cmp_gt_f32_e32 vcc, 0, v155
	v_and_b32_e32 v155, 0x7fffffff, v159
	v_pk_fma_f32 v[154:155], v[154:155], s[14:15], 1.0 op_sel_hi:[1,0,0]
	v_cndmask_b32_e32 v141, v157, v161, vcc
	v_rcp_f32_e32 v154, v154
	v_rcp_f32_e32 v155, v155
	v_pk_mul_f32 v[160:161], v[158:159], v[158:159]
	v_cmp_gt_f32_e32 vcc, 0, v158
	v_pk_mul_f32 v[160:161], v[160:161], s[18:19] op_sel_hi:[1,0]
	v_pk_fma_f32 v[156:157], v[154:155], s[38:39], v[150:151] op_sel_hi:[1,0,0]
	v_exp_f32_e32 v160, v160
	v_pk_fma_f32 v[156:157], v[154:155], v[156:157], s[10:11] op_sel_hi:[1,1,0]
	v_exp_f32_e32 v161, v161
	v_pk_fma_f32 v[156:157], v[154:155], v[156:157], s[56:57] op_sel_hi:[1,1,0]
	s_nop 0
	v_pk_fma_f32 v[156:157], v[154:155], v[156:157], s[64:65] op_sel_hi:[1,1,0]
	s_nop 0
	v_pk_mul_f32 v[154:155], v[154:155], v[156:157]
	v_pk_mul_f32 v[156:157], v[152:153], v[152:153]
	v_pk_mul_f32 v[154:155], v[160:161], v[154:155]
	v_pk_mul_f32 v[156:157], v[156:157], s[18:19] op_sel_hi:[1,0]
	v_pk_mul_f32 v[160:161], v[158:159], v[154:155]
	v_pk_fma_f32 v[154:155], v[158:159], v[154:155], v[158:159] neg_lo:[1,0,0] neg_hi:[1,0,0]
	v_exp_f32_e32 v156, v156
	v_cndmask_b32_e32 v143, v154, v160, vcc
	v_cmp_gt_f32_e32 vcc, 0, v159
	v_and_b32_e32 v154, 0x7fffffff, v152
	v_exp_f32_e32 v157, v157
	v_cndmask_b32_e32 v160, v155, v161, vcc
	v_and_b32_e32 v155, 0x7fffffff, v153
	v_pk_fma_f32 v[154:155], v[154:155], s[14:15], 1.0 op_sel_hi:[1,0,0]
	v_cmp_gt_f32_e32 vcc, 0, v152
	v_rcp_f32_e32 v154, v154
	v_rcp_f32_e32 v155, v155
	s_nop 0
	v_pk_fma_f32 v[158:159], v[154:155], s[38:39], v[150:151] op_sel_hi:[1,0,0]
	s_nop 0
	v_pk_fma_f32 v[158:159], v[154:155], v[158:159], s[10:11] op_sel_hi:[1,1,0]
	s_nop 0
	v_pk_fma_f32 v[158:159], v[154:155], v[158:159], s[56:57] op_sel_hi:[1,1,0]
	s_nop 0
	v_pk_fma_f32 v[158:159], v[154:155], v[158:159], s[64:65] op_sel_hi:[1,1,0]
	s_nop 0
	v_pk_mul_f32 v[154:155], v[154:155], v[158:159]
	v_pk_mul_f32 v[158:159], v[18:19], v[134:135] op_sel_hi:[1,0]
	v_pk_mul_f32 v[154:155], v[156:157], v[154:155]
	s_nop 0
	v_pk_mul_f32 v[156:157], v[152:153], v[154:155]
	v_pk_fma_f32 v[154:155], v[152:153], v[154:155], v[152:153] neg_lo:[1,0,0] neg_hi:[1,0,0]
	v_mul_f32_e32 v152, v137, v137
	v_cndmask_b32_e32 v156, v154, v156, vcc
	v_cmp_gt_f32_e32 vcc, 0, v153
	v_mul_f32_e32 v153, v141, v141
	v_fmac_f32_e32 v152, v135, v135
	v_fmac_f32_e32 v153, v139, v139
	v_add_f32_e32 v152, v152, v153
	v_mul_f32_e32 v153, v160, v160
	v_cndmask_b32_e32 v155, v155, v157, vcc
	v_fmac_f32_e32 v153, v143, v143
	v_add_f32_e32 v152, v153, v152
	v_mul_f32_e32 v153, v155, v155
	v_fmac_f32_e32 v153, v156, v156
	v_cvt_pk_bf16_f32 v155, v156, v155
	v_pk_mul_f32 v[156:157], v[22:23], v[134:135] op_sel_hi:[1,0]
	v_cvt_pk_bf16_f32 v154, v143, v160
	v_and_b32_e32 v161, 0x7fffffff, v157
	v_and_b32_e32 v160, 0x7fffffff, v156
	v_pk_fma_f32 v[160:161], v[160:161], s[14:15], 1.0 op_sel_hi:[1,0,0]
	v_pk_mul_f32 v[164:165], v[156:157], v[156:157]
	v_rcp_f32_e32 v160, v160
	v_rcp_f32_e32 v161, v161
	v_pk_mul_f32 v[164:165], v[164:165], s[18:19] op_sel_hi:[1,0]
	v_add_f32_e32 v166, v153, v152
	v_exp_f32_e32 v164, v164
	v_pk_fma_f32 v[162:163], v[160:161], s[38:39], v[150:151] op_sel_hi:[1,0,0]
	v_exp_f32_e32 v165, v165
	v_pk_fma_f32 v[162:163], v[160:161], v[162:163], s[10:11] op_sel_hi:[1,1,0]
	v_cvt_pk_bf16_f32 v152, v135, v137
	v_pk_fma_f32 v[162:163], v[160:161], v[162:163], s[56:57] op_sel_hi:[1,1,0]
	v_cvt_pk_bf16_f32 v153, v139, v141
	v_pk_fma_f32 v[162:163], v[160:161], v[162:163], s[64:65] op_sel_hi:[1,1,0]
	s_waitcnt lgkmcnt(0)
; __device__ __forceinline__ float sigm(float v) { return __builtin_amdgcn_rcpf(1.0f + __builtin_amdgcn_exp2f(-1.44269504089f * v)); }
; __device__ __forceinline__ u32x4 pack8(const f32x4& v0, const f32x4& v1) { u32x4 w; w.x = cvt_pk_bf16(v0[0], v0[1]); w.y = cvt_pk_bf16(v0[2], v0[3]); w.z = cvt_pk_bf16(v1[0], v1[1]); w.w = cvt_pk_bf16(v1[2], v1[3]); return w; }
; __device__ __forceinline__ float sumsq8(const f32x4& v0, const f32x4& v1) { return (v0[0] * v0[0] + v0[1] * v0[1]) + (v0[2] * v0[2] + v0[3] * v0[3]) + (v1[0] * v1[0] + v1[1] * v1[1]) + (v1[2] * v1[2] + v1[3] * v1[3]); }
; __device__ __forceinline__ f32x2 gelu_pk(f32x2 v) {
;     const f32x2 av = __builtin_elementwise_abs(v), d = av * 0.2316418882f + 1.0f;
;     f32x2 t; t.x = __builtin_amdgcn_rcpf(d.x); t.y = __builtin_amdgcn_rcpf(d.y);
;     f32x2 q = t * 0.5307027145f + (-0.7265760135f); q = q * t + 0.7107068705f; q = q * t + (-0.142248368f); q = q * t + 0.127414796f; q = q * t;
;     const f32x2 s = (v * v) * (-0.72134752044f);
;     f32x2 e; e.x = __builtin_amdgcn_exp2f(s.x); e.y = __builtin_amdgcn_exp2f(s.y);
;     const f32x2 m = v * (q * e), r = v - m;
;     f32x2 o; o.x = v.x < 0.f ? m.x : r.x; o.y = v.y < 0.f ? m.y : r.y; return o;
; }
; template <int ACT> __device__ __forceinline__ void epi_act_store(f32x4 (&acc)[2][2][4][2], const float (&rs)[2][4], bf16_t* out, int ld, int row0, int col0, float* ssqv_slot, bool want_ssq, int fq) {
;     ...
;         for (int m = 0; m < 4; ++m) { const int row = row0 + ai * 128 + m * 16; float sq = 0.f;
; #pragma unroll
;             for (int bj = 0; bj < 2; ++bj) { f32x4 v0 = acc[ai][bj][m][0] * rs[ai][m], v1 = acc[ai][bj][m][1] * rs[ai][m];
;                 if (ACT == 1) { f32x2 a = gelu_pk((f32x2){v0[0], v0[1]}), b = gelu_pk((f32x2){v0[2], v0[3]}), c = gelu_pk((f32x2){v1[0], v1[1]}), d = gelu_pk((f32x2){v1[2], v1[3]});
;                     v0 = (f32x4){a.x, a.y, b.x, b.y}; v1 = (f32x4){c.x, c.y, d.x, d.y}; sq += sumsq8(v0, v1); }
;                 if (ACT == 2) {
; #pragma unroll
;                     for (int e = 0; e < 4; ++e) { v0[e] = sigm(v0[e]); v1[e] = sigm(v1[e]); } }
;                 *(u32x4*)(out + (size_t)row * ld + col0 + bj * 128) = pack8(v0, v1); }
;             if (ACT == 1) { if (want_ssq) { sq += __shfl_xor(sq, 16); sq += __shfl_xor(sq, 32); if (fq == 0) ssqv_slot[row] = sq; } } }
	global_store_dwordx4 v[178:179], v[172:175], off offset:256
	v_lshl_add_u64 v[176:177], v[148:149], 0, v[180:181]
	ds_bpermute_b32 v168, v167, v152
	ds_bpermute_b32 v169, v167, v153
	ds_bpermute_b32 v170, v167, v154
	ds_bpermute_b32 v171, v167, v155
	v_pk_mul_f32 v[160:161], v[160:161], v[162:163]
	v_cmp_gt_f32_e32 vcc, 0, v156
	v_pk_mul_f32 v[160:161], v[164:165], v[160:161]
	v_pk_mul_f32 v[154:155], v[24:25], v[134:135] op_sel_hi:[1,0]
	v_pk_mul_f32 v[164:165], v[156:157], v[160:161]
	v_pk_fma_f32 v[160:161], v[156:157], v[160:161], v[156:157] neg_lo:[1,0,0] neg_hi:[1,0,0]
	v_pk_mul_f32 v[152:153], v[20:21], v[134:135] op_sel_hi:[1,0]
	v_cndmask_b32_e32 v135, v160, v164, vcc
	v_cmp_gt_f32_e32 vcc, 0, v157
	v_and_b32_e32 v157, 0x7fffffff, v155
	v_and_b32_e32 v156, 0x7fffffff, v154
	v_pk_fma_f32 v[156:157], v[156:157], s[14:15], 1.0 op_sel_hi:[1,0,0]
	v_cndmask_b32_e32 v137, v161, v165, vcc
	v_rcp_f32_e32 v156, v156
	v_rcp_f32_e32 v157, v157
	v_pk_mul_f32 v[162:163], v[154:155], v[154:155]
	v_cmp_gt_f32_e32 vcc, 0, v154
	v_pk_fma_f32 v[160:161], v[156:157], s[38:39], v[150:151] op_sel_hi:[1,0,0]
	s_nop 0
	v_pk_fma_f32 v[160:161], v[156:157], v[160:161], s[10:11] op_sel_hi:[1,1,0]
	s_nop 0
	v_pk_fma_f32 v[160:161], v[156:157], v[160:161], s[56:57] op_sel_hi:[1,1,0]
	s_nop 0
	v_pk_fma_f32 v[160:161], v[156:157], v[160:161], s[64:65] op_sel_hi:[1,1,0]
	s_nop 0
	v_pk_mul_f32 v[156:157], v[156:157], v[160:161]
	v_pk_mul_f32 v[160:161], v[162:163], s[18:19] op_sel_hi:[1,0]
	s_nop 0
	v_exp_f32_e32 v160, v160
	v_exp_f32_e32 v161, v161
	s_nop 0
	v_pk_mul_f32 v[156:157], v[160:161], v[156:157]
	s_nop 0
	v_pk_mul_f32 v[160:161], v[154:155], v[156:157]
	v_pk_fma_f32 v[156:157], v[154:155], v[156:157], v[154:155] neg_lo:[1,0,0] neg_hi:[1,0,0]
	v_and_b32_e32 v154, 0x7fffffff, v158
	v_cndmask_b32_e32 v139, v156, v160, vcc
	v_cmp_gt_f32_e32 vcc, 0, v155
	v_and_b32_e32 v155, 0x7fffffff, v159
	v_pk_fma_f32 v[154:155], v[154:155], s[14:15], 1.0 op_sel_hi:[1,0,0]
	v_cndmask_b32_e32 v141, v157, v161, vcc
	v_rcp_f32_e32 v154, v154
	v_rcp_f32_e32 v155, v155
	v_pk_mul_f32 v[160:161], v[158:159], v[158:159]
	v_cmp_gt_f32_e32 vcc, 0, v158
	v_pk_mul_f32 v[160:161], v[160:161], s[18:19] op_sel_hi:[1,0]
	v_pk_fma_f32 v[156:157], v[154:155], s[38:39], v[150:151] op_sel_hi:[1,0,0]
	v_exp_f32_e32 v160, v160
	v_pk_fma_f32 v[156:157], v[154:155], v[156:157], s[10:11] op_sel_hi:[1,1,0]
	v_exp_f32_e32 v161, v161
	v_pk_fma_f32 v[156:157], v[154:155], v[156:157], s[56:57] op_sel_hi:[1,1,0]
	s_nop 0
	v_pk_fma_f32 v[156:157], v[154:155], v[156:157], s[64:65] op_sel_hi:[1,1,0]
	s_nop 0
	v_pk_mul_f32 v[154:155], v[154:155], v[156:157]
	v_pk_mul_f32 v[156:157], v[152:153], v[152:153]
	v_pk_mul_f32 v[154:155], v[160:161], v[154:155]
	s_nop 0
	v_pk_mul_f32 v[160:161], v[158:159], v[154:155]
	v_pk_fma_f32 v[154:155], v[158:159], v[154:155], v[158:159] neg_lo:[1,0,0] neg_hi:[1,0,0]
	s_nop 0
	v_cndmask_b32_e32 v143, v154, v160, vcc
	v_cmp_gt_f32_e32 vcc, 0, v159
	v_and_b32_e32 v154, 0x7fffffff, v152
	s_nop 0
	v_cndmask_b32_e32 v158, v155, v161, vcc
	v_and_b32_e32 v155, 0x7fffffff, v153
	v_pk_fma_f32 v[154:155], v[154:155], s[14:15], 1.0 op_sel_hi:[1,0,0]
	v_cmp_gt_f32_e32 vcc, 0, v152
	v_rcp_f32_e32 v154, v154
	v_rcp_f32_e32 v155, v155
	s_nop 0
	v_pk_fma_f32 v[150:151], v[154:155], s[38:39], v[150:151] op_sel_hi:[1,0,0]
	s_nop 0
	v_pk_fma_f32 v[150:151], v[154:155], v[150:151], s[10:11] op_sel_hi:[1,1,0]
	s_nop 0
	v_pk_fma_f32 v[150:151], v[154:155], v[150:151], s[56:57] op_sel_hi:[1,1,0]
	s_nop 0
	v_pk_fma_f32 v[150:151], v[154:155], v[150:151], s[64:65] op_sel_hi:[1,1,0]
	s_nop 0
	v_pk_mul_f32 v[150:151], v[154:155], v[150:151]
	v_pk_mul_f32 v[154:155], v[156:157], s[18:19] op_sel_hi:[1,0]
	s_nop 0
	v_exp_f32_e32 v154, v154
	v_exp_f32_e32 v155, v155
	s_nop 0
	v_pk_mul_f32 v[150:151], v[154:155], v[150:151]
	s_nop 0
	v_pk_mul_f32 v[154:155], v[152:153], v[150:151]
	v_pk_fma_f32 v[150:151], v[152:153], v[150:151], v[152:153] neg_lo:[1,0,0] neg_hi:[1,0,0]
	v_cvt_pk_bf16_f32 v152, v143, v158
	v_cndmask_b32_e32 v154, v150, v154, vcc
	v_cmp_gt_f32_e32 vcc, 0, v153
	v_mul_f32_e32 v150, v137, v137
	v_fmac_f32_e32 v150, v135, v135
	v_cndmask_b32_e32 v153, v151, v155, vcc
	v_mul_f32_e32 v151, v141, v141
	v_fmac_f32_e32 v151, v139, v139
	v_add_f32_e32 v150, v150, v151
	v_mul_f32_e32 v151, v158, v158
	v_fmac_f32_e32 v151, v143, v143
	v_add_f32_e32 v150, v151, v150
	v_mul_f32_e32 v151, v153, v153
	v_fmac_f32_e32 v151, v154, v154
	v_add_f32_e32 v150, v151, v150
	v_add_f32_e32 v155, v166, v150
	v_cvt_pk_bf16_f32 v150, v135, v137
	ds_bpermute_b32 v135, v133, v155
	v_cvt_pk_bf16_f32 v151, v139, v141
	v_cvt_pk_bf16_f32 v153, v154, v153
	s_waitcnt lgkmcnt(0)
	global_store_dwordx4 v[176:177], v[168:171], off
	v_lshl_add_u64 v[178:179], v[148:149], 0, v[180:181]
	ds_bpermute_b32 v172, v167, v150
	ds_bpermute_b32 v173, v167, v151
	ds_bpermute_b32 v174, v167, v152
	ds_bpermute_b32 v175, v167, v153
	s_waitcnt lgkmcnt(0)
	v_add_f32_e32 v135, v155, v135
	ds_bpermute_b32 v137, v131, v135
	s_and_saveexec_b64 s[8:9], s[40:41]
	s_cbranch_execz .LBB0_345
	s_waitcnt lgkmcnt(0)
	v_add_f32_e32 v135, v135, v137
	global_store_dword v[144:145], v135, off offset:640
; __device__ __forceinline__ float sigm(float v) { return __builtin_amdgcn_rcpf(1.0f + __builtin_amdgcn_exp2f(-1.44269504089f * v)); }
; __device__ __forceinline__ u32x4 pack8(const f32x4& v0, const f32x4& v1) { u32x4 w; w.x = cvt_pk_bf16(v0[0], v0[1]); w.y = cvt_pk_bf16(v0[2], v0[3]); w.z = cvt_pk_bf16(v1[0], v1[1]); w.w = cvt_pk_bf16(v1[2], v1[3]); return w; }
; __device__ __forceinline__ float sumsq8(const f32x4& v0, const f32x4& v1) { return (v0[0] * v0[0] + v0[1] * v0[1]) + (v0[2] * v0[2] + v0[3] * v0[3]) + (v1[0] * v1[0] + v1[1] * v1[1]) + (v1[2] * v1[2] + v1[3] * v1[3]); }
; __device__ __forceinline__ f32x2 gelu_pk(f32x2 v) {
;     const f32x2 av = __builtin_elementwise_abs(v), d = av * 0.2316418882f + 1.0f;
;     f32x2 t; t.x = __builtin_amdgcn_rcpf(d.x); t.y = __builtin_amdgcn_rcpf(d.y);
;     f32x2 q = t * 0.5307027145f + (-0.7265760135f); q = q * t + 0.7107068705f; q = q * t + (-0.142248368f); q = q * t + 0.127414796f; q = q * t;
;     const f32x2 s = (v * v) * (-0.72134752044f);
;     f32x2 e; e.x = __builtin_amdgcn_exp2f(s.x); e.y = __builtin_amdgcn_exp2f(s.y);
;     const f32x2 m = v * (q * e), r = v - m;
;     f32x2 o; o.x = v.x < 0.f ? m.x : r.x; o.y = v.y < 0.f ? m.y : r.y; return o;
; }
; template <int ACT> __device__ __forceinline__ void epi_act_store(f32x4 (&acc)[2][2][4][2], const float (&rs)[2][4], bf16_t* out, int ld, int row0, int col0, float* ssqv_slot, bool want_ssq, int fq) {
;     ...
;         for (int m = 0; m < 4; ++m) { const int row = row0 + ai * 128 + m * 16; float sq = 0.f;
; #pragma unroll
;             for (int bj = 0; bj < 2; ++bj) { f32x4 v0 = acc[ai][bj][m][0] * rs[ai][m], v1 = acc[ai][bj][m][1] * rs[ai][m];
;                 if (ACT == 1) { f32x2 a = gelu_pk((f32x2){v0[0], v0[1]}), b = gelu_pk((f32x2){v0[2], v0[3]}), c = gelu_pk((f32x2){v1[0], v1[1]}), d = gelu_pk((f32x2){v1[2], v1[3]});
;                     v0 = (f32x4){a.x, a.y, b.x, b.y}; v1 = (f32x4){c.x, c.y, d.x, d.y}; sq += sumsq8(v0, v1); }
;                 if (ACT == 2) {
; #pragma unroll
;                     for (int e = 0; e < 4; ++e) { v0[e] = sigm(v0[e]); v1[e] = sigm(v1[e]); } }
;                 *(u32x4*)(out + (size_t)row * ld + col0 + bj * 128) = pack8(v0, v1); }
;             if (ACT == 1) { if (want_ssq) { sq += __shfl_xor(sq, 16); sq += __shfl_xor(sq, 32); if (fq == 0) ssqv_slot[row] = sq; } } }
.LBB0_345:
	s_or_b64 exec, exec, s[8:9]
	s_waitcnt lgkmcnt(0)
	v_pk_mul_f32 v[154:155], v[14:15], v[136:137] op_sel_hi:[1,0]
	v_add_u32_e32 v135, 0xb0, v210
	v_and_b32_e32 v149, 0x7fffffff, v155
	v_and_b32_e32 v148, 0x7fffffff, v154
	v_pk_fma_f32 v[148:149], v[148:149], s[14:15], 1.0 op_sel_hi:[1,0,0]
	v_pk_mul_f32 v[162:163], v[154:155], v[154:155]
	v_rcp_f32_e32 v158, v148
	v_rcp_f32_e32 v159, v149
	v_mov_b64_e32 v[148:149], s[2:3]
	v_pk_mul_f32 v[162:163], v[162:163], s[18:19] op_sel_hi:[1,0]
	v_pk_mul_f32 v[152:153], v[16:17], v[136:137] op_sel_hi:[1,0]
	v_pk_fma_f32 v[160:161], v[158:159], s[38:39], v[148:149] op_sel_hi:[1,0,0]
	v_exp_f32_e32 v162, v162
	v_pk_fma_f32 v[160:161], v[158:159], v[160:161], s[10:11] op_sel_hi:[1,1,0]
	v_exp_f32_e32 v163, v163
	v_pk_fma_f32 v[160:161], v[158:159], v[160:161], s[56:57] op_sel_hi:[1,1,0]
	v_cmp_gt_f32_e32 vcc, 0, v154
	v_pk_fma_f32 v[160:161], v[158:159], v[160:161], s[64:65] op_sel_hi:[1,1,0]
	v_mad_i64_i32 v[146:147], s[8:9], v135, s69, v[146:147]
	v_pk_mul_f32 v[158:159], v[158:159], v[160:161]
	v_pk_mul_f32 v[150:151], v[12:13], v[136:137] op_sel_hi:[1,0]
	v_pk_mul_f32 v[158:159], v[162:163], v[158:159]
	v_pk_mul_f32 v[156:157], v[10:11], v[136:137] op_sel_hi:[1,0]
	v_pk_mul_f32 v[162:163], v[154:155], v[158:159]
	v_pk_fma_f32 v[158:159], v[154:155], v[158:159], v[154:155] neg_lo:[1,0,0] neg_hi:[1,0,0]
	v_and_b32_e32 v154, 0x7fffffff, v152
	v_cndmask_b32_e32 v135, v158, v162, vcc
	v_cmp_gt_f32_e32 vcc, 0, v155
	v_and_b32_e32 v155, 0x7fffffff, v153
	v_pk_fma_f32 v[154:155], v[154:155], s[14:15], 1.0 op_sel_hi:[1,0,0]
	v_cndmask_b32_e32 v137, v159, v163, vcc
	v_rcp_f32_e32 v154, v154
	v_rcp_f32_e32 v155, v155
	v_pk_mul_f32 v[160:161], v[152:153], v[152:153]
	v_cmp_gt_f32_e32 vcc, 0, v152
	v_pk_fma_f32 v[158:159], v[154:155], s[38:39], v[148:149] op_sel_hi:[1,0,0]
	s_nop 0
	v_pk_fma_f32 v[158:159], v[154:155], v[158:159], s[10:11] op_sel_hi:[1,1,0]
	s_nop 0
	v_pk_fma_f32 v[158:159], v[154:155], v[158:159], s[56:57] op_sel_hi:[1,1,0]
	s_nop 0
	v_pk_fma_f32 v[158:159], v[154:155], v[158:159], s[64:65] op_sel_hi:[1,1,0]
	s_nop 0
	v_pk_mul_f32 v[154:155], v[154:155], v[158:159]
	v_pk_mul_f32 v[158:159], v[160:161], s[18:19] op_sel_hi:[1,0]
	s_nop 0
	v_exp_f32_e32 v158, v158
	v_exp_f32_e32 v159, v159
	s_nop 0
	v_pk_mul_f32 v[154:155], v[158:159], v[154:155]
	s_nop 0
	v_pk_mul_f32 v[158:159], v[152:153], v[154:155]
	v_pk_fma_f32 v[154:155], v[152:153], v[154:155], v[152:153] neg_lo:[1,0,0] neg_hi:[1,0,0]
	v_and_b32_e32 v152, 0x7fffffff, v156
	v_cndmask_b32_e32 v139, v154, v158, vcc
	v_cmp_gt_f32_e32 vcc, 0, v153
	v_and_b32_e32 v153, 0x7fffffff, v157
	v_pk_fma_f32 v[152:153], v[152:153], s[14:15], 1.0 op_sel_hi:[1,0,0]
	v_cndmask_b32_e32 v141, v155, v159, vcc
	v_rcp_f32_e32 v152, v152
	v_rcp_f32_e32 v153, v153
	v_pk_mul_f32 v[158:159], v[156:157], v[156:157]
	v_cmp_gt_f32_e32 vcc, 0, v156
	v_pk_mul_f32 v[158:159], v[158:159], s[18:19] op_sel_hi:[1,0]
	v_pk_fma_f32 v[154:155], v[152:153], s[38:39], v[148:149] op_sel_hi:[1,0,0]
	v_exp_f32_e32 v158, v158
	v_pk_fma_f32 v[154:155], v[152:153], v[154:155], s[10:11] op_sel_hi:[1,1,0]
	v_exp_f32_e32 v159, v159
	v_pk_fma_f32 v[154:155], v[152:153], v[154:155], s[56:57] op_sel_hi:[1,1,0]
	s_nop 0
	v_pk_fma_f32 v[154:155], v[152:153], v[154:155], s[64:65] op_sel_hi:[1,1,0]
	s_nop 0
	v_pk_mul_f32 v[152:153], v[152:153], v[154:155]
	v_pk_mul_f32 v[154:155], v[150:151], v[150:151]
	v_pk_mul_f32 v[152:153], v[158:159], v[152:153]
	v_pk_mul_f32 v[154:155], v[154:155], s[18:19] op_sel_hi:[1,0]
	v_pk_mul_f32 v[158:159], v[156:157], v[152:153]
	v_pk_fma_f32 v[152:153], v[156:157], v[152:153], v[156:157] neg_lo:[1,0,0] neg_hi:[1,0,0]
	v_exp_f32_e32 v154, v154
	v_cndmask_b32_e32 v143, v152, v158, vcc
	v_cmp_gt_f32_e32 vcc, 0, v157
	v_and_b32_e32 v152, 0x7fffffff, v150
	v_exp_f32_e32 v155, v155
	v_cndmask_b32_e32 v158, v153, v159, vcc
	v_and_b32_e32 v153, 0x7fffffff, v151
	v_pk_fma_f32 v[152:153], v[152:153], s[14:15], 1.0 op_sel_hi:[1,0,0]
	v_cmp_gt_f32_e32 vcc, 0, v150
	v_rcp_f32_e32 v152, v152
	v_rcp_f32_e32 v153, v153
	s_nop 0
	v_pk_fma_f32 v[156:157], v[152:153], s[38:39], v[148:149] op_sel_hi:[1,0,0]
	s_nop 0
	v_pk_fma_f32 v[156:157], v[152:153], v[156:157], s[10:11] op_sel_hi:[1,1,0]
	s_nop 0
	v_pk_fma_f32 v[156:157], v[152:153], v[156:157], s[56:57] op_sel_hi:[1,1,0]
	s_nop 0
	v_pk_fma_f32 v[156:157], v[152:153], v[156:157], s[64:65] op_sel_hi:[1,1,0]
	s_nop 0
	v_pk_mul_f32 v[152:153], v[152:153], v[156:157]
	v_pk_mul_f32 v[156:157], v[2:3], v[136:137] op_sel_hi:[1,0]
	v_pk_mul_f32 v[152:153], v[154:155], v[152:153]
	s_nop 0
	v_pk_mul_f32 v[154:155], v[150:151], v[152:153]
	v_pk_fma_f32 v[152:153], v[150:151], v[152:153], v[150:151] neg_lo:[1,0,0] neg_hi:[1,0,0]
	v_mul_f32_e32 v150, v137, v137
	v_cndmask_b32_e32 v154, v152, v154, vcc
	v_cmp_gt_f32_e32 vcc, 0, v151
	v_mul_f32_e32 v151, v141, v141
	v_fmac_f32_e32 v150, v135, v135
	v_fmac_f32_e32 v151, v139, v139
	v_add_f32_e32 v150, v150, v151
	v_mul_f32_e32 v151, v158, v158
	v_cndmask_b32_e32 v153, v153, v155, vcc
	v_fmac_f32_e32 v151, v143, v143
	v_add_f32_e32 v150, v151, v150
	v_mul_f32_e32 v151, v153, v153
	v_fmac_f32_e32 v151, v154, v154
	v_cvt_pk_bf16_f32 v153, v154, v153
	v_pk_mul_f32 v[154:155], v[6:7], v[136:137] op_sel_hi:[1,0]
	v_cvt_pk_bf16_f32 v152, v143, v158
	v_and_b32_e32 v159, 0x7fffffff, v155
	v_and_b32_e32 v158, 0x7fffffff, v154
	v_pk_fma_f32 v[158:159], v[158:159], s[14:15], 1.0 op_sel_hi:[1,0,0]
	v_pk_mul_f32 v[162:163], v[154:155], v[154:155]
	v_rcp_f32_e32 v158, v158
	v_rcp_f32_e32 v159, v159
	v_pk_mul_f32 v[162:163], v[162:163], s[18:19] op_sel_hi:[1,0]
	v_add_f32_e32 v164, v151, v150
	v_exp_f32_e32 v162, v162
	v_pk_fma_f32 v[160:161], v[158:159], s[38:39], v[148:149] op_sel_hi:[1,0,0]
	v_exp_f32_e32 v163, v163
	v_pk_fma_f32 v[160:161], v[158:159], v[160:161], s[10:11] op_sel_hi:[1,1,0]
	v_cvt_pk_bf16_f32 v150, v135, v137
	v_pk_fma_f32 v[160:161], v[158:159], v[160:161], s[56:57] op_sel_hi:[1,1,0]
	v_cvt_pk_bf16_f32 v151, v139, v141
	v_pk_fma_f32 v[160:161], v[158:159], v[160:161], s[64:65] op_sel_hi:[1,1,0]
	s_waitcnt lgkmcnt(0)
; __device__ __forceinline__ float sigm(float v) { return __builtin_amdgcn_rcpf(1.0f + __builtin_amdgcn_exp2f(-1.44269504089f * v)); }
; __device__ __forceinline__ u32x4 pack8(const f32x4& v0, const f32x4& v1) { u32x4 w; w.x = cvt_pk_bf16(v0[0], v0[1]); w.y = cvt_pk_bf16(v0[2], v0[3]); w.z = cvt_pk_bf16(v1[0], v1[1]); w.w = cvt_pk_bf16(v1[2], v1[3]); return w; }
; __device__ __forceinline__ float sumsq8(const f32x4& v0, const f32x4& v1) { return (v0[0] * v0[0] + v0[1] * v0[1]) + (v0[2] * v0[2] + v0[3] * v0[3]) + (v1[0] * v1[0] + v1[1] * v1[1]) + (v1[2] * v1[2] + v1[3] * v1[3]); }
; __device__ __forceinline__ f32x2 gelu_pk(f32x2 v) {
;     const f32x2 av = __builtin_elementwise_abs(v), d = av * 0.2316418882f + 1.0f;
;     f32x2 t; t.x = __builtin_amdgcn_rcpf(d.x); t.y = __builtin_amdgcn_rcpf(d.y);
;     f32x2 q = t * 0.5307027145f + (-0.7265760135f); q = q * t + 0.7107068705f; q = q * t + (-0.142248368f); q = q * t + 0.127414796f; q = q * t;
;     const f32x2 s = (v * v) * (-0.72134752044f);
;     f32x2 e; e.x = __builtin_amdgcn_exp2f(s.x); e.y = __builtin_amdgcn_exp2f(s.y);
;     const f32x2 m = v * (q * e), r = v - m;
;     f32x2 o; o.x = v.x < 0.f ? m.x : r.x; o.y = v.y < 0.f ? m.y : r.y; return o;
; }
; template <int ACT> __device__ __forceinline__ void epi_act_store(f32x4 (&acc)[2][2][4][2], const float (&rs)[2][4], bf16_t* out, int ld, int row0, int col0, float* ssqv_slot, bool want_ssq, int fq) {
;     ...
;         for (int m = 0; m < 4; ++m) { const int row = row0 + ai * 128 + m * 16; float sq = 0.f;
; #pragma unroll
;             for (int bj = 0; bj < 2; ++bj) { f32x4 v0 = acc[ai][bj][m][0] * rs[ai][m], v1 = acc[ai][bj][m][1] * rs[ai][m];
;                 if (ACT == 1) { f32x2 a = gelu_pk((f32x2){v0[0], v0[1]}), b = gelu_pk((f32x2){v0[2], v0[3]}), c = gelu_pk((f32x2){v1[0], v1[1]}), d = gelu_pk((f32x2){v1[2], v1[3]});
;                     v0 = (f32x4){a.x, a.y, b.x, b.y}; v1 = (f32x4){c.x, c.y, d.x, d.y}; sq += sumsq8(v0, v1); }
;                 if (ACT == 2) {
; #pragma unroll
;                     for (int e = 0; e < 4; ++e) { v0[e] = sigm(v0[e]); v1[e] = sigm(v1[e]); } }
;                 *(u32x4*)(out + (size_t)row * ld + col0 + bj * 128) = pack8(v0, v1); }
;             if (ACT == 1) { if (want_ssq) { sq += __shfl_xor(sq, 16); sq += __shfl_xor(sq, 32); if (fq == 0) ssqv_slot[row] = sq; } } }
	global_store_dwordx4 v[178:179], v[172:175], off offset:256
	v_lshl_add_u64 v[176:177], v[146:147], 0, v[180:181]
	ds_bpermute_b32 v168, v167, v150
	ds_bpermute_b32 v169, v167, v151
	ds_bpermute_b32 v170, v167, v152
	ds_bpermute_b32 v171, v167, v153
	v_pk_mul_f32 v[158:159], v[158:159], v[160:161]
	v_cmp_gt_f32_e32 vcc, 0, v154
	v_pk_mul_f32 v[158:159], v[162:163], v[158:159]
	v_pk_mul_f32 v[152:153], v[8:9], v[136:137] op_sel_hi:[1,0]
	v_pk_mul_f32 v[162:163], v[154:155], v[158:159]
	v_pk_fma_f32 v[158:159], v[154:155], v[158:159], v[154:155] neg_lo:[1,0,0] neg_hi:[1,0,0]
	v_and_b32_e32 v154, 0x7fffffff, v152
	v_cndmask_b32_e32 v135, v158, v162, vcc
	v_cmp_gt_f32_e32 vcc, 0, v155
	v_and_b32_e32 v155, 0x7fffffff, v153
	v_pk_fma_f32 v[154:155], v[154:155], s[14:15], 1.0 op_sel_hi:[1,0,0]
	v_pk_mul_f32 v[150:151], v[4:5], v[136:137] op_sel_hi:[1,0]
	v_rcp_f32_e32 v154, v154
	v_rcp_f32_e32 v155, v155
	v_cndmask_b32_e32 v137, v159, v163, vcc
	v_pk_mul_f32 v[160:161], v[152:153], v[152:153]
	v_cmp_gt_f32_e32 vcc, 0, v152
	v_pk_fma_f32 v[158:159], v[154:155], s[38:39], v[148:149] op_sel_hi:[1,0,0]
	s_nop 0
	v_pk_fma_f32 v[158:159], v[154:155], v[158:159], s[10:11] op_sel_hi:[1,1,0]
	s_nop 0
	v_pk_fma_f32 v[158:159], v[154:155], v[158:159], s[56:57] op_sel_hi:[1,1,0]
	s_nop 0
	v_pk_fma_f32 v[158:159], v[154:155], v[158:159], s[64:65] op_sel_hi:[1,1,0]
	s_nop 0
	v_pk_mul_f32 v[154:155], v[154:155], v[158:159]
	v_pk_mul_f32 v[158:159], v[160:161], s[18:19] op_sel_hi:[1,0]
	s_nop 0
	v_exp_f32_e32 v158, v158
	v_exp_f32_e32 v159, v159
	s_nop 0
	v_pk_mul_f32 v[154:155], v[158:159], v[154:155]
	s_nop 0
	v_pk_mul_f32 v[158:159], v[152:153], v[154:155]
	v_pk_fma_f32 v[154:155], v[152:153], v[154:155], v[152:153] neg_lo:[1,0,0] neg_hi:[1,0,0]
	v_and_b32_e32 v152, 0x7fffffff, v156
	v_cndmask_b32_e32 v139, v154, v158, vcc
	v_cmp_gt_f32_e32 vcc, 0, v153
	v_and_b32_e32 v153, 0x7fffffff, v157
	v_pk_fma_f32 v[152:153], v[152:153], s[14:15], 1.0 op_sel_hi:[1,0,0]
	v_cndmask_b32_e32 v141, v155, v159, vcc
	v_rcp_f32_e32 v152, v152
	v_rcp_f32_e32 v153, v153
	v_pk_mul_f32 v[158:159], v[156:157], v[156:157]
	v_cmp_gt_f32_e32 vcc, 0, v156
	v_pk_mul_f32 v[158:159], v[158:159], s[18:19] op_sel_hi:[1,0]
	v_pk_fma_f32 v[154:155], v[152:153], s[38:39], v[148:149] op_sel_hi:[1,0,0]
	v_exp_f32_e32 v158, v158
	v_pk_fma_f32 v[154:155], v[152:153], v[154:155], s[10:11] op_sel_hi:[1,1,0]
	v_exp_f32_e32 v159, v159
	v_pk_fma_f32 v[154:155], v[152:153], v[154:155], s[56:57] op_sel_hi:[1,1,0]
	s_nop 0
	v_pk_fma_f32 v[154:155], v[152:153], v[154:155], s[64:65] op_sel_hi:[1,1,0]
	s_nop 0
	v_pk_mul_f32 v[152:153], v[152:153], v[154:155]
	v_pk_mul_f32 v[154:155], v[150:151], v[150:151]
	v_pk_mul_f32 v[152:153], v[158:159], v[152:153]
	s_nop 0
	v_pk_mul_f32 v[158:159], v[156:157], v[152:153]
	v_pk_fma_f32 v[152:153], v[156:157], v[152:153], v[156:157] neg_lo:[1,0,0] neg_hi:[1,0,0]
	s_nop 0
	v_cndmask_b32_e32 v143, v152, v158, vcc
	v_cmp_gt_f32_e32 vcc, 0, v157
	v_and_b32_e32 v152, 0x7fffffff, v150
	s_nop 0
	v_cndmask_b32_e32 v156, v153, v159, vcc
	v_and_b32_e32 v153, 0x7fffffff, v151
	v_pk_fma_f32 v[152:153], v[152:153], s[14:15], 1.0 op_sel_hi:[1,0,0]
	v_cmp_gt_f32_e32 vcc, 0, v150
	v_rcp_f32_e32 v152, v152
	v_rcp_f32_e32 v153, v153
	s_nop 0
	v_pk_fma_f32 v[148:149], v[152:153], s[38:39], v[148:149] op_sel_hi:[1,0,0]
	s_nop 0
	v_pk_fma_f32 v[148:149], v[152:153], v[148:149], s[10:11] op_sel_hi:[1,1,0]
	s_nop 0
	v_pk_fma_f32 v[148:149], v[152:153], v[148:149], s[56:57] op_sel_hi:[1,1,0]
	s_nop 0
	v_pk_fma_f32 v[148:149], v[152:153], v[148:149], s[64:65] op_sel_hi:[1,1,0]
	s_nop 0
	v_pk_mul_f32 v[148:149], v[152:153], v[148:149]
	v_pk_mul_f32 v[152:153], v[154:155], s[18:19] op_sel_hi:[1,0]
	s_nop 0
	v_exp_f32_e32 v152, v152
	v_exp_f32_e32 v153, v153
	s_nop 0
	v_pk_mul_f32 v[148:149], v[152:153], v[148:149]
	s_nop 0
	v_pk_mul_f32 v[152:153], v[150:151], v[148:149]
	v_pk_fma_f32 v[148:149], v[150:151], v[148:149], v[150:151] neg_lo:[1,0,0] neg_hi:[1,0,0]
	v_cvt_pk_bf16_f32 v150, v143, v156
	v_cndmask_b32_e32 v152, v148, v152, vcc
	v_cmp_gt_f32_e32 vcc, 0, v151
	v_mul_f32_e32 v148, v137, v137
	v_fmac_f32_e32 v148, v135, v135
	v_cndmask_b32_e32 v151, v149, v153, vcc
	v_mul_f32_e32 v149, v141, v141
	v_fmac_f32_e32 v149, v139, v139
	v_add_f32_e32 v148, v148, v149
	v_mul_f32_e32 v149, v156, v156
	v_fmac_f32_e32 v149, v143, v143
	v_add_f32_e32 v148, v149, v148
	v_mul_f32_e32 v149, v151, v151
	v_fmac_f32_e32 v149, v152, v152
	v_add_f32_e32 v148, v149, v148
	v_add_f32_e32 v153, v164, v148
	ds_bpermute_b32 v133, v133, v153
	v_cvt_pk_bf16_f32 v148, v135, v137
	v_cvt_pk_bf16_f32 v149, v139, v141
	v_cvt_pk_bf16_f32 v151, v152, v151
	s_waitcnt lgkmcnt(0)
	global_store_dwordx4 v[176:177], v[168:171], off
	v_lshl_add_u64 v[178:179], v[146:147], 0, v[180:181]
	ds_bpermute_b32 v172, v167, v148
	ds_bpermute_b32 v173, v167, v149
	ds_bpermute_b32 v174, v167, v150
	ds_bpermute_b32 v175, v167, v151
	s_waitcnt lgkmcnt(0)
	global_store_dwordx4 v[178:179], v[172:175], off offset:256
	s_waitcnt lgkmcnt(0)
	v_add_f32_e32 v133, v153, v133
	ds_bpermute_b32 v131, v131, v133
	s_and_saveexec_b64 s[8:9], s[40:41]
	s_cbranch_execz .LBB0_347
	s_waitcnt lgkmcnt(0)
	v_add_f32_e32 v131, v133, v131
	global_store_dword v[144:145], v131, off offset:704
